# v067 + trailing half's per-unit offset barrier sunk below the peeled first load segment's preamble and LDS-DMA issue (its first staging loads fly while it waits for the leading half); peeled copies of
# baseline (speedup 1.0000x reference)
; #define PG8_STAGE(bufoff, gbase, voff) do { _Pragma("unroll") for (int _i = 0; _i < 2; ++_i) \
;         __builtin_amdgcn_global_load_lds((const unsigned*)((const char*)(gbase) + (voff)[_i]), (PG8_LAS unsigned*)(lds + (bufoff) + ldsw + _i * 8192), 16, 0, AUX_A); } while (0)
; #define PG8_STAGEB(bufoff, gbase, voff) do { _Pragma("unroll") for (int _i = 0; _i < 2; ++_i) \
;         __builtin_amdgcn_global_load_lds((const unsigned*)((const char*)(gbase) + (voff)[_i]), (PG8_LAS unsigned*)(lds + (bufoff) + ldsw + _i * 8192), 16, 0, AUX_B); } while (0)
; #define PG8_WAIT_V(n) asm volatile("s_waitcnt vmcnt(" #n ")" ::: "memory")
; template <class Epi, class Sched, bool ALIGN_EPI = false, bool SP2 = false>
; __device__ __forceinline__ void gemm_phase(PG8_LAS unsigned char* lds, const Gemm g, const Sched& S, const Epi& E) {
;     ...
;         for (int t = 0; t < nt; t += 2) {
;             const bool last = (t == nt - 2);
;             const char* a1 = PG8_KP(cA, t + 1, rot, nt);
;             const char* a2 = last ? nAr : PG8_KP(cA, t + 2, rot, nt); const char* b2 = last ? nBr : PG8_KP(cB, t + 2, rot, nt);
;             const char* a3 = a2 + kstep; const char* b3 = b2 + kstep;
;             if (last && has_next) S.a_ready(nxt);
;             if constexpr (SP2) {
;             PG8_LDB(B0, 0, 0); PG8_LDB(B1, 0, 1); PG8_SCHED; PG8_LDA(At, 0, 0); PG8_STAGE(PG8_SA(1, 1), a1 + hstep, voffA);
;             PG8_WAIT_V(8); PG8_WAIT_L(0); PG8_BAR; PG8_MMA(0, 0, At, B0); PG8_MMA(0, 1, At, B1); PG8_BAR; PG8_SCHED;
;             PG8_LDA(At, 0, 1); PG8_STAGEB(PG8_SB(0, 0), b2, voffB); PG8_STAGEB(PG8_SB(0, 1), b2 + hstep, voffB); PG8_STAGE(PG8_SA(0, 0), a2, voffA);
;             PG8_WAIT_V(8); PG8_WAIT_L(0); PG8_BAR; PG8_MMA(1, 0, At, B0); PG8_MMA(1, 1, At, B1); PG8_BAR; PG8_SCHED;
;             PG8_LDB(B0, 1, 0); PG8_LDB(B1, 1, 1); PG8_SCHED; PG8_LDA(At, 1, 0); PG8_STAGE(PG8_SA(0, 1), a2 + hstep, voffA);
;             PG8_WAIT_V(8); PG8_WAIT_L(0); PG8_BAR; PG8_MMA(0, 0, At, B0); PG8_MMA(0, 1, At, B1); PG8_BAR; PG8_SCHED;
;             PG8_LDA(At, 1, 1); PG8_STAGEB(PG8_SB(1, 0), b3, voffB); PG8_STAGEB(PG8_SB(1, 1), b3 + hstep, voffB); PG8_STAGE(PG8_SA(1, 0), a3, voffA);
;             PG8_WAIT_V(8); PG8_WAIT_L(0); PG8_BAR; PG8_MMA(1, 0, At, B0); PG8_MMA(1, 1, At, B1); PG8_BAR; PG8_SCHED;
;     ...
;         if constexpr (ALIGN_EPI) { if (wr == 1) PG8_BAR; }
.Lpk_270:
	s_add_i32 s81, s29, 2
	s_cmp_lt_u32 s29, 30
	s_cselect_b32 s0, 0, 0xffffffe0
	s_add_i32 s0, s81, s0
	s_ashr_i32 s1, s0, 31
	s_lshl_b64 s[0:1], s[0:1], 7
	s_add_u32 s42, s40, s0
	s_addc_u32 s43, s41, s1
	s_add_u32 s0, s38, s0
	s_addc_u32 s1, s39, s1
	s_cmp_eq_u32 s29, 30
	s_cselect_b32 s59, s49, s43
	s_cselect_b32 s58, s51, s42
	s_cselect_b32 s61, vcc_lo, s1
	s_cselect_b32 s60, vcc_hi, s0
	s_add_i32 s43, 0, 0x10000
	s_add_i32 s97, s43, s70
	s_add_i32 s46, 0, 0x14000
	s_add_i32 m0, s96, 0xc000
	s_add_i32 s69, s96, 0xe000
	s_add_i32 s84, s97, 0x2000
	s_add_u32 s62, s60, 0x80000
	s_addc_u32 s63, s61, 0
	s_add_i32 s4, s46, s70
	s_add_i32 s5, s4, 0x2000
	s_add_i32 s1, 0, 0x18000
	s_add_i32 s47, 0, 0x1c000
	s_add_u32 s56, s58, 0x80000
	s_addc_u32 s57, s59, 0
	s_add_i32 s0, s1, s70
	s_add_i32 s89, s0, 0x2000
	s_add_u32 s42, s60, 0x80080
	s_addc_u32 s43, s61, 0
	s_add_i32 s46, s47, s70
	s_add_i32 s92, s46, 0x2000
	global_load_lds_dwordx4 v[134:135], off
	s_mov_b32 m0, s69
	s_nop 0
	global_load_lds_dwordx4 v[132:133], off
	s_cmp_lg_u64 s[10:11], 0
	s_cbranch_scc1 .Lrp_270
	s_barrier
.Lrp_270:
	s_waitcnt vmcnt(8)
	s_waitcnt lgkmcnt(0)
	s_setprio 1
	s_barrier
	v_mfma_f32_16x16x32_bf16 v[128:131], v[136:139], v[192:195], 0
	v_mfma_f32_16x16x32_bf16 v[128:131], v[140:143], v[196:199], v[128:131]
	v_mfma_f32_16x16x32_bf16 v[124:127], v[144:147], v[192:195], 0
	v_mfma_f32_16x16x32_bf16 v[124:127], v[148:151], v[196:199], v[124:127]
	v_mfma_f32_16x16x32_bf16 v[112:115], v[136:139], v[200:203], 0
	v_mfma_f32_16x16x32_bf16 v[112:115], v[140:143], v[224:227], v[112:115]
	v_mfma_f32_16x16x32_bf16 v[108:111], v[144:147], v[200:203], 0
	v_mfma_f32_16x16x32_bf16 v[108:111], v[148:151], v[224:227], v[108:111]
	v_mfma_f32_16x16x32_bf16 v[94:97], v[136:139], v[228:231], 0
	v_mfma_f32_16x16x32_bf16 v[94:97], v[140:143], v[232:235], v[94:97]
	v_mfma_f32_16x16x32_bf16 v[90:93], v[144:147], v[228:231], 0
	v_mfma_f32_16x16x32_bf16 v[90:93], v[148:151], v[232:235], v[90:93]
	v_mfma_f32_16x16x32_bf16 v[78:81], v[136:139], v[236:239], 0
	v_mfma_f32_16x16x32_bf16 v[78:81], v[140:143], v[240:243], v[78:81]
	v_mfma_f32_16x16x32_bf16 v[74:77], v[144:147], v[236:239], 0
	v_mfma_f32_16x16x32_bf16 v[74:77], v[148:151], v[240:243], v[74:77]
	s_setprio 0
	s_setprio 1
	v_mfma_f32_16x16x32_bf16 v[120:123], v[152:155], v[192:195], 0
	v_mfma_f32_16x16x32_bf16 v[120:123], v[156:159], v[196:199], v[120:123]
	v_mfma_f32_16x16x32_bf16 v[116:119], v[160:163], v[192:195], 0
	v_mfma_f32_16x16x32_bf16 v[116:119], v[164:167], v[196:199], v[116:119]
	v_mfma_f32_16x16x32_bf16 v[104:107], v[152:155], v[200:203], 0
	v_mfma_f32_16x16x32_bf16 v[104:107], v[156:159], v[224:227], v[104:107]
	v_mfma_f32_16x16x32_bf16 v[100:103], v[160:163], v[200:203], 0
	v_mfma_f32_16x16x32_bf16 v[100:103], v[164:167], v[224:227], v[100:103]
	v_mfma_f32_16x16x32_bf16 v[86:89], v[152:155], v[228:231], 0
	v_mfma_f32_16x16x32_bf16 v[86:89], v[156:159], v[232:235], v[86:89]
	v_mfma_f32_16x16x32_bf16 v[82:85], v[160:163], v[228:231], 0
	v_mfma_f32_16x16x32_bf16 v[82:85], v[164:167], v[232:235], v[82:85]
	v_mfma_f32_16x16x32_bf16 v[70:73], v[152:155], v[236:239], 0
	v_mfma_f32_16x16x32_bf16 v[70:73], v[156:159], v[240:243], v[70:73]
	s_setprio 2
	s_barrier
	v_mfma_f32_16x16x32_bf16 v[66:69], v[160:163], v[236:239], 0
	v_mfma_f32_16x16x32_bf16 v[66:69], v[164:167], v[240:243], v[66:69]
	s_setprio 0
	s_mov_b32 m0, s97
	v_lshl_add_u64 v[244:245], s[60:61], 0, v[184:185]
	ds_read_b128 v[192:195], v222 offset:16384
	ds_read_b128 v[196:199], v222 offset:17408
	ds_read_b128 v[200:203], v222 offset:18432
	ds_read_b128 v[224:227], v222 offset:19456
	ds_read_b128 v[228:231], v222 offset:20480
	ds_read_b128 v[232:235], v222 offset:21504
	ds_read_b128 v[236:239], v222 offset:22528
	ds_read_b128 v[240:243], v222 offset:23552
	global_load_lds_dwordx4 v[244:245], off
	v_lshl_add_u64 v[246:247], s[60:61], 0, v[180:181]
	s_mov_b32 m0, s84
	v_lshl_add_u64 v[212:213], s[62:63], 0, v[184:185]
	global_load_lds_dwordx4 v[246:247], off
	s_mov_b32 m0, s4
	v_lshl_add_u64 v[172:173], s[58:59], 0, v[182:183]
	global_load_lds_dwordx4 v[212:213], off
	v_lshl_add_u64 v[212:213], s[62:63], 0, v[180:181]
	s_mov_b32 m0, s5
	s_nop 0
	global_load_lds_dwordx4 v[212:213], off
	v_lshl_add_u64 v[212:213], s[58:59], 0, v[186:187]
	s_mov_b32 m0, s96
	s_nop 0
	global_load_lds_dwordx4 v[212:213], off
	s_mov_b32 m0, s71
	s_nop 0
	global_load_lds_dwordx4 v[172:173], off
	s_waitcnt vmcnt(8)
	s_waitcnt lgkmcnt(0)
	s_setprio 1
	s_barrier
	v_mfma_f32_16x16x32_bf16 v[62:65], v[136:139], v[192:195], 0
	v_mfma_f32_16x16x32_bf16 v[62:65], v[140:143], v[196:199], v[62:65]
	v_mfma_f32_16x16x32_bf16 v[58:61], v[144:147], v[192:195], 0
	v_mfma_f32_16x16x32_bf16 v[58:61], v[148:151], v[196:199], v[58:61]
	v_mfma_f32_16x16x32_bf16 v[46:49], v[136:139], v[200:203], 0
	v_mfma_f32_16x16x32_bf16 v[46:49], v[140:143], v[224:227], v[46:49]
	v_mfma_f32_16x16x32_bf16 v[42:45], v[144:147], v[200:203], 0
	v_mfma_f32_16x16x32_bf16 v[42:45], v[148:151], v[224:227], v[42:45]
	v_mfma_f32_16x16x32_bf16 v[30:33], v[136:139], v[228:231], 0
	v_mfma_f32_16x16x32_bf16 v[30:33], v[140:143], v[232:235], v[30:33]
	v_mfma_f32_16x16x32_bf16 v[26:29], v[144:147], v[228:231], 0
	v_mfma_f32_16x16x32_bf16 v[26:29], v[148:151], v[232:235], v[26:29]
	v_mfma_f32_16x16x32_bf16 v[14:17], v[136:139], v[236:239], 0
	v_mfma_f32_16x16x32_bf16 v[14:17], v[140:143], v[240:243], v[14:17]
	v_mfma_f32_16x16x32_bf16 v[10:13], v[144:147], v[236:239], 0
	v_mfma_f32_16x16x32_bf16 v[10:13], v[148:151], v[240:243], v[10:13]
	s_setprio 0
	s_setprio 1
	v_mfma_f32_16x16x32_bf16 v[54:57], v[152:155], v[192:195], 0
	v_mfma_f32_16x16x32_bf16 v[54:57], v[156:159], v[196:199], v[54:57]
	v_mfma_f32_16x16x32_bf16 v[50:53], v[160:163], v[192:195], 0
	v_mfma_f32_16x16x32_bf16 v[50:53], v[164:167], v[196:199], v[50:53]
	v_mfma_f32_16x16x32_bf16 v[38:41], v[152:155], v[200:203], 0
	v_mfma_f32_16x16x32_bf16 v[38:41], v[156:159], v[224:227], v[38:41]
	v_mfma_f32_16x16x32_bf16 v[34:37], v[160:163], v[200:203], 0
	v_mfma_f32_16x16x32_bf16 v[34:37], v[164:167], v[224:227], v[34:37]
	v_mfma_f32_16x16x32_bf16 v[22:25], v[152:155], v[228:231], 0
	v_mfma_f32_16x16x32_bf16 v[22:25], v[156:159], v[232:235], v[22:25]
	v_mfma_f32_16x16x32_bf16 v[18:21], v[160:163], v[228:231], 0
	v_mfma_f32_16x16x32_bf16 v[18:21], v[164:167], v[232:235], v[18:21]
	v_mfma_f32_16x16x32_bf16 v[6:9], v[152:155], v[236:239], 0
	v_mfma_f32_16x16x32_bf16 v[6:9], v[156:159], v[240:243], v[6:9]
	s_setprio 2
	s_barrier
; #define PG8_STAGE(bufoff, gbase, voff) do { _Pragma("unroll") for (int _i = 0; _i < 2; ++_i) \
;         __builtin_amdgcn_global_load_lds((const unsigned*)((const char*)(gbase) + (voff)[_i]), (PG8_LAS unsigned*)(lds + (bufoff) + ldsw + _i * 8192), 16, 0, AUX_A); } while (0)
; #define PG8_STAGEB(bufoff, gbase, voff) do { _Pragma("unroll") for (int _i = 0; _i < 2; ++_i) \
;         __builtin_amdgcn_global_load_lds((const unsigned*)((const char*)(gbase) + (voff)[_i]), (PG8_LAS unsigned*)(lds + (bufoff) + ldsw + _i * 8192), 16, 0, AUX_B); } while (0)
; #define PG8_LDA(dst, b, h) do { _Pragma("unroll") for (int m = 0; m < 4; ++m) _Pragma("unroll") for (int k = 0; k < 2; ++k) dst[m][k] = *(const PG8_LAS bf16x8*)(lds + PG8_SA(b, h) + aoff + m * 2048 + k * 1024); } while (0)
; #define PG8_LDB(dst, b, h) do { _Pragma("unroll") for (int n = 0; n < 2; ++n) _Pragma("unroll") for (int k = 0; k < 2; ++k) dst[n][k] = *(const PG8_LAS bf16x8*)(lds + PG8_SB(b, h) + boff + n * 2048 + k * 1024); } while (0)
; #define PG8_WAIT_V(n) asm volatile("s_waitcnt vmcnt(" #n ")" ::: "memory")
; #define PG8_WAIT_L(n) asm volatile("s_waitcnt lgkmcnt(" #n ")" ::: "memory")
; template <class Epi, class Sched, bool ALIGN_EPI = false, bool SP2 = false>
; __device__ __forceinline__ void gemm_phase(PG8_LAS unsigned char* lds, const Gemm g, const Sched& S, const Epi& E) {
;     ...
;             PG8_LDB(B0, 0, 0); PG8_LDB(B1, 0, 1); PG8_SCHED; PG8_LDA(At, 0, 0); PG8_STAGE(PG8_SA(1, 1), a1 + hstep, voffA);
;             PG8_WAIT_V(8); PG8_WAIT_L(0); PG8_BAR; PG8_MMA(0, 0, At, B0); PG8_MMA(0, 1, At, B1); PG8_BAR; PG8_SCHED;
;             PG8_LDA(At, 0, 1); PG8_STAGEB(PG8_SB(0, 0), b2, voffB); PG8_STAGEB(PG8_SB(0, 1), b2 + hstep, voffB); PG8_STAGE(PG8_SA(0, 0), a2, voffA);
;             PG8_WAIT_V(8); PG8_WAIT_L(0); PG8_BAR; PG8_MMA(1, 0, At, B0); PG8_MMA(1, 1, At, B1); PG8_BAR; PG8_SCHED;
;             PG8_LDB(B0, 1, 0); PG8_LDB(B1, 1, 1); PG8_SCHED; PG8_LDA(At, 1, 0); PG8_STAGE(PG8_SA(0, 1), a2 + hstep, voffA);
;             PG8_WAIT_V(8); PG8_WAIT_L(0); PG8_BAR; PG8_MMA(0, 0, At, B0); PG8_MMA(0, 1, At, B1); PG8_BAR; PG8_SCHED;
;             PG8_LDA(At, 1, 1); PG8_STAGEB(PG8_SB(1, 0), b3, voffB); PG8_STAGEB(PG8_SB(1, 1), b3 + hstep, voffB); PG8_STAGE(PG8_SA(1, 0), a3, voffA);
;             PG8_WAIT_V(8); PG8_WAIT_L(0); PG8_BAR; PG8_MMA(1, 0, At, B0); PG8_MMA(1, 1, At, B1); PG8_BAR; PG8_SCHED;
	v_mfma_f32_16x16x32_bf16 v[2:5], v[160:163], v[236:239], 0
	v_mfma_f32_16x16x32_bf16 v[2:5], v[164:167], v[240:243], v[2:5]
	s_setprio 0
	v_add_u32_e32 v148, s1, v221
	v_add_u32_e32 v164, s47, v221
	ds_read_b128 v[136:139], v148
	ds_read_b128 v[140:143], v148 offset:1024
	ds_read_b128 v[144:147], v148 offset:2048
	ds_read_b128 v[148:151], v148 offset:3072
	ds_read_b128 v[152:155], v164
	ds_read_b128 v[156:159], v164 offset:1024
	ds_read_b128 v[160:163], v164 offset:2048
	ds_read_b128 v[164:167], v164 offset:3072
	s_mov_b32 m0, s33
	v_lshl_add_u64 v[168:169], s[56:57], 0, v[186:187]
	ds_read_b128 v[192:195], v222 offset:32768
	ds_read_b128 v[196:199], v222 offset:33792
	ds_read_b128 v[200:203], v222 offset:34816
	ds_read_b128 v[224:227], v222 offset:35840
	ds_read_b128 v[228:231], v222 offset:36864
	ds_read_b128 v[232:235], v222 offset:37888
	ds_read_b128 v[236:239], v222 offset:38912
	ds_read_b128 v[240:243], v222 offset:39936
	global_load_lds_dwordx4 v[168:169], off
	v_lshl_add_u64 v[168:169], s[56:57], 0, v[182:183]
	s_mov_b32 m0, s30
	s_nop 0
	global_load_lds_dwordx4 v[168:169], off
	s_waitcnt vmcnt(8)
	s_waitcnt lgkmcnt(0)
	s_setprio 1
	s_barrier
	v_mfma_f32_16x16x32_bf16 v[128:131], v[136:139], v[192:195], v[128:131]
	v_mfma_f32_16x16x32_bf16 v[128:131], v[140:143], v[196:199], v[128:131]
	v_mfma_f32_16x16x32_bf16 v[124:127], v[144:147], v[192:195], v[124:127]
	v_mfma_f32_16x16x32_bf16 v[124:127], v[148:151], v[196:199], v[124:127]
	v_mfma_f32_16x16x32_bf16 v[112:115], v[136:139], v[200:203], v[112:115]
	v_mfma_f32_16x16x32_bf16 v[112:115], v[140:143], v[224:227], v[112:115]
	v_mfma_f32_16x16x32_bf16 v[108:111], v[144:147], v[200:203], v[108:111]
	v_mfma_f32_16x16x32_bf16 v[108:111], v[148:151], v[224:227], v[108:111]
	v_mfma_f32_16x16x32_bf16 v[94:97], v[136:139], v[228:231], v[94:97]
	v_mfma_f32_16x16x32_bf16 v[94:97], v[140:143], v[232:235], v[94:97]
	v_mfma_f32_16x16x32_bf16 v[90:93], v[144:147], v[228:231], v[90:93]
	v_mfma_f32_16x16x32_bf16 v[90:93], v[148:151], v[232:235], v[90:93]
	v_mfma_f32_16x16x32_bf16 v[78:81], v[136:139], v[236:239], v[78:81]
	v_mfma_f32_16x16x32_bf16 v[78:81], v[140:143], v[240:243], v[78:81]
	v_mfma_f32_16x16x32_bf16 v[74:77], v[144:147], v[236:239], v[74:77]
	v_mfma_f32_16x16x32_bf16 v[74:77], v[148:151], v[240:243], v[74:77]
	s_setprio 0
	s_setprio 1
	v_mfma_f32_16x16x32_bf16 v[120:123], v[152:155], v[192:195], v[120:123]
	v_mfma_f32_16x16x32_bf16 v[120:123], v[156:159], v[196:199], v[120:123]
	v_mfma_f32_16x16x32_bf16 v[116:119], v[160:163], v[192:195], v[116:119]
	v_mfma_f32_16x16x32_bf16 v[116:119], v[164:167], v[196:199], v[116:119]
	v_mfma_f32_16x16x32_bf16 v[104:107], v[152:155], v[200:203], v[104:107]
	v_mfma_f32_16x16x32_bf16 v[104:107], v[156:159], v[224:227], v[104:107]
	v_mfma_f32_16x16x32_bf16 v[100:103], v[160:163], v[200:203], v[100:103]
	v_mfma_f32_16x16x32_bf16 v[100:103], v[164:167], v[224:227], v[100:103]
	v_mfma_f32_16x16x32_bf16 v[86:89], v[152:155], v[228:231], v[86:89]
	v_mfma_f32_16x16x32_bf16 v[86:89], v[156:159], v[232:235], v[86:89]
	v_mfma_f32_16x16x32_bf16 v[82:85], v[160:163], v[228:231], v[82:85]
	v_mfma_f32_16x16x32_bf16 v[82:85], v[164:167], v[232:235], v[82:85]
	v_mfma_f32_16x16x32_bf16 v[70:73], v[152:155], v[236:239], v[70:73]
	v_mfma_f32_16x16x32_bf16 v[70:73], v[156:159], v[240:243], v[70:73]
	s_setprio 2
	s_barrier
	v_mfma_f32_16x16x32_bf16 v[66:69], v[160:163], v[236:239], v[66:69]
	v_mfma_f32_16x16x32_bf16 v[66:69], v[164:167], v[240:243], v[66:69]
	s_setprio 0
	s_mov_b32 m0, s0
	v_lshl_add_u64 v[168:169], v[244:245], 0, s[76:77]
	ds_read_b128 v[192:195], v222 offset:49152
	ds_read_b128 v[196:199], v222 offset:50176
	ds_read_b128 v[200:203], v222 offset:51200
	ds_read_b128 v[224:227], v222 offset:52224
	ds_read_b128 v[228:231], v222 offset:53248
	ds_read_b128 v[232:235], v222 offset:54272
	ds_read_b128 v[236:239], v222 offset:55296
	ds_read_b128 v[240:243], v222 offset:56320
	global_load_lds_dwordx4 v[168:169], off
	v_lshl_add_u64 v[168:169], v[246:247], 0, s[76:77]
	s_mov_b32 m0, s89
	s_nop 0
	global_load_lds_dwordx4 v[168:169], off
	v_lshl_add_u64 v[168:169], s[42:43], 0, v[184:185]
	s_mov_b32 m0, s46
	s_nop 0
	global_load_lds_dwordx4 v[168:169], off
	v_lshl_add_u64 v[168:169], s[42:43], 0, v[180:181]
	s_mov_b32 m0, s92
	s_nop 0
	global_load_lds_dwordx4 v[168:169], off
	v_lshl_add_u64 v[168:169], v[212:213], 0, s[76:77]
	s_mov_b32 m0, s90
	s_nop 0
	global_load_lds_dwordx4 v[168:169], off
	v_lshl_add_u64 v[168:169], v[172:173], 0, s[76:77]
	s_mov_b32 m0, s91
	s_nop 0
	global_load_lds_dwordx4 v[168:169], off
	s_waitcnt vmcnt(8)
	s_waitcnt lgkmcnt(0)
	s_setprio 1
	s_barrier
	v_mfma_f32_16x16x32_bf16 v[62:65], v[136:139], v[192:195], v[62:65]
	v_mfma_f32_16x16x32_bf16 v[62:65], v[140:143], v[196:199], v[62:65]
	v_mfma_f32_16x16x32_bf16 v[58:61], v[144:147], v[192:195], v[58:61]
	v_mfma_f32_16x16x32_bf16 v[58:61], v[148:151], v[196:199], v[58:61]
	v_mfma_f32_16x16x32_bf16 v[46:49], v[136:139], v[200:203], v[46:49]
	v_mfma_f32_16x16x32_bf16 v[46:49], v[140:143], v[224:227], v[46:49]
	v_mfma_f32_16x16x32_bf16 v[42:45], v[144:147], v[200:203], v[42:45]
	v_mfma_f32_16x16x32_bf16 v[42:45], v[148:151], v[224:227], v[42:45]
	v_mfma_f32_16x16x32_bf16 v[30:33], v[136:139], v[228:231], v[30:33]
	v_mfma_f32_16x16x32_bf16 v[30:33], v[140:143], v[232:235], v[30:33]
	v_mfma_f32_16x16x32_bf16 v[26:29], v[144:147], v[228:231], v[26:29]
	v_mfma_f32_16x16x32_bf16 v[26:29], v[148:151], v[232:235], v[26:29]
	v_mfma_f32_16x16x32_bf16 v[14:17], v[136:139], v[236:239], v[14:17]
	v_mfma_f32_16x16x32_bf16 v[14:17], v[140:143], v[240:243], v[14:17]
	v_mfma_f32_16x16x32_bf16 v[10:13], v[144:147], v[236:239], v[10:13]
	v_mfma_f32_16x16x32_bf16 v[10:13], v[148:151], v[240:243], v[10:13]
	s_setprio 0
	s_setprio 1
	v_mfma_f32_16x16x32_bf16 v[54:57], v[152:155], v[192:195], v[54:57]
	v_mfma_f32_16x16x32_bf16 v[54:57], v[156:159], v[196:199], v[54:57]
	v_mfma_f32_16x16x32_bf16 v[50:53], v[160:163], v[192:195], v[50:53]
	v_mfma_f32_16x16x32_bf16 v[50:53], v[164:167], v[196:199], v[50:53]
	v_mfma_f32_16x16x32_bf16 v[38:41], v[152:155], v[200:203], v[38:41]
	v_mfma_f32_16x16x32_bf16 v[38:41], v[156:159], v[224:227], v[38:41]
	v_mfma_f32_16x16x32_bf16 v[34:37], v[160:163], v[200:203], v[34:37]
	v_mfma_f32_16x16x32_bf16 v[34:37], v[164:167], v[224:227], v[34:37]
	v_mfma_f32_16x16x32_bf16 v[22:25], v[152:155], v[228:231], v[22:25]
	v_mfma_f32_16x16x32_bf16 v[22:25], v[156:159], v[232:235], v[22:25]
	v_mfma_f32_16x16x32_bf16 v[18:21], v[160:163], v[228:231], v[18:21]
	v_mfma_f32_16x16x32_bf16 v[18:21], v[164:167], v[232:235], v[18:21]
	v_mfma_f32_16x16x32_bf16 v[6:9], v[152:155], v[236:239], v[6:9]
	v_mfma_f32_16x16x32_bf16 v[6:9], v[156:159], v[240:243], v[6:9]
	s_setprio 2
	s_barrier
	v_mfma_f32_16x16x32_bf16 v[2:5], v[160:163], v[236:239], v[2:5]
	v_mfma_f32_16x16x32_bf16 v[2:5], v[164:167], v[240:243], v[2:5]
	s_setprio 0
	v_lshl_add_u64 v[132:133], v[132:133], 0, s[86:87]
	v_lshl_add_u64 v[134:135], v[134:135], 0, s[86:87]
	s_mov_b32 s29, s81

; #define PG8_STAGE(bufoff, gbase, voff) do { _Pragma("unroll") for (int _i = 0; _i < 2; ++_i) \
;         __builtin_amdgcn_global_load_lds((const unsigned*)((const char*)(gbase) + (voff)[_i]), (PG8_LAS unsigned*)(lds + (bufoff) + ldsw + _i * 8192), 16, 0, AUX_A); } while (0)
; #define PG8_STAGEB(bufoff, gbase, voff) do { _Pragma("unroll") for (int _i = 0; _i < 2; ++_i) \
;         __builtin_amdgcn_global_load_lds((const unsigned*)((const char*)(gbase) + (voff)[_i]), (PG8_LAS unsigned*)(lds + (bufoff) + ldsw + _i * 8192), 16, 0, AUX_B); } while (0)
; #define PG8_WAIT_V(n) asm volatile("s_waitcnt vmcnt(" #n ")" ::: "memory")
; template <class Epi, class Sched, bool ALIGN_EPI = false, bool SP2 = false>
; __device__ __forceinline__ void gemm_phase(PG8_LAS unsigned char* lds, const Gemm g, const Sched& S, const Epi& E) {
;     ...
;         for (int t = 0; t < nt; t += 2) {
;             const bool last = (t == nt - 2);
;             const char* a1 = PG8_KP(cA, t + 1, rot, nt);
;             const char* a2 = last ? nAr : PG8_KP(cA, t + 2, rot, nt); const char* b2 = last ? nBr : PG8_KP(cB, t + 2, rot, nt);
;             const char* a3 = a2 + kstep; const char* b3 = b2 + kstep;
;             if (last && has_next) S.a_ready(nxt);
;             if constexpr (SP2) {
;             PG8_LDB(B0, 0, 0); PG8_LDB(B1, 0, 1); PG8_SCHED; PG8_LDA(At, 0, 0); PG8_STAGE(PG8_SA(1, 1), a1 + hstep, voffA);
;             PG8_WAIT_V(8); PG8_WAIT_L(0); PG8_BAR; PG8_MMA(0, 0, At, B0); PG8_MMA(0, 1, At, B1); PG8_BAR; PG8_SCHED;
;             PG8_LDA(At, 0, 1); PG8_STAGEB(PG8_SB(0, 0), b2, voffB); PG8_STAGEB(PG8_SB(0, 1), b2 + hstep, voffB); PG8_STAGE(PG8_SA(0, 0), a2, voffA);
;             PG8_WAIT_V(8); PG8_WAIT_L(0); PG8_BAR; PG8_MMA(1, 0, At, B0); PG8_MMA(1, 1, At, B1); PG8_BAR; PG8_SCHED;
;             PG8_LDB(B0, 1, 0); PG8_LDB(B1, 1, 1); PG8_SCHED; PG8_LDA(At, 1, 0); PG8_STAGE(PG8_SA(0, 1), a2 + hstep, voffA);
;             PG8_WAIT_V(8); PG8_WAIT_L(0); PG8_BAR; PG8_MMA(0, 0, At, B0); PG8_MMA(0, 1, At, B1); PG8_BAR; PG8_SCHED;
;             PG8_LDA(At, 1, 1); PG8_STAGEB(PG8_SB(1, 0), b3, voffB); PG8_STAGEB(PG8_SB(1, 1), b3 + hstep, voffB); PG8_STAGE(PG8_SA(1, 0), a3, voffA);
;             PG8_WAIT_V(8); PG8_WAIT_L(0); PG8_BAR; PG8_MMA(1, 0, At, B0); PG8_MMA(1, 1, At, B1); PG8_BAR; PG8_SCHED;
;     ...
;         if constexpr (ALIGN_EPI) { if (wr == 1) PG8_BAR; }
.Lpk_936:
	s_add_i32 s81, s29, 2
	s_cmp_lt_u32 s29, 14
	s_cselect_b32 s0, 0, -16
	s_add_i32 s0, s81, s0
	s_ashr_i32 s1, s0, 31
	s_lshl_b64 s[0:1], s[0:1], 7
	s_add_u32 s2, s64, s0
	s_addc_u32 s46, s65, s1
	s_add_u32 s0, s26, s0
	s_addc_u32 s1, s27, s1
	s_cmp_eq_u32 s29, 14
	s_cselect_b32 s57, s15, s46
	s_cselect_b32 s56, s17, s2
	s_cselect_b32 s59, s43, s1
	s_cselect_b32 s58, s78, s0
	s_add_i32 s2, 0, 0x10000
	s_add_i32 s83, s2, s33
	s_add_i32 s46, 0, 0x14000
	s_add_i32 m0, s25, 0xc000
	s_add_i32 s82, s25, 0xe000
	s_add_i32 s84, s83, 0x2000
	s_add_u32 s60, s58, 0x40000
	s_addc_u32 s61, s59, 0
	s_add_i32 s88, s46, s33
	s_add_i32 s89, s88, 0x2000
	s_add_i32 s90, 0, 0x18000
	s_add_i32 s91, 0, 0x1c000
	s_add_u32 s54, s56, 0x40000
	s_addc_u32 s55, s57, 0
	s_add_i32 s1, s90, s33
	s_add_i32 s0, s1, 0x2000
	s_add_u32 s52, s58, 0x40080
	s_addc_u32 s53, s59, 0
	s_add_i32 s47, s91, s33
	s_add_i32 s46, s47, 0x2000
	global_load_lds_dwordx4 v[16:17], off
	s_mov_b32 m0, s82
	s_nop 0
	global_load_lds_dwordx4 v[14:15], off
	s_cmp_lg_u64 s[12:13], 0
	s_cbranch_scc1 .Lrp_936
	s_barrier
.Lrp_936:
	s_waitcnt vmcnt(8)
	s_waitcnt lgkmcnt(0)
	s_setprio 1
	s_barrier
	v_mfma_f32_16x16x32_bf16 v[144:147], v[22:25], v[196:199], 0
	v_mfma_f32_16x16x32_bf16 v[144:147], v[34:37], v[200:203], v[144:147]
	v_mfma_f32_16x16x32_bf16 v[140:143], v[38:41], v[196:199], 0
	v_mfma_f32_16x16x32_bf16 v[140:143], v[160:163], v[200:203], v[140:143]
	v_mfma_f32_16x16x32_bf16 v[128:131], v[22:25], v[222:225], 0
	v_mfma_f32_16x16x32_bf16 v[128:131], v[34:37], v[226:229], v[128:131]
	v_mfma_f32_16x16x32_bf16 v[124:127], v[38:41], v[222:225], 0
	v_mfma_f32_16x16x32_bf16 v[124:127], v[160:163], v[226:229], v[124:127]
	v_mfma_f32_16x16x32_bf16 v[112:115], v[22:25], v[230:233], 0
	v_mfma_f32_16x16x32_bf16 v[112:115], v[34:37], v[234:237], v[112:115]
	v_mfma_f32_16x16x32_bf16 v[108:111], v[38:41], v[230:233], 0
	v_mfma_f32_16x16x32_bf16 v[108:111], v[160:163], v[234:237], v[108:111]
	v_mfma_f32_16x16x32_bf16 v[94:97], v[22:25], v[238:241], 0
	v_mfma_f32_16x16x32_bf16 v[94:97], v[34:37], v[242:245], v[94:97]
	v_mfma_f32_16x16x32_bf16 v[90:93], v[38:41], v[238:241], 0
	v_mfma_f32_16x16x32_bf16 v[90:93], v[160:163], v[242:245], v[90:93]
	s_setprio 0
	s_setprio 1
	v_mfma_f32_16x16x32_bf16 v[136:139], v[180:183], v[196:199], 0
	v_mfma_f32_16x16x32_bf16 v[136:139], v[184:187], v[200:203], v[136:139]
	v_mfma_f32_16x16x32_bf16 v[132:135], v[188:191], v[196:199], 0
	v_mfma_f32_16x16x32_bf16 v[132:135], v[192:195], v[200:203], v[132:135]
	v_mfma_f32_16x16x32_bf16 v[120:123], v[180:183], v[222:225], 0
	v_mfma_f32_16x16x32_bf16 v[120:123], v[184:187], v[226:229], v[120:123]
	v_mfma_f32_16x16x32_bf16 v[116:119], v[188:191], v[222:225], 0
	v_mfma_f32_16x16x32_bf16 v[116:119], v[192:195], v[226:229], v[116:119]
	v_mfma_f32_16x16x32_bf16 v[104:107], v[180:183], v[230:233], 0
	v_mfma_f32_16x16x32_bf16 v[104:107], v[184:187], v[234:237], v[104:107]
	v_mfma_f32_16x16x32_bf16 v[100:103], v[188:191], v[230:233], 0
	v_mfma_f32_16x16x32_bf16 v[100:103], v[192:195], v[234:237], v[100:103]
	v_mfma_f32_16x16x32_bf16 v[86:89], v[180:183], v[238:241], 0
	v_mfma_f32_16x16x32_bf16 v[86:89], v[184:187], v[242:245], v[86:89]
	s_setprio 2
	s_barrier
	v_mfma_f32_16x16x32_bf16 v[82:85], v[188:191], v[238:241], 0
	v_mfma_f32_16x16x32_bf16 v[82:85], v[192:195], v[242:245], v[82:85]
	s_setprio 0
	s_mov_b32 m0, s83
	v_lshl_add_u64 v[166:167], s[58:59], 0, v[150:151]
	ds_read_b128 v[196:199], v165 offset:16384
	ds_read_b128 v[200:203], v165 offset:17408
	ds_read_b128 v[222:225], v165 offset:18432
	ds_read_b128 v[226:229], v165 offset:19456
	ds_read_b128 v[230:233], v165 offset:20480
	ds_read_b128 v[234:237], v165 offset:21504
	ds_read_b128 v[238:241], v165 offset:22528
	ds_read_b128 v[242:245], v165 offset:23552
	global_load_lds_dwordx4 v[166:167], off
	v_lshl_add_u64 v[168:169], s[58:59], 0, v[154:155]
	s_mov_b32 m0, s84
	v_lshl_add_u64 v[172:173], s[60:61], 0, v[150:151]
	global_load_lds_dwordx4 v[168:169], off
	s_mov_b32 m0, s88
	v_lshl_add_u64 v[212:213], s[56:57], 0, v[152:153]
	global_load_lds_dwordx4 v[172:173], off
	v_lshl_add_u64 v[172:173], s[60:61], 0, v[154:155]
	s_mov_b32 m0, s89
	s_nop 0
	global_load_lds_dwordx4 v[172:173], off
	v_lshl_add_u64 v[172:173], s[56:57], 0, v[148:149]
	s_mov_b32 m0, s25
	s_nop 0
	global_load_lds_dwordx4 v[172:173], off
	s_mov_b32 m0, s62
	s_nop 0
	global_load_lds_dwordx4 v[212:213], off
	s_waitcnt vmcnt(8)
	s_waitcnt lgkmcnt(0)
	s_setprio 1
	s_barrier
	v_mfma_f32_16x16x32_bf16 v[78:81], v[22:25], v[196:199], 0
	v_mfma_f32_16x16x32_bf16 v[78:81], v[34:37], v[200:203], v[78:81]
	v_mfma_f32_16x16x32_bf16 v[74:77], v[38:41], v[196:199], 0
	v_mfma_f32_16x16x32_bf16 v[74:77], v[160:163], v[200:203], v[74:77]
	v_mfma_f32_16x16x32_bf16 v[62:65], v[22:25], v[222:225], 0
	v_mfma_f32_16x16x32_bf16 v[62:65], v[34:37], v[226:229], v[62:65]
	v_mfma_f32_16x16x32_bf16 v[58:61], v[38:41], v[222:225], 0
	v_mfma_f32_16x16x32_bf16 v[58:61], v[160:163], v[226:229], v[58:61]
	v_mfma_f32_16x16x32_bf16 v[46:49], v[22:25], v[230:233], 0
	v_mfma_f32_16x16x32_bf16 v[46:49], v[34:37], v[234:237], v[46:49]
	v_mfma_f32_16x16x32_bf16 v[42:45], v[38:41], v[230:233], 0
	v_mfma_f32_16x16x32_bf16 v[42:45], v[160:163], v[234:237], v[42:45]
	v_mfma_f32_16x16x32_bf16 v[18:21], v[22:25], v[238:241], 0
	v_mfma_f32_16x16x32_bf16 v[18:21], v[34:37], v[242:245], v[18:21]
	v_mfma_f32_16x16x32_bf16 v[10:13], v[38:41], v[238:241], 0
	v_mfma_f32_16x16x32_bf16 v[10:13], v[160:163], v[242:245], v[10:13]
	s_setprio 0
	s_setprio 1
	v_mfma_f32_16x16x32_bf16 v[50:53], v[188:191], v[222:225], 0
	v_mfma_f32_16x16x32_bf16 v[30:33], v[180:183], v[230:233], 0
	v_mfma_f32_16x16x32_bf16 v[26:29], v[188:191], v[230:233], 0
	v_mfma_f32_16x16x32_bf16 v[6:9], v[180:183], v[238:241], 0
	v_mfma_f32_16x16x32_bf16 v[2:5], v[188:191], v[238:241], 0
	v_mfma_f32_16x16x32_bf16 v[22:25], v[180:183], v[196:199], 0
	v_mfma_f32_16x16x32_bf16 v[34:37], v[188:191], v[196:199], 0
	v_mfma_f32_16x16x32_bf16 v[38:41], v[180:183], v[222:225], 0
	v_mfma_f32_16x16x32_bf16 v[50:53], v[192:195], v[226:229], v[50:53]
	v_mfma_f32_16x16x32_bf16 v[30:33], v[184:187], v[234:237], v[30:33]
	v_mfma_f32_16x16x32_bf16 v[26:29], v[192:195], v[234:237], v[26:29]
	v_mfma_f32_16x16x32_bf16 v[6:9], v[184:187], v[242:245], v[6:9]
	v_mfma_f32_16x16x32_bf16 v[2:5], v[192:195], v[242:245], v[2:5]
	v_mfma_f32_16x16x32_bf16 v[22:25], v[184:187], v[200:203], v[22:25]
	s_setprio 2
	s_barrier
; #define PG8_STAGE(bufoff, gbase, voff) do { _Pragma("unroll") for (int _i = 0; _i < 2; ++_i) \
;         __builtin_amdgcn_global_load_lds((const unsigned*)((const char*)(gbase) + (voff)[_i]), (PG8_LAS unsigned*)(lds + (bufoff) + ldsw + _i * 8192), 16, 0, AUX_A); } while (0)
; #define PG8_STAGEB(bufoff, gbase, voff) do { _Pragma("unroll") for (int _i = 0; _i < 2; ++_i) \
;         __builtin_amdgcn_global_load_lds((const unsigned*)((const char*)(gbase) + (voff)[_i]), (PG8_LAS unsigned*)(lds + (bufoff) + ldsw + _i * 8192), 16, 0, AUX_B); } while (0)
; #define PG8_LDA(dst, b, h) do { _Pragma("unroll") for (int m = 0; m < 4; ++m) _Pragma("unroll") for (int k = 0; k < 2; ++k) dst[m][k] = *(const PG8_LAS bf16x8*)(lds + PG8_SA(b, h) + aoff + m * 2048 + k * 1024); } while (0)
; #define PG8_LDB(dst, b, h) do { _Pragma("unroll") for (int n = 0; n < 2; ++n) _Pragma("unroll") for (int k = 0; k < 2; ++k) dst[n][k] = *(const PG8_LAS bf16x8*)(lds + PG8_SB(b, h) + boff + n * 2048 + k * 1024); } while (0)
; #define PG8_WAIT_V(n) asm volatile("s_waitcnt vmcnt(" #n ")" ::: "memory")
; #define PG8_WAIT_L(n) asm volatile("s_waitcnt lgkmcnt(" #n ")" ::: "memory")
; template <class Epi, class Sched, bool ALIGN_EPI = false, bool SP2 = false>
; __device__ __forceinline__ void gemm_phase(PG8_LAS unsigned char* lds, const Gemm g, const Sched& S, const Epi& E) {
;     ...
;             PG8_LDB(B0, 0, 0); PG8_LDB(B1, 0, 1); PG8_SCHED; PG8_LDA(At, 0, 0); PG8_STAGE(PG8_SA(1, 1), a1 + hstep, voffA);
;             PG8_WAIT_V(8); PG8_WAIT_L(0); PG8_BAR; PG8_MMA(0, 0, At, B0); PG8_MMA(0, 1, At, B1); PG8_BAR; PG8_SCHED;
;             PG8_LDA(At, 0, 1); PG8_STAGEB(PG8_SB(0, 0), b2, voffB); PG8_STAGEB(PG8_SB(0, 1), b2 + hstep, voffB); PG8_STAGE(PG8_SA(0, 0), a2, voffA);
;             PG8_WAIT_V(8); PG8_WAIT_L(0); PG8_BAR; PG8_MMA(1, 0, At, B0); PG8_MMA(1, 1, At, B1); PG8_BAR; PG8_SCHED;
;             PG8_LDB(B0, 1, 0); PG8_LDB(B1, 1, 1); PG8_SCHED; PG8_LDA(At, 1, 0); PG8_STAGE(PG8_SA(0, 1), a2 + hstep, voffA);
;             PG8_WAIT_V(8); PG8_WAIT_L(0); PG8_BAR; PG8_MMA(0, 0, At, B0); PG8_MMA(0, 1, At, B1); PG8_BAR; PG8_SCHED;
;             PG8_LDA(At, 1, 1); PG8_STAGEB(PG8_SB(1, 0), b3, voffB); PG8_STAGEB(PG8_SB(1, 1), b3 + hstep, voffB); PG8_STAGE(PG8_SA(1, 0), a3, voffA);
;             PG8_WAIT_V(8); PG8_WAIT_L(0); PG8_BAR; PG8_MMA(1, 0, At, B0); PG8_MMA(1, 1, At, B1); PG8_BAR; PG8_SCHED;
	v_mfma_f32_16x16x32_bf16 v[34:37], v[192:195], v[200:203], v[34:37]
	v_mfma_f32_16x16x32_bf16 v[38:41], v[184:187], v[226:229], v[38:41]
	s_setprio 0
	v_add_u32_e32 v160, s90, v99
	v_add_u32_e32 v192, s91, v99
	ds_read_b128 v[54:57], v160
	ds_read_b128 v[66:69], v160 offset:1024
	ds_read_b128 v[70:73], v160 offset:2048
	ds_read_b128 v[160:163], v160 offset:3072
	ds_read_b128 v[180:183], v192
	ds_read_b128 v[184:187], v192 offset:1024
	ds_read_b128 v[188:191], v192 offset:2048
	ds_read_b128 v[192:195], v192 offset:3072
	s_mov_b32 m0, s63
	v_lshl_add_u64 v[246:247], s[54:55], 0, v[148:149]
	ds_read_b128 v[196:199], v165 offset:32768
	ds_read_b128 v[200:203], v165 offset:33792
	ds_read_b128 v[222:225], v165 offset:34816
	ds_read_b128 v[226:229], v165 offset:35840
	ds_read_b128 v[230:233], v165 offset:36864
	ds_read_b128 v[234:237], v165 offset:37888
	ds_read_b128 v[238:241], v165 offset:38912
	ds_read_b128 v[242:245], v165 offset:39936
	global_load_lds_dwordx4 v[246:247], off
	v_lshl_add_u64 v[246:247], s[54:55], 0, v[152:153]
	s_mov_b32 m0, s69
	s_nop 0
	global_load_lds_dwordx4 v[246:247], off
	s_waitcnt vmcnt(8)
	s_waitcnt lgkmcnt(0)
	s_setprio 1
	s_barrier
	v_mfma_f32_16x16x32_bf16 v[144:147], v[54:57], v[196:199], v[144:147]
	v_mfma_f32_16x16x32_bf16 v[144:147], v[66:69], v[200:203], v[144:147]
	v_mfma_f32_16x16x32_bf16 v[140:143], v[70:73], v[196:199], v[140:143]
	v_mfma_f32_16x16x32_bf16 v[140:143], v[160:163], v[200:203], v[140:143]
	v_mfma_f32_16x16x32_bf16 v[128:131], v[54:57], v[222:225], v[128:131]
	v_mfma_f32_16x16x32_bf16 v[128:131], v[66:69], v[226:229], v[128:131]
	v_mfma_f32_16x16x32_bf16 v[124:127], v[70:73], v[222:225], v[124:127]
	v_mfma_f32_16x16x32_bf16 v[124:127], v[160:163], v[226:229], v[124:127]
	v_mfma_f32_16x16x32_bf16 v[112:115], v[54:57], v[230:233], v[112:115]
	v_mfma_f32_16x16x32_bf16 v[112:115], v[66:69], v[234:237], v[112:115]
	v_mfma_f32_16x16x32_bf16 v[108:111], v[70:73], v[230:233], v[108:111]
	v_mfma_f32_16x16x32_bf16 v[108:111], v[160:163], v[234:237], v[108:111]
	v_mfma_f32_16x16x32_bf16 v[94:97], v[54:57], v[238:241], v[94:97]
	v_mfma_f32_16x16x32_bf16 v[94:97], v[66:69], v[242:245], v[94:97]
	v_mfma_f32_16x16x32_bf16 v[90:93], v[70:73], v[238:241], v[90:93]
	v_mfma_f32_16x16x32_bf16 v[90:93], v[160:163], v[242:245], v[90:93]
	s_setprio 0
	s_setprio 1
	v_mfma_f32_16x16x32_bf16 v[136:139], v[180:183], v[196:199], v[136:139]
	v_mfma_f32_16x16x32_bf16 v[136:139], v[184:187], v[200:203], v[136:139]
	v_mfma_f32_16x16x32_bf16 v[132:135], v[188:191], v[196:199], v[132:135]
	v_mfma_f32_16x16x32_bf16 v[132:135], v[192:195], v[200:203], v[132:135]
	v_mfma_f32_16x16x32_bf16 v[120:123], v[180:183], v[222:225], v[120:123]
	v_mfma_f32_16x16x32_bf16 v[120:123], v[184:187], v[226:229], v[120:123]
	v_mfma_f32_16x16x32_bf16 v[116:119], v[188:191], v[222:225], v[116:119]
	v_mfma_f32_16x16x32_bf16 v[116:119], v[192:195], v[226:229], v[116:119]
	v_mfma_f32_16x16x32_bf16 v[104:107], v[180:183], v[230:233], v[104:107]
	v_mfma_f32_16x16x32_bf16 v[104:107], v[184:187], v[234:237], v[104:107]
	v_mfma_f32_16x16x32_bf16 v[100:103], v[188:191], v[230:233], v[100:103]
	v_mfma_f32_16x16x32_bf16 v[100:103], v[192:195], v[234:237], v[100:103]
	v_mfma_f32_16x16x32_bf16 v[86:89], v[180:183], v[238:241], v[86:89]
	v_mfma_f32_16x16x32_bf16 v[86:89], v[184:187], v[242:245], v[86:89]
	s_setprio 2
	s_barrier
	v_mfma_f32_16x16x32_bf16 v[82:85], v[188:191], v[238:241], v[82:85]
	v_mfma_f32_16x16x32_bf16 v[82:85], v[192:195], v[242:245], v[82:85]
	s_setprio 0
	s_mov_b32 m0, s1
	v_lshl_add_u64 v[166:167], v[166:167], 0, s[76:77]
	ds_read_b128 v[196:199], v165 offset:49152
	ds_read_b128 v[200:203], v165 offset:50176
	ds_read_b128 v[222:225], v165 offset:51200
	ds_read_b128 v[226:229], v165 offset:52224
	ds_read_b128 v[230:233], v165 offset:53248
	ds_read_b128 v[234:237], v165 offset:54272
	ds_read_b128 v[238:241], v165 offset:55296
	ds_read_b128 v[242:245], v165 offset:56320
	global_load_lds_dwordx4 v[166:167], off
	v_lshl_add_u64 v[166:167], v[168:169], 0, s[76:77]
	s_mov_b32 m0, s0
	s_nop 0
	global_load_lds_dwordx4 v[166:167], off
	v_lshl_add_u64 v[166:167], s[52:53], 0, v[150:151]
	s_mov_b32 m0, s47
	s_nop 0
	global_load_lds_dwordx4 v[166:167], off
	v_lshl_add_u64 v[166:167], s[52:53], 0, v[154:155]
	s_mov_b32 m0, s46
	s_nop 0
	global_load_lds_dwordx4 v[166:167], off
	v_lshl_add_u64 v[166:167], v[172:173], 0, s[76:77]
	s_mov_b32 m0, s70
	s_nop 0
	global_load_lds_dwordx4 v[166:167], off
	v_lshl_add_u64 v[166:167], v[212:213], 0, s[76:77]
	s_mov_b32 m0, s71
	s_nop 0
	global_load_lds_dwordx4 v[166:167], off
	s_waitcnt vmcnt(8)
	s_waitcnt lgkmcnt(0)
	s_setprio 1
	s_barrier
	v_mfma_f32_16x16x32_bf16 v[78:81], v[54:57], v[196:199], v[78:81]
	v_mfma_f32_16x16x32_bf16 v[78:81], v[66:69], v[200:203], v[78:81]
	v_mfma_f32_16x16x32_bf16 v[74:77], v[70:73], v[196:199], v[74:77]
	v_mfma_f32_16x16x32_bf16 v[74:77], v[160:163], v[200:203], v[74:77]
	v_mfma_f32_16x16x32_bf16 v[62:65], v[54:57], v[222:225], v[62:65]
	v_mfma_f32_16x16x32_bf16 v[62:65], v[66:69], v[226:229], v[62:65]
	v_mfma_f32_16x16x32_bf16 v[58:61], v[70:73], v[222:225], v[58:61]
	v_mfma_f32_16x16x32_bf16 v[58:61], v[160:163], v[226:229], v[58:61]
	v_mfma_f32_16x16x32_bf16 v[46:49], v[54:57], v[230:233], v[46:49]
	v_mfma_f32_16x16x32_bf16 v[46:49], v[66:69], v[234:237], v[46:49]
	v_mfma_f32_16x16x32_bf16 v[42:45], v[70:73], v[230:233], v[42:45]
	v_mfma_f32_16x16x32_bf16 v[42:45], v[160:163], v[234:237], v[42:45]
	v_mfma_f32_16x16x32_bf16 v[18:21], v[54:57], v[238:241], v[18:21]
	v_mfma_f32_16x16x32_bf16 v[18:21], v[66:69], v[242:245], v[18:21]
	v_mfma_f32_16x16x32_bf16 v[10:13], v[70:73], v[238:241], v[10:13]
	v_mfma_f32_16x16x32_bf16 v[10:13], v[160:163], v[242:245], v[10:13]
	s_setprio 0
	s_setprio 1
	v_mfma_f32_16x16x32_bf16 v[22:25], v[180:183], v[196:199], v[22:25]
	v_mfma_f32_16x16x32_bf16 v[70:73], v[184:187], v[200:203], v[22:25]
	v_mfma_f32_16x16x32_bf16 v[22:25], v[188:191], v[196:199], v[34:37]
	v_mfma_f32_16x16x32_bf16 v[66:69], v[192:195], v[200:203], v[22:25]
	v_mfma_f32_16x16x32_bf16 v[22:25], v[180:183], v[222:225], v[38:41]
	v_mfma_f32_16x16x32_bf16 v[54:57], v[184:187], v[226:229], v[22:25]
	v_mfma_f32_16x16x32_bf16 v[22:25], v[188:191], v[222:225], v[50:53]
	v_mfma_f32_16x16x32_bf16 v[50:53], v[192:195], v[226:229], v[22:25]
	v_mfma_f32_16x16x32_bf16 v[22:25], v[180:183], v[230:233], v[30:33]
	v_mfma_f32_16x16x32_bf16 v[30:33], v[184:187], v[234:237], v[22:25]
	v_mfma_f32_16x16x32_bf16 v[22:25], v[188:191], v[230:233], v[26:29]
	v_mfma_f32_16x16x32_bf16 v[6:9], v[180:183], v[238:241], v[6:9]
	v_mfma_f32_16x16x32_bf16 v[2:5], v[188:191], v[238:241], v[2:5]
	v_mfma_f32_16x16x32_bf16 v[26:29], v[192:195], v[234:237], v[22:25]
	s_setprio 2
	s_barrier
	v_mfma_f32_16x16x32_bf16 v[6:9], v[184:187], v[242:245], v[6:9]
	v_mfma_f32_16x16x32_bf16 v[2:5], v[192:195], v[242:245], v[2:5]
	s_setprio 0
	v_lshl_add_u64 v[14:15], v[14:15], 0, s[86:87]
	v_lshl_add_u64 v[16:17], v[16:17], 0, s[86:87]
	s_mov_b32 s29, s81

; #define PG8_STAGE(bufoff, gbase, voff) do { _Pragma("unroll") for (int _i = 0; _i < 2; ++_i) \
;         __builtin_amdgcn_global_load_lds((const unsigned*)((const char*)(gbase) + (voff)[_i]), (PG8_LAS unsigned*)(lds + (bufoff) + ldsw + _i * 8192), 16, 0, AUX_A); } while (0)
; #define PG8_STAGEB(bufoff, gbase, voff) do { _Pragma("unroll") for (int _i = 0; _i < 2; ++_i) \
;         __builtin_amdgcn_global_load_lds((const unsigned*)((const char*)(gbase) + (voff)[_i]), (PG8_LAS unsigned*)(lds + (bufoff) + ldsw + _i * 8192), 16, 0, AUX_B); } while (0)
; #define PG8_WAIT_V(n) asm volatile("s_waitcnt vmcnt(" #n ")" ::: "memory")
; template <class Epi, class Sched, bool ALIGN_EPI = false, bool SP2 = false>
; __device__ __forceinline__ void gemm_phase(PG8_LAS unsigned char* lds, const Gemm g, const Sched& S, const Epi& E) {
;     ...
;         for (int t = 0; t < nt; t += 2) {
;             const bool last = (t == nt - 2);
;             const char* a1 = PG8_KP(cA, t + 1, rot, nt);
;             const char* a2 = last ? nAr : PG8_KP(cA, t + 2, rot, nt); const char* b2 = last ? nBr : PG8_KP(cB, t + 2, rot, nt);
;             const char* a3 = a2 + kstep; const char* b3 = b2 + kstep;
;             if (last && has_next) S.a_ready(nxt);
;             if constexpr (SP2) {
;             PG8_LDB(B0, 0, 0); PG8_LDB(B1, 0, 1); PG8_SCHED; PG8_LDA(At, 0, 0); PG8_STAGE(PG8_SA(1, 1), a1 + hstep, voffA);
;             PG8_WAIT_V(8); PG8_WAIT_L(0); PG8_BAR; PG8_MMA(0, 0, At, B0); PG8_MMA(0, 1, At, B1); PG8_BAR; PG8_SCHED;
;             PG8_LDA(At, 0, 1); PG8_STAGEB(PG8_SB(0, 0), b2, voffB); PG8_STAGEB(PG8_SB(0, 1), b2 + hstep, voffB); PG8_STAGE(PG8_SA(0, 0), a2, voffA);
;             PG8_WAIT_V(8); PG8_WAIT_L(0); PG8_BAR; PG8_MMA(1, 0, At, B0); PG8_MMA(1, 1, At, B1); PG8_BAR; PG8_SCHED;
;             PG8_LDB(B0, 1, 0); PG8_LDB(B1, 1, 1); PG8_SCHED; PG8_LDA(At, 1, 0); PG8_STAGE(PG8_SA(0, 1), a2 + hstep, voffA);
;             PG8_WAIT_V(8); PG8_WAIT_L(0); PG8_BAR; PG8_MMA(0, 0, At, B0); PG8_MMA(0, 1, At, B1); PG8_BAR; PG8_SCHED;
;             PG8_LDA(At, 1, 1); PG8_STAGEB(PG8_SB(1, 0), b3, voffB); PG8_STAGEB(PG8_SB(1, 1), b3 + hstep, voffB); PG8_STAGE(PG8_SA(1, 0), a3, voffA);
;             PG8_WAIT_V(8); PG8_WAIT_L(0); PG8_BAR; PG8_MMA(1, 0, At, B0); PG8_MMA(1, 1, At, B1); PG8_BAR; PG8_SCHED;
;     ...
;         if constexpr (ALIGN_EPI) { if (wr == 1) PG8_BAR; }
.Lpk_1067:
	s_add_i32 s81, s29, 2
	s_cmp_lt_u32 s29, 14
	s_cselect_b32 s0, 0, -16
	s_add_i32 s0, s81, s0
	s_ashr_i32 s1, s0, 31
	s_lshl_b64 s[0:1], s[0:1], 7
	s_add_u32 s2, s52, s0
	s_addc_u32 s46, s53, s1
	s_add_u32 s0, s42, s0
	s_addc_u32 s1, s43, s1
	s_cmp_eq_u32 s29, 14
	s_cselect_b32 s59, s15, s46
	s_cselect_b32 s58, s17, s2
	s_cselect_b32 s61, s92, s1
	s_cselect_b32 s60, s93, s0
	s_add_i32 s2, 0, 0x10000
	s_add_i32 s94, s2, s70
	s_add_i32 s46, 0, 0x14000
	s_add_i32 m0, s71, 0xc000
	s_add_i32 s84, s71, 0xe000
	s_add_i32 s95, s94, 0x2000
	s_add_u32 s62, s60, 0x40000
	s_addc_u32 s63, s61, 0
	s_add_i32 s96, s46, s70
	s_add_i32 s97, s96, 0x2000
	s_add_i32 vcc_lo, 0, 0x18000
	s_add_i32 vcc_hi, 0, 0x1c000
	s_add_u32 s56, s58, 0x40000
	s_addc_u32 s57, s59, 0
	s_add_i32 s1, vcc_lo, s70
	s_add_i32 s0, s1, 0x2000
	s_add_u32 s54, s60, 0x40080
	s_addc_u32 s55, s61, 0
	s_add_i32 s47, vcc_hi, s70
	s_add_i32 s46, s47, 0x2000
	global_load_lds_dwordx4 v[146:147], off
	s_mov_b32 m0, s84
	s_nop 0
	global_load_lds_dwordx4 v[144:145], off
	s_cmp_lg_u64 s[12:13], 0
	s_cbranch_scc1 .Lrp_1067
	s_barrier
.Lrp_1067:
	s_waitcnt vmcnt(8)
	s_waitcnt lgkmcnt(0)
	s_setprio 1
	s_barrier
	v_mfma_f32_16x16x32_bf16 v[128:131], v[152:155], v[196:199], 0
	v_mfma_f32_16x16x32_bf16 v[128:131], v[156:159], v[200:203], v[128:131]
	v_mfma_f32_16x16x32_bf16 v[124:127], v[160:163], v[196:199], 0
	v_mfma_f32_16x16x32_bf16 v[124:127], v[164:167], v[200:203], v[124:127]
	v_mfma_f32_16x16x32_bf16 v[112:115], v[152:155], v[222:225], 0
	v_mfma_f32_16x16x32_bf16 v[112:115], v[156:159], v[226:229], v[112:115]
	v_mfma_f32_16x16x32_bf16 v[108:111], v[160:163], v[222:225], 0
	v_mfma_f32_16x16x32_bf16 v[108:111], v[164:167], v[226:229], v[108:111]
	v_mfma_f32_16x16x32_bf16 v[94:97], v[152:155], v[230:233], 0
	v_mfma_f32_16x16x32_bf16 v[94:97], v[156:159], v[234:237], v[94:97]
	v_mfma_f32_16x16x32_bf16 v[90:93], v[160:163], v[230:233], 0
	v_mfma_f32_16x16x32_bf16 v[90:93], v[164:167], v[234:237], v[90:93]
	v_mfma_f32_16x16x32_bf16 v[78:81], v[152:155], v[238:241], 0
	v_mfma_f32_16x16x32_bf16 v[78:81], v[156:159], v[242:245], v[78:81]
	v_mfma_f32_16x16x32_bf16 v[74:77], v[160:163], v[238:241], 0
	v_mfma_f32_16x16x32_bf16 v[74:77], v[164:167], v[242:245], v[74:77]
	s_setprio 0
	s_setprio 1
	v_mfma_f32_16x16x32_bf16 v[120:123], v[180:183], v[196:199], 0
	v_mfma_f32_16x16x32_bf16 v[120:123], v[184:187], v[200:203], v[120:123]
	v_mfma_f32_16x16x32_bf16 v[116:119], v[188:191], v[196:199], 0
	v_mfma_f32_16x16x32_bf16 v[116:119], v[192:195], v[200:203], v[116:119]
	v_mfma_f32_16x16x32_bf16 v[104:107], v[180:183], v[222:225], 0
	v_mfma_f32_16x16x32_bf16 v[104:107], v[184:187], v[226:229], v[104:107]
	v_mfma_f32_16x16x32_bf16 v[100:103], v[188:191], v[222:225], 0
	v_mfma_f32_16x16x32_bf16 v[100:103], v[192:195], v[226:229], v[100:103]
	v_mfma_f32_16x16x32_bf16 v[86:89], v[180:183], v[230:233], 0
	v_mfma_f32_16x16x32_bf16 v[86:89], v[184:187], v[234:237], v[86:89]
	v_mfma_f32_16x16x32_bf16 v[82:85], v[188:191], v[230:233], 0
	v_mfma_f32_16x16x32_bf16 v[82:85], v[192:195], v[234:237], v[82:85]
	v_mfma_f32_16x16x32_bf16 v[70:73], v[180:183], v[238:241], 0
	v_mfma_f32_16x16x32_bf16 v[70:73], v[184:187], v[242:245], v[70:73]
	s_setprio 2
	s_barrier
	v_mfma_f32_16x16x32_bf16 v[66:69], v[188:191], v[238:241], 0
	v_mfma_f32_16x16x32_bf16 v[66:69], v[192:195], v[242:245], v[66:69]
	s_setprio 0
	s_mov_b32 m0, s94
	v_lshl_add_u64 v[148:149], s[60:61], 0, v[136:137]
	ds_read_b128 v[196:199], v151 offset:16384
	ds_read_b128 v[200:203], v151 offset:17408
	ds_read_b128 v[222:225], v151 offset:18432
	ds_read_b128 v[226:229], v151 offset:19456
	ds_read_b128 v[230:233], v151 offset:20480
	ds_read_b128 v[234:237], v151 offset:21504
	ds_read_b128 v[238:241], v151 offset:22528
	ds_read_b128 v[242:245], v151 offset:23552
	global_load_lds_dwordx4 v[148:149], off
	v_lshl_add_u64 v[168:169], s[60:61], 0, v[132:133]
	s_mov_b32 m0, s95
	v_lshl_add_u64 v[172:173], s[62:63], 0, v[136:137]
	global_load_lds_dwordx4 v[168:169], off
	s_mov_b32 m0, s96
	v_lshl_add_u64 v[212:213], s[58:59], 0, v[134:135]
	global_load_lds_dwordx4 v[172:173], off
	v_lshl_add_u64 v[172:173], s[62:63], 0, v[132:133]
	s_mov_b32 m0, s97
	s_nop 0
	global_load_lds_dwordx4 v[172:173], off
	v_lshl_add_u64 v[172:173], s[58:59], 0, v[138:139]
	s_mov_b32 m0, s71
	s_nop 0
	global_load_lds_dwordx4 v[172:173], off
	s_mov_b32 m0, s75
	s_nop 0
	global_load_lds_dwordx4 v[212:213], off
	s_waitcnt vmcnt(8)
	s_waitcnt lgkmcnt(0)
	s_setprio 1
	s_barrier
	v_mfma_f32_16x16x32_bf16 v[62:65], v[152:155], v[196:199], 0
	v_mfma_f32_16x16x32_bf16 v[62:65], v[156:159], v[200:203], v[62:65]
	v_mfma_f32_16x16x32_bf16 v[58:61], v[160:163], v[196:199], 0
	v_mfma_f32_16x16x32_bf16 v[58:61], v[164:167], v[200:203], v[58:61]
	v_mfma_f32_16x16x32_bf16 v[46:49], v[152:155], v[222:225], 0
	v_mfma_f32_16x16x32_bf16 v[46:49], v[156:159], v[226:229], v[46:49]
	v_mfma_f32_16x16x32_bf16 v[42:45], v[160:163], v[222:225], 0
	v_mfma_f32_16x16x32_bf16 v[42:45], v[164:167], v[226:229], v[42:45]
	v_mfma_f32_16x16x32_bf16 v[30:33], v[152:155], v[230:233], 0
	v_mfma_f32_16x16x32_bf16 v[30:33], v[156:159], v[234:237], v[30:33]
	v_mfma_f32_16x16x32_bf16 v[26:29], v[160:163], v[230:233], 0
	v_mfma_f32_16x16x32_bf16 v[26:29], v[164:167], v[234:237], v[26:29]
	v_mfma_f32_16x16x32_bf16 v[14:17], v[152:155], v[238:241], 0
	v_mfma_f32_16x16x32_bf16 v[14:17], v[156:159], v[242:245], v[14:17]
	v_mfma_f32_16x16x32_bf16 v[10:13], v[160:163], v[238:241], 0
	v_mfma_f32_16x16x32_bf16 v[10:13], v[164:167], v[242:245], v[10:13]
	s_setprio 0
	s_setprio 1
	v_mfma_f32_16x16x32_bf16 v[54:57], v[180:183], v[196:199], 0
	v_mfma_f32_16x16x32_bf16 v[54:57], v[184:187], v[200:203], v[54:57]
	v_mfma_f32_16x16x32_bf16 v[50:53], v[188:191], v[196:199], 0
	v_mfma_f32_16x16x32_bf16 v[50:53], v[192:195], v[200:203], v[50:53]
	v_mfma_f32_16x16x32_bf16 v[38:41], v[180:183], v[222:225], 0
	v_mfma_f32_16x16x32_bf16 v[38:41], v[184:187], v[226:229], v[38:41]
	v_mfma_f32_16x16x32_bf16 v[34:37], v[188:191], v[222:225], 0
	v_mfma_f32_16x16x32_bf16 v[34:37], v[192:195], v[226:229], v[34:37]
	v_mfma_f32_16x16x32_bf16 v[22:25], v[180:183], v[230:233], 0
	v_mfma_f32_16x16x32_bf16 v[22:25], v[184:187], v[234:237], v[22:25]
	v_mfma_f32_16x16x32_bf16 v[18:21], v[188:191], v[230:233], 0
	v_mfma_f32_16x16x32_bf16 v[18:21], v[192:195], v[234:237], v[18:21]
	v_mfma_f32_16x16x32_bf16 v[6:9], v[180:183], v[238:241], 0
	v_mfma_f32_16x16x32_bf16 v[6:9], v[184:187], v[242:245], v[6:9]
	s_setprio 2
	s_barrier
; #define PG8_STAGE(bufoff, gbase, voff) do { _Pragma("unroll") for (int _i = 0; _i < 2; ++_i) \
;         __builtin_amdgcn_global_load_lds((const unsigned*)((const char*)(gbase) + (voff)[_i]), (PG8_LAS unsigned*)(lds + (bufoff) + ldsw + _i * 8192), 16, 0, AUX_A); } while (0)
; #define PG8_STAGEB(bufoff, gbase, voff) do { _Pragma("unroll") for (int _i = 0; _i < 2; ++_i) \
;         __builtin_amdgcn_global_load_lds((const unsigned*)((const char*)(gbase) + (voff)[_i]), (PG8_LAS unsigned*)(lds + (bufoff) + ldsw + _i * 8192), 16, 0, AUX_B); } while (0)
; #define PG8_LDA(dst, b, h) do { _Pragma("unroll") for (int m = 0; m < 4; ++m) _Pragma("unroll") for (int k = 0; k < 2; ++k) dst[m][k] = *(const PG8_LAS bf16x8*)(lds + PG8_SA(b, h) + aoff + m * 2048 + k * 1024); } while (0)
; #define PG8_LDB(dst, b, h) do { _Pragma("unroll") for (int n = 0; n < 2; ++n) _Pragma("unroll") for (int k = 0; k < 2; ++k) dst[n][k] = *(const PG8_LAS bf16x8*)(lds + PG8_SB(b, h) + boff + n * 2048 + k * 1024); } while (0)
; #define PG8_WAIT_V(n) asm volatile("s_waitcnt vmcnt(" #n ")" ::: "memory")
; #define PG8_WAIT_L(n) asm volatile("s_waitcnt lgkmcnt(" #n ")" ::: "memory")
; template <class Epi, class Sched, bool ALIGN_EPI = false, bool SP2 = false>
; __device__ __forceinline__ void gemm_phase(PG8_LAS unsigned char* lds, const Gemm g, const Sched& S, const Epi& E) {
;     ...
;             PG8_LDB(B0, 0, 0); PG8_LDB(B1, 0, 1); PG8_SCHED; PG8_LDA(At, 0, 0); PG8_STAGE(PG8_SA(1, 1), a1 + hstep, voffA);
;             PG8_WAIT_V(8); PG8_WAIT_L(0); PG8_BAR; PG8_MMA(0, 0, At, B0); PG8_MMA(0, 1, At, B1); PG8_BAR; PG8_SCHED;
;             PG8_LDA(At, 0, 1); PG8_STAGEB(PG8_SB(0, 0), b2, voffB); PG8_STAGEB(PG8_SB(0, 1), b2 + hstep, voffB); PG8_STAGE(PG8_SA(0, 0), a2, voffA);
;             PG8_WAIT_V(8); PG8_WAIT_L(0); PG8_BAR; PG8_MMA(1, 0, At, B0); PG8_MMA(1, 1, At, B1); PG8_BAR; PG8_SCHED;
;             PG8_LDB(B0, 1, 0); PG8_LDB(B1, 1, 1); PG8_SCHED; PG8_LDA(At, 1, 0); PG8_STAGE(PG8_SA(0, 1), a2 + hstep, voffA);
;             PG8_WAIT_V(8); PG8_WAIT_L(0); PG8_BAR; PG8_MMA(0, 0, At, B0); PG8_MMA(0, 1, At, B1); PG8_BAR; PG8_SCHED;
;             PG8_LDA(At, 1, 1); PG8_STAGEB(PG8_SB(1, 0), b3, voffB); PG8_STAGEB(PG8_SB(1, 1), b3 + hstep, voffB); PG8_STAGE(PG8_SA(1, 0), a3, voffA);
;             PG8_WAIT_V(8); PG8_WAIT_L(0); PG8_BAR; PG8_MMA(1, 0, At, B0); PG8_MMA(1, 1, At, B1); PG8_BAR; PG8_SCHED;
	v_mfma_f32_16x16x32_bf16 v[2:5], v[188:191], v[238:241], 0
	v_mfma_f32_16x16x32_bf16 v[2:5], v[192:195], v[242:245], v[2:5]
	s_setprio 0
	v_add_u32_e32 v164, vcc_lo, v99
	v_add_u32_e32 v192, vcc_hi, v99
	ds_read_b128 v[152:155], v164
	ds_read_b128 v[156:159], v164 offset:1024
	ds_read_b128 v[160:163], v164 offset:2048
	ds_read_b128 v[164:167], v164 offset:3072
	ds_read_b128 v[180:183], v192
	ds_read_b128 v[184:187], v192 offset:1024
	ds_read_b128 v[188:191], v192 offset:2048
	ds_read_b128 v[192:195], v192 offset:3072
	s_mov_b32 m0, s78
	v_lshl_add_u64 v[246:247], s[56:57], 0, v[138:139]
	ds_read_b128 v[196:199], v151 offset:32768
	ds_read_b128 v[200:203], v151 offset:33792
	ds_read_b128 v[222:225], v151 offset:34816
	ds_read_b128 v[226:229], v151 offset:35840
	ds_read_b128 v[230:233], v151 offset:36864
	ds_read_b128 v[234:237], v151 offset:37888
	ds_read_b128 v[238:241], v151 offset:38912
	ds_read_b128 v[242:245], v151 offset:39936
	global_load_lds_dwordx4 v[246:247], off
	v_lshl_add_u64 v[246:247], s[56:57], 0, v[134:135]
	s_mov_b32 m0, s82
	s_nop 0
	global_load_lds_dwordx4 v[246:247], off
	s_waitcnt vmcnt(8)
	s_waitcnt lgkmcnt(0)
	s_setprio 1
	s_barrier
	v_mfma_f32_16x16x32_bf16 v[128:131], v[152:155], v[196:199], v[128:131]
	v_mfma_f32_16x16x32_bf16 v[128:131], v[156:159], v[200:203], v[128:131]
	v_mfma_f32_16x16x32_bf16 v[124:127], v[160:163], v[196:199], v[124:127]
	v_mfma_f32_16x16x32_bf16 v[124:127], v[164:167], v[200:203], v[124:127]
	v_mfma_f32_16x16x32_bf16 v[112:115], v[152:155], v[222:225], v[112:115]
	v_mfma_f32_16x16x32_bf16 v[112:115], v[156:159], v[226:229], v[112:115]
	v_mfma_f32_16x16x32_bf16 v[108:111], v[160:163], v[222:225], v[108:111]
	v_mfma_f32_16x16x32_bf16 v[108:111], v[164:167], v[226:229], v[108:111]
	v_mfma_f32_16x16x32_bf16 v[94:97], v[152:155], v[230:233], v[94:97]
	v_mfma_f32_16x16x32_bf16 v[94:97], v[156:159], v[234:237], v[94:97]
	v_mfma_f32_16x16x32_bf16 v[90:93], v[160:163], v[230:233], v[90:93]
	v_mfma_f32_16x16x32_bf16 v[90:93], v[164:167], v[234:237], v[90:93]
	v_mfma_f32_16x16x32_bf16 v[78:81], v[152:155], v[238:241], v[78:81]
	v_mfma_f32_16x16x32_bf16 v[78:81], v[156:159], v[242:245], v[78:81]
	v_mfma_f32_16x16x32_bf16 v[74:77], v[160:163], v[238:241], v[74:77]
	v_mfma_f32_16x16x32_bf16 v[74:77], v[164:167], v[242:245], v[74:77]
	s_setprio 0
	s_setprio 1
	v_mfma_f32_16x16x32_bf16 v[120:123], v[180:183], v[196:199], v[120:123]
	v_mfma_f32_16x16x32_bf16 v[120:123], v[184:187], v[200:203], v[120:123]
	v_mfma_f32_16x16x32_bf16 v[116:119], v[188:191], v[196:199], v[116:119]
	v_mfma_f32_16x16x32_bf16 v[116:119], v[192:195], v[200:203], v[116:119]
	v_mfma_f32_16x16x32_bf16 v[104:107], v[180:183], v[222:225], v[104:107]
	v_mfma_f32_16x16x32_bf16 v[104:107], v[184:187], v[226:229], v[104:107]
	v_mfma_f32_16x16x32_bf16 v[100:103], v[188:191], v[222:225], v[100:103]
	v_mfma_f32_16x16x32_bf16 v[100:103], v[192:195], v[226:229], v[100:103]
	v_mfma_f32_16x16x32_bf16 v[86:89], v[180:183], v[230:233], v[86:89]
	v_mfma_f32_16x16x32_bf16 v[86:89], v[184:187], v[234:237], v[86:89]
	v_mfma_f32_16x16x32_bf16 v[82:85], v[188:191], v[230:233], v[82:85]
	v_mfma_f32_16x16x32_bf16 v[82:85], v[192:195], v[234:237], v[82:85]
	v_mfma_f32_16x16x32_bf16 v[70:73], v[180:183], v[238:241], v[70:73]
	v_mfma_f32_16x16x32_bf16 v[70:73], v[184:187], v[242:245], v[70:73]
	s_setprio 2
	s_barrier
	v_mfma_f32_16x16x32_bf16 v[66:69], v[188:191], v[238:241], v[66:69]
	v_mfma_f32_16x16x32_bf16 v[66:69], v[192:195], v[242:245], v[66:69]
	s_setprio 0
	s_mov_b32 m0, s1
	v_lshl_add_u64 v[148:149], v[148:149], 0, s[76:77]
	ds_read_b128 v[196:199], v151 offset:49152
	ds_read_b128 v[200:203], v151 offset:50176
	ds_read_b128 v[222:225], v151 offset:51200
	ds_read_b128 v[226:229], v151 offset:52224
	ds_read_b128 v[230:233], v151 offset:53248
	ds_read_b128 v[234:237], v151 offset:54272
	ds_read_b128 v[238:241], v151 offset:55296
	ds_read_b128 v[242:245], v151 offset:56320
	global_load_lds_dwordx4 v[148:149], off
	v_lshl_add_u64 v[148:149], v[168:169], 0, s[76:77]
	s_mov_b32 m0, s0
	s_nop 0
	global_load_lds_dwordx4 v[148:149], off
	v_lshl_add_u64 v[148:149], s[54:55], 0, v[136:137]
	s_mov_b32 m0, s47
	s_nop 0
	global_load_lds_dwordx4 v[148:149], off
	v_lshl_add_u64 v[148:149], s[54:55], 0, v[132:133]
	s_mov_b32 m0, s46
	s_nop 0
	global_load_lds_dwordx4 v[148:149], off
	v_lshl_add_u64 v[148:149], v[172:173], 0, s[76:77]
	s_mov_b32 m0, s83
	s_nop 0
	global_load_lds_dwordx4 v[148:149], off
	v_lshl_add_u64 v[148:149], v[212:213], 0, s[76:77]
	s_mov_b32 m0, s88
	s_nop 0
	global_load_lds_dwordx4 v[148:149], off
	s_waitcnt vmcnt(8)
	s_waitcnt lgkmcnt(0)
	s_setprio 1
	s_barrier
	v_mfma_f32_16x16x32_bf16 v[62:65], v[152:155], v[196:199], v[62:65]
	v_mfma_f32_16x16x32_bf16 v[62:65], v[156:159], v[200:203], v[62:65]
	v_mfma_f32_16x16x32_bf16 v[58:61], v[160:163], v[196:199], v[58:61]
	v_mfma_f32_16x16x32_bf16 v[58:61], v[164:167], v[200:203], v[58:61]
	v_mfma_f32_16x16x32_bf16 v[46:49], v[152:155], v[222:225], v[46:49]
	v_mfma_f32_16x16x32_bf16 v[46:49], v[156:159], v[226:229], v[46:49]
	v_mfma_f32_16x16x32_bf16 v[42:45], v[160:163], v[222:225], v[42:45]
	v_mfma_f32_16x16x32_bf16 v[42:45], v[164:167], v[226:229], v[42:45]
	v_mfma_f32_16x16x32_bf16 v[30:33], v[152:155], v[230:233], v[30:33]
	v_mfma_f32_16x16x32_bf16 v[30:33], v[156:159], v[234:237], v[30:33]
	v_mfma_f32_16x16x32_bf16 v[26:29], v[160:163], v[230:233], v[26:29]
	v_mfma_f32_16x16x32_bf16 v[26:29], v[164:167], v[234:237], v[26:29]
	v_mfma_f32_16x16x32_bf16 v[14:17], v[152:155], v[238:241], v[14:17]
	v_mfma_f32_16x16x32_bf16 v[14:17], v[156:159], v[242:245], v[14:17]
	v_mfma_f32_16x16x32_bf16 v[10:13], v[160:163], v[238:241], v[10:13]
	v_mfma_f32_16x16x32_bf16 v[10:13], v[164:167], v[242:245], v[10:13]
	s_setprio 0
	s_setprio 1
	v_mfma_f32_16x16x32_bf16 v[54:57], v[180:183], v[196:199], v[54:57]
	v_mfma_f32_16x16x32_bf16 v[54:57], v[184:187], v[200:203], v[54:57]
	v_mfma_f32_16x16x32_bf16 v[50:53], v[188:191], v[196:199], v[50:53]
	v_mfma_f32_16x16x32_bf16 v[50:53], v[192:195], v[200:203], v[50:53]
	v_mfma_f32_16x16x32_bf16 v[38:41], v[180:183], v[222:225], v[38:41]
	v_mfma_f32_16x16x32_bf16 v[38:41], v[184:187], v[226:229], v[38:41]
	v_mfma_f32_16x16x32_bf16 v[34:37], v[188:191], v[222:225], v[34:37]
	v_mfma_f32_16x16x32_bf16 v[34:37], v[192:195], v[226:229], v[34:37]
	v_mfma_f32_16x16x32_bf16 v[22:25], v[180:183], v[230:233], v[22:25]
	v_mfma_f32_16x16x32_bf16 v[22:25], v[184:187], v[234:237], v[22:25]
	v_mfma_f32_16x16x32_bf16 v[18:21], v[188:191], v[230:233], v[18:21]
	v_mfma_f32_16x16x32_bf16 v[18:21], v[192:195], v[234:237], v[18:21]
	v_mfma_f32_16x16x32_bf16 v[6:9], v[180:183], v[238:241], v[6:9]
	v_mfma_f32_16x16x32_bf16 v[6:9], v[184:187], v[242:245], v[6:9]
	s_setprio 2
	s_barrier
	v_mfma_f32_16x16x32_bf16 v[2:5], v[188:191], v[238:241], v[2:5]
	v_mfma_f32_16x16x32_bf16 v[2:5], v[192:195], v[242:245], v[2:5]
	s_setprio 0
	v_lshl_add_u64 v[144:145], v[144:145], 0, s[86:87]
	v_lshl_add_u64 v[146:147], v[146:147], 0, s[86:87]
	s_mov_b32 s29, s81

; #define PG8_STAGE(bufoff, gbase, voff) do { _Pragma("unroll") for (int _i = 0; _i < 2; ++_i) \
;         __builtin_amdgcn_global_load_lds((const unsigned*)((const char*)(gbase) + (voff)[_i]), (PG8_LAS unsigned*)(lds + (bufoff) + ldsw + _i * 8192), 16, 0, AUX_A); } while (0)
; #define PG8_STAGEB(bufoff, gbase, voff) do { _Pragma("unroll") for (int _i = 0; _i < 2; ++_i) \
;         __builtin_amdgcn_global_load_lds((const unsigned*)((const char*)(gbase) + (voff)[_i]), (PG8_LAS unsigned*)(lds + (bufoff) + ldsw + _i * 8192), 16, 0, AUX_B); } while (0)
; #define PG8_WAIT_V(n) asm volatile("s_waitcnt vmcnt(" #n ")" ::: "memory")
; template <class Epi, class Sched, bool ALIGN_EPI = false, bool SP2 = false>
; __device__ __forceinline__ void gemm_phase(PG8_LAS unsigned char* lds, const Gemm g, const Sched& S, const Epi& E) {
;     ...
;         for (int t = 0; t < nt; t += 2) {
;             const bool last = (t == nt - 2);
;             const char* a1 = PG8_KP(cA, t + 1, rot, nt);
;             const char* a2 = last ? nAr : PG8_KP(cA, t + 2, rot, nt); const char* b2 = last ? nBr : PG8_KP(cB, t + 2, rot, nt);
;             const char* a3 = a2 + kstep; const char* b3 = b2 + kstep;
;             if (last && has_next) S.a_ready(nxt);
;             if constexpr (SP2) {
;             PG8_LDB(B0, 0, 0); PG8_LDB(B1, 0, 1); PG8_SCHED; PG8_LDA(At, 0, 0); PG8_STAGE(PG8_SA(1, 1), a1 + hstep, voffA);
;             PG8_WAIT_V(8); PG8_WAIT_L(0); PG8_BAR; PG8_MMA(0, 0, At, B0); PG8_MMA(0, 1, At, B1); PG8_BAR; PG8_SCHED;
;             PG8_LDA(At, 0, 1); PG8_STAGEB(PG8_SB(0, 0), b2, voffB); PG8_STAGEB(PG8_SB(0, 1), b2 + hstep, voffB); PG8_STAGE(PG8_SA(0, 0), a2, voffA);
;             PG8_WAIT_V(8); PG8_WAIT_L(0); PG8_BAR; PG8_MMA(1, 0, At, B0); PG8_MMA(1, 1, At, B1); PG8_BAR; PG8_SCHED;
;             PG8_LDB(B0, 1, 0); PG8_LDB(B1, 1, 1); PG8_SCHED; PG8_LDA(At, 1, 0); PG8_STAGE(PG8_SA(0, 1), a2 + hstep, voffA);
;             PG8_WAIT_V(8); PG8_WAIT_L(0); PG8_BAR; PG8_MMA(0, 0, At, B0); PG8_MMA(0, 1, At, B1); PG8_BAR; PG8_SCHED;
;             PG8_LDA(At, 1, 1); PG8_STAGEB(PG8_SB(1, 0), b3, voffB); PG8_STAGEB(PG8_SB(1, 1), b3 + hstep, voffB); PG8_STAGE(PG8_SA(1, 0), a3, voffA);
;             PG8_WAIT_V(8); PG8_WAIT_L(0); PG8_BAR; PG8_MMA(1, 0, At, B0); PG8_MMA(1, 1, At, B1); PG8_BAR; PG8_SCHED;
;     ...
;         if constexpr (ALIGN_EPI) { if (wr == 1) PG8_BAR; }
.Lpk_1157:
	s_add_i32 s81, s29, 2
	s_cmp_lt_u32 s29, 14
	s_cselect_b32 s0, 0, -16
	s_add_i32 s0, s81, s0
	s_ashr_i32 s1, s0, 31
	s_lshl_b64 s[0:1], s[0:1], 7
	s_add_u32 s2, s52, s0
	s_addc_u32 s46, s53, s1
	s_add_u32 s0, s50, s0
	s_addc_u32 s1, s51, s1
	s_cmp_eq_u32 s29, 14
	s_cselect_b32 s59, s19, s46
	s_cselect_b32 s58, s39, s2
	s_cselect_b32 s61, s92, s1
	s_cselect_b32 s60, s93, s0
	s_add_i32 s2, 0, 0x10000
	s_add_i32 s94, s2, s70
	s_add_i32 s46, 0, 0x14000
	s_add_i32 m0, s71, 0xc000
	s_add_i32 s84, s71, 0xe000
	s_add_i32 s95, s94, 0x2000
	s_add_u32 s62, s60, 0x40000
	s_addc_u32 s63, s61, 0
	s_add_i32 s96, s46, s70
	s_add_i32 s97, s96, 0x2000
	s_add_i32 vcc_lo, 0, 0x18000
	s_add_i32 vcc_hi, 0, 0x1c000
	s_add_u32 s56, s58, 0x40000
	s_addc_u32 s57, s59, 0
	s_add_i32 s1, vcc_lo, s70
	s_add_i32 s0, s1, 0x2000
	s_add_u32 s54, s60, 0x40080
	s_addc_u32 s55, s61, 0
	s_add_i32 s47, vcc_hi, s70
	s_add_i32 s46, s47, 0x2000
	global_load_lds_dwordx4 v[146:147], off
	s_mov_b32 m0, s84
	s_nop 0
	global_load_lds_dwordx4 v[144:145], off
	s_cmp_lg_u64 s[16:17], 0
	s_cbranch_scc1 .Lrp_1157
	s_barrier
.Lrp_1157:
	s_waitcnt vmcnt(8)
	s_waitcnt lgkmcnt(0)
	s_setprio 1
	s_barrier
	v_mfma_f32_16x16x32_bf16 v[128:131], v[148:151], v[196:199], 0
	v_mfma_f32_16x16x32_bf16 v[128:131], v[154:157], v[200:203], v[128:131]
	v_mfma_f32_16x16x32_bf16 v[124:127], v[158:161], v[196:199], 0
	v_mfma_f32_16x16x32_bf16 v[124:127], v[162:165], v[200:203], v[124:127]
	v_mfma_f32_16x16x32_bf16 v[112:115], v[148:151], v[222:225], 0
	v_mfma_f32_16x16x32_bf16 v[112:115], v[154:157], v[226:229], v[112:115]
	v_mfma_f32_16x16x32_bf16 v[108:111], v[158:161], v[222:225], 0
	v_mfma_f32_16x16x32_bf16 v[108:111], v[162:165], v[226:229], v[108:111]
	v_mfma_f32_16x16x32_bf16 v[94:97], v[148:151], v[230:233], 0
	v_mfma_f32_16x16x32_bf16 v[94:97], v[154:157], v[234:237], v[94:97]
	v_mfma_f32_16x16x32_bf16 v[90:93], v[158:161], v[230:233], 0
	v_mfma_f32_16x16x32_bf16 v[90:93], v[162:165], v[234:237], v[90:93]
	v_mfma_f32_16x16x32_bf16 v[78:81], v[148:151], v[238:241], 0
	v_mfma_f32_16x16x32_bf16 v[78:81], v[154:157], v[242:245], v[78:81]
	v_mfma_f32_16x16x32_bf16 v[74:77], v[158:161], v[238:241], 0
	v_mfma_f32_16x16x32_bf16 v[74:77], v[162:165], v[242:245], v[74:77]
	s_setprio 0
	s_setprio 1
	v_mfma_f32_16x16x32_bf16 v[120:123], v[180:183], v[196:199], 0
	v_mfma_f32_16x16x32_bf16 v[120:123], v[184:187], v[200:203], v[120:123]
	v_mfma_f32_16x16x32_bf16 v[116:119], v[188:191], v[196:199], 0
	v_mfma_f32_16x16x32_bf16 v[116:119], v[192:195], v[200:203], v[116:119]
	v_mfma_f32_16x16x32_bf16 v[104:107], v[180:183], v[222:225], 0
	v_mfma_f32_16x16x32_bf16 v[104:107], v[184:187], v[226:229], v[104:107]
	v_mfma_f32_16x16x32_bf16 v[100:103], v[188:191], v[222:225], 0
	v_mfma_f32_16x16x32_bf16 v[100:103], v[192:195], v[226:229], v[100:103]
	v_mfma_f32_16x16x32_bf16 v[86:89], v[180:183], v[230:233], 0
	v_mfma_f32_16x16x32_bf16 v[86:89], v[184:187], v[234:237], v[86:89]
	v_mfma_f32_16x16x32_bf16 v[82:85], v[188:191], v[230:233], 0
	v_mfma_f32_16x16x32_bf16 v[82:85], v[192:195], v[234:237], v[82:85]
	v_mfma_f32_16x16x32_bf16 v[70:73], v[180:183], v[238:241], 0
	v_mfma_f32_16x16x32_bf16 v[70:73], v[184:187], v[242:245], v[70:73]
	s_setprio 2
	s_barrier
	v_mfma_f32_16x16x32_bf16 v[66:69], v[188:191], v[238:241], 0
	v_mfma_f32_16x16x32_bf16 v[66:69], v[192:195], v[242:245], v[66:69]
	s_setprio 0
	s_mov_b32 m0, s94
	v_lshl_add_u64 v[166:167], s[60:61], 0, v[136:137]
	ds_read_b128 v[196:199], v153 offset:16384
	ds_read_b128 v[200:203], v153 offset:17408
	ds_read_b128 v[222:225], v153 offset:18432
	ds_read_b128 v[226:229], v153 offset:19456
	ds_read_b128 v[230:233], v153 offset:20480
	ds_read_b128 v[234:237], v153 offset:21504
	ds_read_b128 v[238:241], v153 offset:22528
	ds_read_b128 v[242:245], v153 offset:23552
	global_load_lds_dwordx4 v[166:167], off
	v_lshl_add_u64 v[168:169], s[60:61], 0, v[132:133]
	s_mov_b32 m0, s95
	v_lshl_add_u64 v[172:173], s[62:63], 0, v[136:137]
	global_load_lds_dwordx4 v[168:169], off
	s_mov_b32 m0, s96
	v_lshl_add_u64 v[212:213], s[58:59], 0, v[134:135]
	global_load_lds_dwordx4 v[172:173], off
	v_lshl_add_u64 v[172:173], s[62:63], 0, v[132:133]
	s_mov_b32 m0, s97
	s_nop 0
	global_load_lds_dwordx4 v[172:173], off
	v_lshl_add_u64 v[172:173], s[58:59], 0, v[138:139]
	s_mov_b32 m0, s71
	s_nop 0
	global_load_lds_dwordx4 v[172:173], off
	s_mov_b32 m0, s75
	s_nop 0
	global_load_lds_dwordx4 v[212:213], off
	s_waitcnt vmcnt(8)
	s_waitcnt lgkmcnt(0)
	s_setprio 1
	s_barrier
	v_mfma_f32_16x16x32_bf16 v[62:65], v[148:151], v[196:199], 0
	v_mfma_f32_16x16x32_bf16 v[62:65], v[154:157], v[200:203], v[62:65]
	v_mfma_f32_16x16x32_bf16 v[58:61], v[158:161], v[196:199], 0
	v_mfma_f32_16x16x32_bf16 v[58:61], v[162:165], v[200:203], v[58:61]
	v_mfma_f32_16x16x32_bf16 v[46:49], v[148:151], v[222:225], 0
	v_mfma_f32_16x16x32_bf16 v[46:49], v[154:157], v[226:229], v[46:49]
	v_mfma_f32_16x16x32_bf16 v[42:45], v[158:161], v[222:225], 0
	v_mfma_f32_16x16x32_bf16 v[42:45], v[162:165], v[226:229], v[42:45]
	v_mfma_f32_16x16x32_bf16 v[30:33], v[148:151], v[230:233], 0
	v_mfma_f32_16x16x32_bf16 v[30:33], v[154:157], v[234:237], v[30:33]
	v_mfma_f32_16x16x32_bf16 v[26:29], v[158:161], v[230:233], 0
	v_mfma_f32_16x16x32_bf16 v[26:29], v[162:165], v[234:237], v[26:29]
	v_mfma_f32_16x16x32_bf16 v[14:17], v[148:151], v[238:241], 0
	v_mfma_f32_16x16x32_bf16 v[14:17], v[154:157], v[242:245], v[14:17]
	v_mfma_f32_16x16x32_bf16 v[10:13], v[158:161], v[238:241], 0
	v_mfma_f32_16x16x32_bf16 v[10:13], v[162:165], v[242:245], v[10:13]
	s_setprio 0
	s_setprio 1
	v_mfma_f32_16x16x32_bf16 v[54:57], v[180:183], v[196:199], 0
	v_mfma_f32_16x16x32_bf16 v[54:57], v[184:187], v[200:203], v[54:57]
	v_mfma_f32_16x16x32_bf16 v[50:53], v[188:191], v[196:199], 0
	v_mfma_f32_16x16x32_bf16 v[50:53], v[192:195], v[200:203], v[50:53]
	v_mfma_f32_16x16x32_bf16 v[38:41], v[180:183], v[222:225], 0
	v_mfma_f32_16x16x32_bf16 v[38:41], v[184:187], v[226:229], v[38:41]
	v_mfma_f32_16x16x32_bf16 v[34:37], v[188:191], v[222:225], 0
	v_mfma_f32_16x16x32_bf16 v[34:37], v[192:195], v[226:229], v[34:37]
	v_mfma_f32_16x16x32_bf16 v[22:25], v[180:183], v[230:233], 0
	v_mfma_f32_16x16x32_bf16 v[22:25], v[184:187], v[234:237], v[22:25]
	v_mfma_f32_16x16x32_bf16 v[18:21], v[188:191], v[230:233], 0
	v_mfma_f32_16x16x32_bf16 v[18:21], v[192:195], v[234:237], v[18:21]
	v_mfma_f32_16x16x32_bf16 v[6:9], v[180:183], v[238:241], 0
	v_mfma_f32_16x16x32_bf16 v[6:9], v[184:187], v[242:245], v[6:9]
	s_setprio 2
	s_barrier
; #define PG8_STAGE(bufoff, gbase, voff) do { _Pragma("unroll") for (int _i = 0; _i < 2; ++_i) \
;         __builtin_amdgcn_global_load_lds((const unsigned*)((const char*)(gbase) + (voff)[_i]), (PG8_LAS unsigned*)(lds + (bufoff) + ldsw + _i * 8192), 16, 0, AUX_A); } while (0)
; #define PG8_STAGEB(bufoff, gbase, voff) do { _Pragma("unroll") for (int _i = 0; _i < 2; ++_i) \
;         __builtin_amdgcn_global_load_lds((const unsigned*)((const char*)(gbase) + (voff)[_i]), (PG8_LAS unsigned*)(lds + (bufoff) + ldsw + _i * 8192), 16, 0, AUX_B); } while (0)
; #define PG8_LDA(dst, b, h) do { _Pragma("unroll") for (int m = 0; m < 4; ++m) _Pragma("unroll") for (int k = 0; k < 2; ++k) dst[m][k] = *(const PG8_LAS bf16x8*)(lds + PG8_SA(b, h) + aoff + m * 2048 + k * 1024); } while (0)
; #define PG8_LDB(dst, b, h) do { _Pragma("unroll") for (int n = 0; n < 2; ++n) _Pragma("unroll") for (int k = 0; k < 2; ++k) dst[n][k] = *(const PG8_LAS bf16x8*)(lds + PG8_SB(b, h) + boff + n * 2048 + k * 1024); } while (0)
; #define PG8_WAIT_V(n) asm volatile("s_waitcnt vmcnt(" #n ")" ::: "memory")
; #define PG8_WAIT_L(n) asm volatile("s_waitcnt lgkmcnt(" #n ")" ::: "memory")
; template <class Epi, class Sched, bool ALIGN_EPI = false, bool SP2 = false>
; __device__ __forceinline__ void gemm_phase(PG8_LAS unsigned char* lds, const Gemm g, const Sched& S, const Epi& E) {
;     ...
;             PG8_LDB(B0, 0, 0); PG8_LDB(B1, 0, 1); PG8_SCHED; PG8_LDA(At, 0, 0); PG8_STAGE(PG8_SA(1, 1), a1 + hstep, voffA);
;             PG8_WAIT_V(8); PG8_WAIT_L(0); PG8_BAR; PG8_MMA(0, 0, At, B0); PG8_MMA(0, 1, At, B1); PG8_BAR; PG8_SCHED;
;             PG8_LDA(At, 0, 1); PG8_STAGEB(PG8_SB(0, 0), b2, voffB); PG8_STAGEB(PG8_SB(0, 1), b2 + hstep, voffB); PG8_STAGE(PG8_SA(0, 0), a2, voffA);
;             PG8_WAIT_V(8); PG8_WAIT_L(0); PG8_BAR; PG8_MMA(1, 0, At, B0); PG8_MMA(1, 1, At, B1); PG8_BAR; PG8_SCHED;
;             PG8_LDB(B0, 1, 0); PG8_LDB(B1, 1, 1); PG8_SCHED; PG8_LDA(At, 1, 0); PG8_STAGE(PG8_SA(0, 1), a2 + hstep, voffA);
;             PG8_WAIT_V(8); PG8_WAIT_L(0); PG8_BAR; PG8_MMA(0, 0, At, B0); PG8_MMA(0, 1, At, B1); PG8_BAR; PG8_SCHED;
;             PG8_LDA(At, 1, 1); PG8_STAGEB(PG8_SB(1, 0), b3, voffB); PG8_STAGEB(PG8_SB(1, 1), b3 + hstep, voffB); PG8_STAGE(PG8_SA(1, 0), a3, voffA);
;             PG8_WAIT_V(8); PG8_WAIT_L(0); PG8_BAR; PG8_MMA(1, 0, At, B0); PG8_MMA(1, 1, At, B1); PG8_BAR; PG8_SCHED;
	v_mfma_f32_16x16x32_bf16 v[2:5], v[188:191], v[238:241], 0
	v_mfma_f32_16x16x32_bf16 v[2:5], v[192:195], v[242:245], v[2:5]
	s_setprio 0
	v_add_u32_e32 v162, vcc_lo, v99
	v_add_u32_e32 v192, vcc_hi, v99
	ds_read_b128 v[148:151], v162
	ds_read_b128 v[154:157], v162 offset:1024
	ds_read_b128 v[158:161], v162 offset:2048
	ds_read_b128 v[162:165], v162 offset:3072
	ds_read_b128 v[180:183], v192
	ds_read_b128 v[184:187], v192 offset:1024
	ds_read_b128 v[188:191], v192 offset:2048
	ds_read_b128 v[192:195], v192 offset:3072
	s_mov_b32 m0, s78
	v_lshl_add_u64 v[246:247], s[56:57], 0, v[138:139]
	ds_read_b128 v[196:199], v153 offset:32768
	ds_read_b128 v[200:203], v153 offset:33792
	ds_read_b128 v[222:225], v153 offset:34816
	ds_read_b128 v[226:229], v153 offset:35840
	ds_read_b128 v[230:233], v153 offset:36864
	ds_read_b128 v[234:237], v153 offset:37888
	ds_read_b128 v[238:241], v153 offset:38912
	ds_read_b128 v[242:245], v153 offset:39936
	global_load_lds_dwordx4 v[246:247], off
	v_lshl_add_u64 v[246:247], s[56:57], 0, v[134:135]
	s_mov_b32 m0, s82
	s_nop 0
	global_load_lds_dwordx4 v[246:247], off
	s_waitcnt vmcnt(8)
	s_waitcnt lgkmcnt(0)
	s_setprio 1
	s_barrier
	v_mfma_f32_16x16x32_bf16 v[128:131], v[148:151], v[196:199], v[128:131]
	v_mfma_f32_16x16x32_bf16 v[128:131], v[154:157], v[200:203], v[128:131]
	v_mfma_f32_16x16x32_bf16 v[124:127], v[158:161], v[196:199], v[124:127]
	v_mfma_f32_16x16x32_bf16 v[124:127], v[162:165], v[200:203], v[124:127]
	v_mfma_f32_16x16x32_bf16 v[112:115], v[148:151], v[222:225], v[112:115]
	v_mfma_f32_16x16x32_bf16 v[112:115], v[154:157], v[226:229], v[112:115]
	v_mfma_f32_16x16x32_bf16 v[108:111], v[158:161], v[222:225], v[108:111]
	v_mfma_f32_16x16x32_bf16 v[108:111], v[162:165], v[226:229], v[108:111]
	v_mfma_f32_16x16x32_bf16 v[94:97], v[148:151], v[230:233], v[94:97]
	v_mfma_f32_16x16x32_bf16 v[94:97], v[154:157], v[234:237], v[94:97]
	v_mfma_f32_16x16x32_bf16 v[90:93], v[158:161], v[230:233], v[90:93]
	v_mfma_f32_16x16x32_bf16 v[90:93], v[162:165], v[234:237], v[90:93]
	v_mfma_f32_16x16x32_bf16 v[78:81], v[148:151], v[238:241], v[78:81]
	v_mfma_f32_16x16x32_bf16 v[78:81], v[154:157], v[242:245], v[78:81]
	v_mfma_f32_16x16x32_bf16 v[74:77], v[158:161], v[238:241], v[74:77]
	v_mfma_f32_16x16x32_bf16 v[74:77], v[162:165], v[242:245], v[74:77]
	s_setprio 0
	s_setprio 1
	v_mfma_f32_16x16x32_bf16 v[120:123], v[180:183], v[196:199], v[120:123]
	v_mfma_f32_16x16x32_bf16 v[120:123], v[184:187], v[200:203], v[120:123]
	v_mfma_f32_16x16x32_bf16 v[116:119], v[188:191], v[196:199], v[116:119]
	v_mfma_f32_16x16x32_bf16 v[116:119], v[192:195], v[200:203], v[116:119]
	v_mfma_f32_16x16x32_bf16 v[104:107], v[180:183], v[222:225], v[104:107]
	v_mfma_f32_16x16x32_bf16 v[104:107], v[184:187], v[226:229], v[104:107]
	v_mfma_f32_16x16x32_bf16 v[100:103], v[188:191], v[222:225], v[100:103]
	v_mfma_f32_16x16x32_bf16 v[100:103], v[192:195], v[226:229], v[100:103]
	v_mfma_f32_16x16x32_bf16 v[86:89], v[180:183], v[230:233], v[86:89]
	v_mfma_f32_16x16x32_bf16 v[86:89], v[184:187], v[234:237], v[86:89]
	v_mfma_f32_16x16x32_bf16 v[82:85], v[188:191], v[230:233], v[82:85]
	v_mfma_f32_16x16x32_bf16 v[82:85], v[192:195], v[234:237], v[82:85]
	v_mfma_f32_16x16x32_bf16 v[70:73], v[180:183], v[238:241], v[70:73]
	v_mfma_f32_16x16x32_bf16 v[70:73], v[184:187], v[242:245], v[70:73]
	s_setprio 2
	s_barrier
	v_mfma_f32_16x16x32_bf16 v[66:69], v[188:191], v[238:241], v[66:69]
	v_mfma_f32_16x16x32_bf16 v[66:69], v[192:195], v[242:245], v[66:69]
	s_setprio 0
	s_mov_b32 m0, s1
	v_lshl_add_u64 v[166:167], v[166:167], 0, s[76:77]
	ds_read_b128 v[196:199], v153 offset:49152
	ds_read_b128 v[200:203], v153 offset:50176
	ds_read_b128 v[222:225], v153 offset:51200
	ds_read_b128 v[226:229], v153 offset:52224
	ds_read_b128 v[230:233], v153 offset:53248
	ds_read_b128 v[234:237], v153 offset:54272
	ds_read_b128 v[238:241], v153 offset:55296
	ds_read_b128 v[242:245], v153 offset:56320
	global_load_lds_dwordx4 v[166:167], off
	v_lshl_add_u64 v[166:167], v[168:169], 0, s[76:77]
	s_mov_b32 m0, s0
	s_nop 0
	global_load_lds_dwordx4 v[166:167], off
	v_lshl_add_u64 v[166:167], s[54:55], 0, v[136:137]
	s_mov_b32 m0, s47
	s_nop 0
	global_load_lds_dwordx4 v[166:167], off
	v_lshl_add_u64 v[166:167], s[54:55], 0, v[132:133]
	s_mov_b32 m0, s46
	s_nop 0
	global_load_lds_dwordx4 v[166:167], off
	v_lshl_add_u64 v[166:167], v[172:173], 0, s[76:77]
	s_mov_b32 m0, s83
	s_nop 0
	global_load_lds_dwordx4 v[166:167], off
	v_lshl_add_u64 v[166:167], v[212:213], 0, s[76:77]
	s_mov_b32 m0, s88
	s_nop 0
	global_load_lds_dwordx4 v[166:167], off
	s_waitcnt vmcnt(8)
	s_waitcnt lgkmcnt(0)
	s_setprio 1
	s_barrier
	v_mfma_f32_16x16x32_bf16 v[62:65], v[148:151], v[196:199], v[62:65]
	v_mfma_f32_16x16x32_bf16 v[62:65], v[154:157], v[200:203], v[62:65]
	v_mfma_f32_16x16x32_bf16 v[58:61], v[158:161], v[196:199], v[58:61]
	v_mfma_f32_16x16x32_bf16 v[58:61], v[162:165], v[200:203], v[58:61]
	v_mfma_f32_16x16x32_bf16 v[46:49], v[148:151], v[222:225], v[46:49]
	v_mfma_f32_16x16x32_bf16 v[46:49], v[154:157], v[226:229], v[46:49]
	v_mfma_f32_16x16x32_bf16 v[42:45], v[158:161], v[222:225], v[42:45]
	v_mfma_f32_16x16x32_bf16 v[42:45], v[162:165], v[226:229], v[42:45]
	v_mfma_f32_16x16x32_bf16 v[30:33], v[148:151], v[230:233], v[30:33]
	v_mfma_f32_16x16x32_bf16 v[30:33], v[154:157], v[234:237], v[30:33]
	v_mfma_f32_16x16x32_bf16 v[26:29], v[158:161], v[230:233], v[26:29]
	v_mfma_f32_16x16x32_bf16 v[26:29], v[162:165], v[234:237], v[26:29]
	v_mfma_f32_16x16x32_bf16 v[14:17], v[148:151], v[238:241], v[14:17]
	v_mfma_f32_16x16x32_bf16 v[14:17], v[154:157], v[242:245], v[14:17]
	v_mfma_f32_16x16x32_bf16 v[10:13], v[158:161], v[238:241], v[10:13]
	v_mfma_f32_16x16x32_bf16 v[10:13], v[162:165], v[242:245], v[10:13]
	s_setprio 0
	s_setprio 1
	v_mfma_f32_16x16x32_bf16 v[54:57], v[180:183], v[196:199], v[54:57]
	v_mfma_f32_16x16x32_bf16 v[54:57], v[184:187], v[200:203], v[54:57]
	v_mfma_f32_16x16x32_bf16 v[50:53], v[188:191], v[196:199], v[50:53]
	v_mfma_f32_16x16x32_bf16 v[50:53], v[192:195], v[200:203], v[50:53]
	v_mfma_f32_16x16x32_bf16 v[38:41], v[180:183], v[222:225], v[38:41]
	v_mfma_f32_16x16x32_bf16 v[38:41], v[184:187], v[226:229], v[38:41]
	v_mfma_f32_16x16x32_bf16 v[34:37], v[188:191], v[222:225], v[34:37]
	v_mfma_f32_16x16x32_bf16 v[34:37], v[192:195], v[226:229], v[34:37]
	v_mfma_f32_16x16x32_bf16 v[22:25], v[180:183], v[230:233], v[22:25]
	v_mfma_f32_16x16x32_bf16 v[22:25], v[184:187], v[234:237], v[22:25]
	v_mfma_f32_16x16x32_bf16 v[18:21], v[188:191], v[230:233], v[18:21]
	v_mfma_f32_16x16x32_bf16 v[18:21], v[192:195], v[234:237], v[18:21]
	v_mfma_f32_16x16x32_bf16 v[6:9], v[180:183], v[238:241], v[6:9]
	v_mfma_f32_16x16x32_bf16 v[6:9], v[184:187], v[242:245], v[6:9]
	s_setprio 2
	s_barrier
	v_mfma_f32_16x16x32_bf16 v[2:5], v[188:191], v[238:241], v[2:5]
	v_mfma_f32_16x16x32_bf16 v[2:5], v[192:195], v[242:245], v[2:5]
	s_setprio 0
	v_lshl_add_u64 v[144:145], v[144:145], 0, s[86:87]
	v_lshl_add_u64 v[146:147], v[146:147], 0, s[86:87]
	s_mov_b32 s29, s81

; #define PG8_STAGE(bufoff, gbase, voff) do { _Pragma("unroll") for (int _i = 0; _i < 2; ++_i) \
;         __builtin_amdgcn_global_load_lds((const unsigned*)((const char*)(gbase) + (voff)[_i]), (PG8_LAS unsigned*)(lds + (bufoff) + ldsw + _i * 8192), 16, 0, AUX_A); } while (0)
; #define PG8_STAGEB(bufoff, gbase, voff) do { _Pragma("unroll") for (int _i = 0; _i < 2; ++_i) \
;         __builtin_amdgcn_global_load_lds((const unsigned*)((const char*)(gbase) + (voff)[_i]), (PG8_LAS unsigned*)(lds + (bufoff) + ldsw + _i * 8192), 16, 0, AUX_B); } while (0)
; #define PG8_WAIT_V(n) asm volatile("s_waitcnt vmcnt(" #n ")" ::: "memory")
; template <class Epi, class Sched, bool ALIGN_EPI = false, bool SP2 = false>
; __device__ __forceinline__ void gemm_phase(PG8_LAS unsigned char* lds, const Gemm g, const Sched& S, const Epi& E) {
;     ...
;         for (int t = 0; t < nt; t += 2) {
;             const bool last = (t == nt - 2);
;             const char* a1 = PG8_KP(cA, t + 1, rot, nt);
;             const char* a2 = last ? nAr : PG8_KP(cA, t + 2, rot, nt); const char* b2 = last ? nBr : PG8_KP(cB, t + 2, rot, nt);
;             const char* a3 = a2 + kstep; const char* b3 = b2 + kstep;
;             if (last && has_next) S.a_ready(nxt);
;             if constexpr (SP2) {
;             PG8_LDB(B0, 0, 0); PG8_LDB(B1, 0, 1); PG8_SCHED; PG8_LDA(At, 0, 0); PG8_STAGE(PG8_SA(1, 1), a1 + hstep, voffA);
;             PG8_WAIT_V(8); PG8_WAIT_L(0); PG8_BAR; PG8_MMA(0, 0, At, B0); PG8_MMA(0, 1, At, B1); PG8_BAR; PG8_SCHED;
;             PG8_LDA(At, 0, 1); PG8_STAGEB(PG8_SB(0, 0), b2, voffB); PG8_STAGEB(PG8_SB(0, 1), b2 + hstep, voffB); PG8_STAGE(PG8_SA(0, 0), a2, voffA);
;             PG8_WAIT_V(8); PG8_WAIT_L(0); PG8_BAR; PG8_MMA(1, 0, At, B0); PG8_MMA(1, 1, At, B1); PG8_BAR; PG8_SCHED;
;             PG8_LDB(B0, 1, 0); PG8_LDB(B1, 1, 1); PG8_SCHED; PG8_LDA(At, 1, 0); PG8_STAGE(PG8_SA(0, 1), a2 + hstep, voffA);
;             PG8_WAIT_V(8); PG8_WAIT_L(0); PG8_BAR; PG8_MMA(0, 0, At, B0); PG8_MMA(0, 1, At, B1); PG8_BAR; PG8_SCHED;
;             PG8_LDA(At, 1, 1); PG8_STAGEB(PG8_SB(1, 0), b3, voffB); PG8_STAGEB(PG8_SB(1, 1), b3 + hstep, voffB); PG8_STAGE(PG8_SA(1, 0), a3, voffA);
;             PG8_WAIT_V(8); PG8_WAIT_L(0); PG8_BAR; PG8_MMA(1, 0, At, B0); PG8_MMA(1, 1, At, B1); PG8_BAR; PG8_SCHED;
;     ...
;         if constexpr (ALIGN_EPI) { if (wr == 1) PG8_BAR; }
.Lpk_1308:
	s_or_b32 s0, s11, 1
	s_cmp_ge_i32 s0, s71
	s_cselect_b32 s2, s71, 0
	s_add_i32 s11, s11, 2
	s_cmp_ge_i32 s11, s71
	s_cselect_b32 s0, s71, 0
	s_sub_i32 s0, s13, s0
	s_ashr_i32 s1, s0, 31
	s_lshl_b64 s[0:1], s[0:1], 7
	s_add_u32 s15, s40, s0
	s_addc_u32 s29, s41, s1
	s_add_u32 s0, s34, s0
	s_addc_u32 s1, s35, s1
	s_cmp_eq_u32 s71, s13
	s_cselect_b32 s45, s43, s29
	s_cselect_b32 s44, s42, s15
	s_cselect_b32 s37, s19, s1
	s_cselect_b32 s36, s18, s0
	s_add_i32 s15, 0, 0x10000
	s_add_i32 s29, 0, 0x14000
	v_mad_i64_i32 v[168:169], s[0:1], s2, v220, v[134:135]
	s_add_i32 m0, s50, 0xc000
	global_load_lds_dwordx4 v[168:169], off
	v_mad_i64_i32 v[168:169], s[0:1], s2, v220, v[132:133]
	s_add_i32 m0, s50, 0xe000
	s_nop 0
	global_load_lds_dwordx4 v[168:169], off
	s_cmp_lg_u64 s[8:9], 0
	s_cbranch_scc1 .Lrp_1308
	s_barrier
.Lrp_1308:
	s_waitcnt vmcnt(8)
	s_waitcnt lgkmcnt(0)
	s_setprio 1
	s_barrier
	v_mfma_f32_16x16x32_bf16 v[128:131], v[136:139], v[194:197], 0
	v_mfma_f32_16x16x32_bf16 v[128:131], v[140:143], v[198:201], v[128:131]
	v_mfma_f32_16x16x32_bf16 v[124:127], v[144:147], v[194:197], 0
	v_mfma_f32_16x16x32_bf16 v[124:127], v[148:151], v[198:201], v[124:127]
	v_mfma_f32_16x16x32_bf16 v[120:123], v[136:139], v[222:225], 0
	v_mfma_f32_16x16x32_bf16 v[120:123], v[140:143], v[226:229], v[120:123]
	v_mfma_f32_16x16x32_bf16 v[112:115], v[144:147], v[222:225], 0
	v_mfma_f32_16x16x32_bf16 v[112:115], v[148:151], v[226:229], v[112:115]
	v_mfma_f32_16x16x32_bf16 v[104:107], v[136:139], v[230:233], 0
	v_mfma_f32_16x16x32_bf16 v[104:107], v[140:143], v[234:237], v[104:107]
	v_mfma_f32_16x16x32_bf16 v[94:97], v[144:147], v[230:233], 0
	v_mfma_f32_16x16x32_bf16 v[94:97], v[148:151], v[234:237], v[94:97]
	v_mfma_f32_16x16x32_bf16 v[86:89], v[136:139], v[238:241], 0
	v_mfma_f32_16x16x32_bf16 v[86:89], v[140:143], v[242:245], v[86:89]
	v_mfma_f32_16x16x32_bf16 v[78:81], v[144:147], v[238:241], 0
	v_mfma_f32_16x16x32_bf16 v[78:81], v[148:151], v[242:245], v[78:81]
	s_setprio 0
	s_setprio 1
	v_mfma_f32_16x16x32_bf16 v[116:119], v[164:167], v[194:197], 0
	v_mfma_f32_16x16x32_bf16 v[116:119], v[182:185], v[198:201], v[116:119]
	v_mfma_f32_16x16x32_bf16 v[108:111], v[186:189], v[194:197], 0
	v_mfma_f32_16x16x32_bf16 v[108:111], v[190:193], v[198:201], v[108:111]
	v_mfma_f32_16x16x32_bf16 v[100:103], v[164:167], v[222:225], 0
	v_mfma_f32_16x16x32_bf16 v[100:103], v[182:185], v[226:229], v[100:103]
	v_mfma_f32_16x16x32_bf16 v[90:93], v[186:189], v[222:225], 0
	v_mfma_f32_16x16x32_bf16 v[90:93], v[190:193], v[226:229], v[90:93]
	v_mfma_f32_16x16x32_bf16 v[82:85], v[164:167], v[230:233], 0
	v_mfma_f32_16x16x32_bf16 v[82:85], v[182:185], v[234:237], v[82:85]
	v_mfma_f32_16x16x32_bf16 v[74:77], v[186:189], v[230:233], 0
	v_mfma_f32_16x16x32_bf16 v[74:77], v[190:193], v[234:237], v[74:77]
	v_mfma_f32_16x16x32_bf16 v[70:73], v[164:167], v[238:241], 0
	v_mfma_f32_16x16x32_bf16 v[70:73], v[182:185], v[242:245], v[70:73]
	s_setprio 2
	s_barrier
	v_mfma_f32_16x16x32_bf16 v[66:69], v[186:189], v[238:241], 0
	v_mfma_f32_16x16x32_bf16 v[66:69], v[190:193], v[242:245], v[66:69]
	s_setprio 0
	s_add_i32 s0, s15, s49
	v_lshl_add_u64 v[168:169], s[36:37], 0, v[156:157]
	s_mov_b32 m0, s0
	ds_read_b128 v[194:197], v181 offset:16384
	ds_read_b128 v[198:201], v181 offset:17408
	ds_read_b128 v[222:225], v181 offset:18432
	ds_read_b128 v[226:229], v181 offset:19456
	ds_read_b128 v[230:233], v181 offset:20480
	ds_read_b128 v[234:237], v181 offset:21504
	ds_read_b128 v[238:241], v181 offset:22528
	ds_read_b128 v[242:245], v181 offset:23552
	global_load_lds_dwordx4 v[168:169], off
	s_add_i32 m0, s0, 0x2000
	s_add_u32 s0, s36, 0x80000
	v_lshl_add_u64 v[172:173], s[36:37], 0, v[152:153]
	s_addc_u32 s1, s37, 0
	s_add_i32 s2, s29, s49
	global_load_lds_dwordx4 v[172:173], off
	v_lshl_add_u64 v[202:203], s[0:1], 0, v[156:157]
	s_mov_b32 m0, s2
	v_lshl_add_u64 v[212:213], s[44:45], 0, v[154:155]
	global_load_lds_dwordx4 v[202:203], off
	v_lshl_add_u64 v[202:203], s[0:1], 0, v[152:153]
	s_add_i32 m0, s2, 0x2000
	s_nop 0
	global_load_lds_dwordx4 v[202:203], off
	v_lshl_add_u64 v[202:203], s[44:45], 0, v[158:159]
	s_mov_b32 m0, s50
	s_nop 0
	global_load_lds_dwordx4 v[202:203], off
	s_mov_b32 m0, s51
	s_nop 0
	global_load_lds_dwordx4 v[212:213], off
	s_waitcnt vmcnt(8)
	s_waitcnt lgkmcnt(0)
	s_setprio 1
	s_barrier
	v_mfma_f32_16x16x32_bf16 v[62:65], v[136:139], v[194:197], 0
	v_mfma_f32_16x16x32_bf16 v[62:65], v[140:143], v[198:201], v[62:65]
	v_mfma_f32_16x16x32_bf16 v[58:61], v[144:147], v[194:197], 0
	v_mfma_f32_16x16x32_bf16 v[58:61], v[148:151], v[198:201], v[58:61]
	v_mfma_f32_16x16x32_bf16 v[54:57], v[136:139], v[222:225], 0
	v_mfma_f32_16x16x32_bf16 v[54:57], v[140:143], v[226:229], v[54:57]
	v_mfma_f32_16x16x32_bf16 v[46:49], v[144:147], v[222:225], 0
	v_mfma_f32_16x16x32_bf16 v[46:49], v[148:151], v[226:229], v[46:49]
	v_mfma_f32_16x16x32_bf16 v[38:41], v[136:139], v[230:233], 0
	v_mfma_f32_16x16x32_bf16 v[38:41], v[140:143], v[234:237], v[38:41]
	v_mfma_f32_16x16x32_bf16 v[30:33], v[144:147], v[230:233], 0
	v_mfma_f32_16x16x32_bf16 v[30:33], v[148:151], v[234:237], v[30:33]
	v_mfma_f32_16x16x32_bf16 v[22:25], v[136:139], v[238:241], 0
	v_mfma_f32_16x16x32_bf16 v[22:25], v[140:143], v[242:245], v[22:25]
	v_mfma_f32_16x16x32_bf16 v[14:17], v[144:147], v[238:241], 0
	v_mfma_f32_16x16x32_bf16 v[14:17], v[148:151], v[242:245], v[14:17]
	s_setprio 0
	s_setprio 1
	v_mfma_f32_16x16x32_bf16 v[50:53], v[164:167], v[194:197], 0
	v_mfma_f32_16x16x32_bf16 v[50:53], v[182:185], v[198:201], v[50:53]
	v_mfma_f32_16x16x32_bf16 v[42:45], v[186:189], v[194:197], 0
	v_mfma_f32_16x16x32_bf16 v[42:45], v[190:193], v[198:201], v[42:45]
	v_mfma_f32_16x16x32_bf16 v[34:37], v[164:167], v[222:225], 0
	v_mfma_f32_16x16x32_bf16 v[34:37], v[182:185], v[226:229], v[34:37]
	v_mfma_f32_16x16x32_bf16 v[26:29], v[186:189], v[222:225], 0
	v_mfma_f32_16x16x32_bf16 v[26:29], v[190:193], v[226:229], v[26:29]
	v_mfma_f32_16x16x32_bf16 v[18:21], v[164:167], v[230:233], 0
	v_mfma_f32_16x16x32_bf16 v[18:21], v[182:185], v[234:237], v[18:21]
	v_mfma_f32_16x16x32_bf16 v[10:13], v[186:189], v[230:233], 0
	v_mfma_f32_16x16x32_bf16 v[10:13], v[190:193], v[234:237], v[10:13]
	v_mfma_f32_16x16x32_bf16 v[6:9], v[164:167], v[238:241], 0
	v_mfma_f32_16x16x32_bf16 v[6:9], v[182:185], v[242:245], v[6:9]
	s_setprio 2
	s_barrier
; #define PG8_STAGE(bufoff, gbase, voff) do { _Pragma("unroll") for (int _i = 0; _i < 2; ++_i) \
;         __builtin_amdgcn_global_load_lds((const unsigned*)((const char*)(gbase) + (voff)[_i]), (PG8_LAS unsigned*)(lds + (bufoff) + ldsw + _i * 8192), 16, 0, AUX_A); } while (0)
; #define PG8_STAGEB(bufoff, gbase, voff) do { _Pragma("unroll") for (int _i = 0; _i < 2; ++_i) \
;         __builtin_amdgcn_global_load_lds((const unsigned*)((const char*)(gbase) + (voff)[_i]), (PG8_LAS unsigned*)(lds + (bufoff) + ldsw + _i * 8192), 16, 0, AUX_B); } while (0)
; #define PG8_LDA(dst, b, h) do { _Pragma("unroll") for (int m = 0; m < 4; ++m) _Pragma("unroll") for (int k = 0; k < 2; ++k) dst[m][k] = *(const PG8_LAS bf16x8*)(lds + PG8_SA(b, h) + aoff + m * 2048 + k * 1024); } while (0)
; #define PG8_LDB(dst, b, h) do { _Pragma("unroll") for (int n = 0; n < 2; ++n) _Pragma("unroll") for (int k = 0; k < 2; ++k) dst[n][k] = *(const PG8_LAS bf16x8*)(lds + PG8_SB(b, h) + boff + n * 2048 + k * 1024); } while (0)
; #define PG8_MMA(ai, bj, At, Bt) do { __builtin_amdgcn_s_setprio(1); _Pragma("unroll") for (int m = 0; m < 4; ++m) _Pragma("unroll") for (int n = 0; n < 2; ++n) _Pragma("unroll") for (int k = 0; k < 2; ++k) \
;         acc[ai][bj][m][n] = __builtin_amdgcn_mfma_f32_16x16x32_bf16(Bt[n][k], At[m][k], acc[ai][bj][m][n], 0, 0, 0); __builtin_amdgcn_s_setprio(0); } while (0)
; #define PG8_WAIT_V(n) asm volatile("s_waitcnt vmcnt(" #n ")" ::: "memory")
; #define PG8_WAIT_L(n) asm volatile("s_waitcnt lgkmcnt(" #n ")" ::: "memory")
; #define PG8_BAR __builtin_amdgcn_s_barrier()
; #define PG8_SCHED __builtin_amdgcn_sched_barrier(0)
; template <class Epi, class Sched, bool ALIGN_EPI = false, bool SP2 = false>
; __device__ __forceinline__ void gemm_phase(PG8_LAS unsigned char* lds, const Gemm g, const Sched& S, const Epi& E) {
;     ...
;             PG8_LDA(At, 0, 1); PG8_STAGEB(PG8_SB(0, 0), b2, voffB); PG8_STAGEB(PG8_SB(0, 1), b2 + hstep, voffB); PG8_STAGE(PG8_SA(0, 0), a2, voffA);
;             PG8_WAIT_V(8); PG8_WAIT_L(0); PG8_BAR; PG8_MMA(1, 0, At, B0); PG8_MMA(1, 1, At, B1); PG8_BAR; PG8_SCHED;
;             PG8_LDB(B0, 1, 0); PG8_LDB(B1, 1, 1); PG8_SCHED; PG8_LDA(At, 1, 0); PG8_STAGE(PG8_SA(0, 1), a2 + hstep, voffA);
;             PG8_WAIT_V(8); PG8_WAIT_L(0); PG8_BAR; PG8_MMA(0, 0, At, B0); PG8_MMA(0, 1, At, B1); PG8_BAR; PG8_SCHED;
	v_mfma_f32_16x16x32_bf16 v[2:5], v[186:189], v[238:241], 0
	v_mfma_f32_16x16x32_bf16 v[2:5], v[190:193], v[242:245], v[2:5]
	s_setprio 0
	s_add_i32 s2, 0, 0x18000
	s_add_i32 s15, 0, 0x1c000
	v_add_u32_e32 v148, s2, v99
	v_add_u32_e32 v190, s15, v99
	ds_read_b128 v[136:139], v148
	ds_read_b128 v[140:143], v148 offset:1024
	ds_read_b128 v[144:147], v148 offset:2048
	ds_read_b128 v[148:151], v148 offset:3072
	ds_read_b128 v[164:167], v190
	ds_read_b128 v[182:185], v190 offset:1024
	ds_read_b128 v[186:189], v190 offset:2048
	ds_read_b128 v[190:193], v190 offset:3072
	s_add_u32 s0, s44, 0x80000
	s_addc_u32 s1, s45, 0
	s_mov_b32 m0, s52
	v_lshl_add_u64 v[246:247], s[0:1], 0, v[158:159]
	ds_read_b128 v[194:197], v181 offset:32768
	ds_read_b128 v[198:201], v181 offset:33792
	ds_read_b128 v[222:225], v181 offset:34816
	ds_read_b128 v[226:229], v181 offset:35840
	ds_read_b128 v[230:233], v181 offset:36864
	ds_read_b128 v[234:237], v181 offset:37888
	ds_read_b128 v[238:241], v181 offset:38912
	ds_read_b128 v[242:245], v181 offset:39936
	global_load_lds_dwordx4 v[246:247], off
	v_lshl_add_u64 v[246:247], s[0:1], 0, v[154:155]
	s_mov_b32 m0, s53
	s_nop 0
	global_load_lds_dwordx4 v[246:247], off
	s_waitcnt vmcnt(8)
	s_waitcnt lgkmcnt(0)
	s_setprio 1
	s_barrier
	v_mfma_f32_16x16x32_bf16 v[128:131], v[136:139], v[194:197], v[128:131]
	v_mfma_f32_16x16x32_bf16 v[128:131], v[140:143], v[198:201], v[128:131]
	v_mfma_f32_16x16x32_bf16 v[124:127], v[144:147], v[194:197], v[124:127]
	v_mfma_f32_16x16x32_bf16 v[124:127], v[148:151], v[198:201], v[124:127]
	v_mfma_f32_16x16x32_bf16 v[120:123], v[136:139], v[222:225], v[120:123]
	v_mfma_f32_16x16x32_bf16 v[120:123], v[140:143], v[226:229], v[120:123]
	v_mfma_f32_16x16x32_bf16 v[112:115], v[144:147], v[222:225], v[112:115]
	v_mfma_f32_16x16x32_bf16 v[112:115], v[148:151], v[226:229], v[112:115]
	v_mfma_f32_16x16x32_bf16 v[104:107], v[136:139], v[230:233], v[104:107]
	v_mfma_f32_16x16x32_bf16 v[104:107], v[140:143], v[234:237], v[104:107]
	v_mfma_f32_16x16x32_bf16 v[94:97], v[144:147], v[230:233], v[94:97]
	v_mfma_f32_16x16x32_bf16 v[94:97], v[148:151], v[234:237], v[94:97]
	v_mfma_f32_16x16x32_bf16 v[86:89], v[136:139], v[238:241], v[86:89]
	v_mfma_f32_16x16x32_bf16 v[86:89], v[140:143], v[242:245], v[86:89]
	v_mfma_f32_16x16x32_bf16 v[78:81], v[144:147], v[238:241], v[78:81]
	v_mfma_f32_16x16x32_bf16 v[78:81], v[148:151], v[242:245], v[78:81]
	s_setprio 0
	s_setprio 1
	v_mfma_f32_16x16x32_bf16 v[116:119], v[164:167], v[194:197], v[116:119]
	v_mfma_f32_16x16x32_bf16 v[116:119], v[182:185], v[198:201], v[116:119]
	v_mfma_f32_16x16x32_bf16 v[108:111], v[186:189], v[194:197], v[108:111]
	v_mfma_f32_16x16x32_bf16 v[108:111], v[190:193], v[198:201], v[108:111]
	v_mfma_f32_16x16x32_bf16 v[100:103], v[164:167], v[222:225], v[100:103]
	v_mfma_f32_16x16x32_bf16 v[100:103], v[182:185], v[226:229], v[100:103]
	v_mfma_f32_16x16x32_bf16 v[90:93], v[186:189], v[222:225], v[90:93]
	v_mfma_f32_16x16x32_bf16 v[90:93], v[190:193], v[226:229], v[90:93]
	v_mfma_f32_16x16x32_bf16 v[82:85], v[164:167], v[230:233], v[82:85]
	v_mfma_f32_16x16x32_bf16 v[82:85], v[182:185], v[234:237], v[82:85]
	v_mfma_f32_16x16x32_bf16 v[74:77], v[186:189], v[230:233], v[74:77]
	v_mfma_f32_16x16x32_bf16 v[74:77], v[190:193], v[234:237], v[74:77]
	v_mfma_f32_16x16x32_bf16 v[70:73], v[164:167], v[238:241], v[70:73]
	v_mfma_f32_16x16x32_bf16 v[70:73], v[182:185], v[242:245], v[70:73]
	s_setprio 2
	s_barrier
; #define PG8_STAGE(bufoff, gbase, voff) do { _Pragma("unroll") for (int _i = 0; _i < 2; ++_i) \
;         __builtin_amdgcn_global_load_lds((const unsigned*)((const char*)(gbase) + (voff)[_i]), (PG8_LAS unsigned*)(lds + (bufoff) + ldsw + _i * 8192), 16, 0, AUX_A); } while (0)
; #define PG8_STAGEB(bufoff, gbase, voff) do { _Pragma("unroll") for (int _i = 0; _i < 2; ++_i) \
;         __builtin_amdgcn_global_load_lds((const unsigned*)((const char*)(gbase) + (voff)[_i]), (PG8_LAS unsigned*)(lds + (bufoff) + ldsw + _i * 8192), 16, 0, AUX_B); } while (0)
; #define PG8_LDA(dst, b, h) do { _Pragma("unroll") for (int m = 0; m < 4; ++m) _Pragma("unroll") for (int k = 0; k < 2; ++k) dst[m][k] = *(const PG8_LAS bf16x8*)(lds + PG8_SA(b, h) + aoff + m * 2048 + k * 1024); } while (0)
; #define PG8_MMA(ai, bj, At, Bt) do { __builtin_amdgcn_s_setprio(1); _Pragma("unroll") for (int m = 0; m < 4; ++m) _Pragma("unroll") for (int n = 0; n < 2; ++n) _Pragma("unroll") for (int k = 0; k < 2; ++k) \
;         acc[ai][bj][m][n] = __builtin_amdgcn_mfma_f32_16x16x32_bf16(Bt[n][k], At[m][k], acc[ai][bj][m][n], 0, 0, 0); __builtin_amdgcn_s_setprio(0); } while (0)
; #define PG8_WAIT_V(n) asm volatile("s_waitcnt vmcnt(" #n ")" ::: "memory")
; #define PG8_WAIT_L(n) asm volatile("s_waitcnt lgkmcnt(" #n ")" ::: "memory")
; #define PG8_BAR __builtin_amdgcn_s_barrier()
; #define PG8_SCHED __builtin_amdgcn_sched_barrier(0)
; template <class Epi, class Sched, bool ALIGN_EPI = false, bool SP2 = false>
; __device__ __forceinline__ void gemm_phase(PG8_LAS unsigned char* lds, const Gemm g, const Sched& S, const Epi& E) {
;     ...
;         for (int t = 0; t < nt; t += 2) {
;     ...
;             PG8_LDA(At, 1, 1); PG8_STAGEB(PG8_SB(1, 0), b3, voffB); PG8_STAGEB(PG8_SB(1, 1), b3 + hstep, voffB); PG8_STAGE(PG8_SA(1, 0), a3, voffA);
;             PG8_WAIT_V(8); PG8_WAIT_L(0); PG8_BAR; PG8_MMA(1, 0, At, B0); PG8_MMA(1, 1, At, B1); PG8_BAR; PG8_SCHED;
	v_mfma_f32_16x16x32_bf16 v[66:69], v[186:189], v[238:241], v[66:69]
	v_mfma_f32_16x16x32_bf16 v[66:69], v[190:193], v[242:245], v[66:69]
	s_setprio 0
	s_add_i32 s0, s2, s49
	v_lshl_add_u64 v[168:169], v[168:169], 0, s[76:77]
	s_mov_b32 m0, s0
	ds_read_b128 v[194:197], v181 offset:49152
	ds_read_b128 v[198:201], v181 offset:50176
	ds_read_b128 v[222:225], v181 offset:51200
	ds_read_b128 v[226:229], v181 offset:52224
	ds_read_b128 v[230:233], v181 offset:53248
	ds_read_b128 v[234:237], v181 offset:54272
	ds_read_b128 v[238:241], v181 offset:55296
	ds_read_b128 v[242:245], v181 offset:56320
	global_load_lds_dwordx4 v[168:169], off
	s_add_i32 m0, s0, 0x2000
	s_add_u32 s0, s36, 0x80080
	v_lshl_add_u64 v[168:169], v[172:173], 0, s[76:77]
	s_addc_u32 s1, s37, 0
	s_add_i32 s2, s15, s49
	global_load_lds_dwordx4 v[168:169], off
	v_lshl_add_u64 v[168:169], s[0:1], 0, v[156:157]
	s_mov_b32 m0, s2
	s_nop 0
	global_load_lds_dwordx4 v[168:169], off
	v_lshl_add_u64 v[168:169], s[0:1], 0, v[152:153]
	s_add_i32 m0, s2, 0x2000
	s_nop 0
	global_load_lds_dwordx4 v[168:169], off
	v_lshl_add_u64 v[168:169], v[202:203], 0, s[76:77]
	s_mov_b32 m0, s59
	s_nop 0
	global_load_lds_dwordx4 v[168:169], off
	v_lshl_add_u64 v[168:169], v[212:213], 0, s[76:77]
	s_mov_b32 m0, s60
	s_nop 0
	global_load_lds_dwordx4 v[168:169], off
	s_waitcnt vmcnt(8)
	s_waitcnt lgkmcnt(0)
	s_setprio 1
	s_barrier
	v_mfma_f32_16x16x32_bf16 v[62:65], v[136:139], v[194:197], v[62:65]
	v_mfma_f32_16x16x32_bf16 v[62:65], v[140:143], v[198:201], v[62:65]
	v_mfma_f32_16x16x32_bf16 v[58:61], v[144:147], v[194:197], v[58:61]
	v_mfma_f32_16x16x32_bf16 v[58:61], v[148:151], v[198:201], v[58:61]
	v_mfma_f32_16x16x32_bf16 v[54:57], v[136:139], v[222:225], v[54:57]
	v_mfma_f32_16x16x32_bf16 v[54:57], v[140:143], v[226:229], v[54:57]
	v_mfma_f32_16x16x32_bf16 v[46:49], v[144:147], v[222:225], v[46:49]
	v_mfma_f32_16x16x32_bf16 v[46:49], v[148:151], v[226:229], v[46:49]
	v_mfma_f32_16x16x32_bf16 v[38:41], v[136:139], v[230:233], v[38:41]
	v_mfma_f32_16x16x32_bf16 v[38:41], v[140:143], v[234:237], v[38:41]
	v_mfma_f32_16x16x32_bf16 v[30:33], v[144:147], v[230:233], v[30:33]
	v_mfma_f32_16x16x32_bf16 v[30:33], v[148:151], v[234:237], v[30:33]
	v_mfma_f32_16x16x32_bf16 v[22:25], v[136:139], v[238:241], v[22:25]
	v_mfma_f32_16x16x32_bf16 v[22:25], v[140:143], v[242:245], v[22:25]
	v_mfma_f32_16x16x32_bf16 v[14:17], v[144:147], v[238:241], v[14:17]
	v_mfma_f32_16x16x32_bf16 v[14:17], v[148:151], v[242:245], v[14:17]
	s_setprio 0
	s_setprio 1
	v_mfma_f32_16x16x32_bf16 v[50:53], v[164:167], v[194:197], v[50:53]
	v_mfma_f32_16x16x32_bf16 v[50:53], v[182:185], v[198:201], v[50:53]
	v_mfma_f32_16x16x32_bf16 v[42:45], v[186:189], v[194:197], v[42:45]
	v_mfma_f32_16x16x32_bf16 v[42:45], v[190:193], v[198:201], v[42:45]
	v_mfma_f32_16x16x32_bf16 v[34:37], v[164:167], v[222:225], v[34:37]
	v_mfma_f32_16x16x32_bf16 v[34:37], v[182:185], v[226:229], v[34:37]
	v_mfma_f32_16x16x32_bf16 v[26:29], v[186:189], v[222:225], v[26:29]
	v_mfma_f32_16x16x32_bf16 v[26:29], v[190:193], v[226:229], v[26:29]
	v_mfma_f32_16x16x32_bf16 v[18:21], v[164:167], v[230:233], v[18:21]
	v_mfma_f32_16x16x32_bf16 v[18:21], v[182:185], v[234:237], v[18:21]
	v_mfma_f32_16x16x32_bf16 v[10:13], v[186:189], v[230:233], v[10:13]
	v_mfma_f32_16x16x32_bf16 v[10:13], v[190:193], v[234:237], v[10:13]
	v_mfma_f32_16x16x32_bf16 v[6:9], v[164:167], v[238:241], v[6:9]
	v_mfma_f32_16x16x32_bf16 v[6:9], v[182:185], v[242:245], v[6:9]
	s_setprio 2
	s_barrier
	v_mfma_f32_16x16x32_bf16 v[2:5], v[186:189], v[238:241], v[2:5]
	v_mfma_f32_16x16x32_bf16 v[2:5], v[190:193], v[242:245], v[2:5]
	s_setprio 0
	s_add_i32 s0, s13, 2
	v_lshl_add_u64 v[132:133], v[132:133], 0, s[86:87]
	v_lshl_add_u64 v[134:135], v[134:135], 0, s[86:87]
	s_cmp_ge_i32 s13, s71
	s_mov_b32 s13, s0
	s_cbranch_scc1 .Lpx_1308

; #define PG8_STAGE(bufoff, gbase, voff) do { _Pragma("unroll") for (int _i = 0; _i < 2; ++_i) \
;         __builtin_amdgcn_global_load_lds((const unsigned*)((const char*)(gbase) + (voff)[_i]), (PG8_LAS unsigned*)(lds + (bufoff) + ldsw + _i * 8192), 16, 0, AUX_A); } while (0)
; #define PG8_STAGEB(bufoff, gbase, voff) do { _Pragma("unroll") for (int _i = 0; _i < 2; ++_i) \
;         __builtin_amdgcn_global_load_lds((const unsigned*)((const char*)(gbase) + (voff)[_i]), (PG8_LAS unsigned*)(lds + (bufoff) + ldsw + _i * 8192), 16, 0, AUX_B); } while (0)
; #define PG8_WAIT_V(n) asm volatile("s_waitcnt vmcnt(" #n ")" ::: "memory")
; template <class Epi, class Sched, bool ALIGN_EPI = false, bool SP2 = false>
; __device__ __forceinline__ void gemm_phase(PG8_LAS unsigned char* lds, const Gemm g, const Sched& S, const Epi& E) {
;     ...
;         for (int t = 0; t < nt; t += 2) {
;             const bool last = (t == nt - 2);
;             const char* a1 = PG8_KP(cA, t + 1, rot, nt);
;             const char* a2 = last ? nAr : PG8_KP(cA, t + 2, rot, nt); const char* b2 = last ? nBr : PG8_KP(cB, t + 2, rot, nt);
;             const char* a3 = a2 + kstep; const char* b3 = b2 + kstep;
;             if (last && has_next) S.a_ready(nxt);
;             if constexpr (SP2) {
;             PG8_LDB(B0, 0, 0); PG8_LDB(B1, 0, 1); PG8_SCHED; PG8_LDA(At, 0, 0); PG8_STAGE(PG8_SA(1, 1), a1 + hstep, voffA);
;             PG8_WAIT_V(8); PG8_WAIT_L(0); PG8_BAR; PG8_MMA(0, 0, At, B0); PG8_MMA(0, 1, At, B1); PG8_BAR; PG8_SCHED;
;             PG8_LDA(At, 0, 1); PG8_STAGEB(PG8_SB(0, 0), b2, voffB); PG8_STAGEB(PG8_SB(0, 1), b2 + hstep, voffB); PG8_STAGE(PG8_SA(0, 0), a2, voffA);
;             PG8_WAIT_V(8); PG8_WAIT_L(0); PG8_BAR; PG8_MMA(1, 0, At, B0); PG8_MMA(1, 1, At, B1); PG8_BAR; PG8_SCHED;
;             PG8_LDB(B0, 1, 0); PG8_LDB(B1, 1, 1); PG8_SCHED; PG8_LDA(At, 1, 0); PG8_STAGE(PG8_SA(0, 1), a2 + hstep, voffA);
;             PG8_WAIT_V(8); PG8_WAIT_L(0); PG8_BAR; PG8_MMA(0, 0, At, B0); PG8_MMA(0, 1, At, B1); PG8_BAR; PG8_SCHED;
;             PG8_LDA(At, 1, 1); PG8_STAGEB(PG8_SB(1, 0), b3, voffB); PG8_STAGEB(PG8_SB(1, 1), b3 + hstep, voffB); PG8_STAGE(PG8_SA(1, 0), a3, voffA);
;             PG8_WAIT_V(8); PG8_WAIT_L(0); PG8_BAR; PG8_MMA(1, 0, At, B0); PG8_MMA(1, 1, At, B1); PG8_BAR; PG8_SCHED;
;     ...
;         if constexpr (ALIGN_EPI) { if (wr == 1) PG8_BAR; }
.Lpk_1458:
	s_lshl_b32 s100, s29, 7
	s_add_u32 s100, s40, s100
	s_addc_u32 s101, s41, 0
	s_add_u32 s100, s100, 0x80
	s_addc_u32 s101, s101, 0
	s_add_i32 s30, s29, 2
	s_cmp_lt_u32 s29, 30
	s_cselect_b32 s0, 0, 0xffffffe0
	s_add_i32 s0, s30, s0
	s_ashr_i32 s1, s0, 31
	s_lshl_b64 s[0:1], s[0:1], 7
	s_add_u32 s2, s40, s0
	s_addc_u32 s31, s41, s1
	s_add_u32 s0, s34, s0
	s_addc_u32 s1, s35, s1
	s_cmp_eq_u32 s29, 30
	s_cselect_b32 s45, s13, s31
	s_cselect_b32 s44, s15, s2
	s_cselect_b32 s49, s71, s1
	s_cselect_b32 s48, s75, s0
	s_add_i32 s2, 0, 0x10000
	s_add_i32 s78, s2, s56
	s_add_i32 s31, 0, 0x14000
	s_add_i32 s47, s57, 0xe000
	s_add_i32 s81, s78, 0x2000
	s_add_u32 s50, s48, 0x80000
	s_addc_u32 s51, s49, 0
	s_add_i32 s82, s31, s56
	s_add_i32 s83, s82, 0x2000
	s_add_i32 s84, 0, 0x18000
	s_add_i32 s88, 0, 0x1c000
	s_add_u32 s42, s44, 0x80000
	s_addc_u32 s43, s45, 0
	s_add_i32 s1, s84, s56
	s_add_i32 s0, s1, 0x2000
	s_add_u32 s36, s48, 0x80080
	s_addc_u32 s37, s49, 0
	s_add_i32 s46, s88, s56
	s_add_i32 s31, s46, 0x2000
	v_lshl_add_u64 v[166:167], s[100:101], 0, v[138:139]
	s_mov_b32 m0, s61
	v_lshl_add_u64 v[168:169], s[100:101], 0, v[134:135]
	global_load_lds_dwordx4 v[166:167], off
	s_mov_b32 m0, s62
	s_nop 0
	global_load_lds_dwordx4 v[168:169], off
	s_add_i32 m0, s57, 0xc000
	s_nop 0
	global_load_lds_dwordx4 v[146:147], off
	s_mov_b32 m0, s47
	s_nop 0
	global_load_lds_dwordx4 v[144:145], off
	s_cmp_lg_u64 s[10:11], 0
	s_cbranch_scc1 .Lrp_1458
	s_barrier
.Lrp_1458:
	s_waitcnt vmcnt(8)
	s_waitcnt lgkmcnt(0)
	s_setprio 1
	s_barrier
	v_mfma_f32_16x16x32_bf16 v[128:131], v[150:153], v[196:199], 0
	v_mfma_f32_16x16x32_bf16 v[128:131], v[154:157], v[200:203], v[128:131]
	v_mfma_f32_16x16x32_bf16 v[120:123], v[158:161], v[196:199], 0
	v_mfma_f32_16x16x32_bf16 v[120:123], v[162:165], v[200:203], v[120:123]
	v_mfma_f32_16x16x32_bf16 v[112:115], v[150:153], v[222:225], 0
	v_mfma_f32_16x16x32_bf16 v[112:115], v[154:157], v[226:229], v[112:115]
	v_mfma_f32_16x16x32_bf16 v[104:107], v[158:161], v[222:225], 0
	v_mfma_f32_16x16x32_bf16 v[104:107], v[162:165], v[226:229], v[104:107]
	v_mfma_f32_16x16x32_bf16 v[94:97], v[150:153], v[230:233], 0
	v_mfma_f32_16x16x32_bf16 v[94:97], v[154:157], v[234:237], v[94:97]
	v_mfma_f32_16x16x32_bf16 v[86:89], v[158:161], v[230:233], 0
	v_mfma_f32_16x16x32_bf16 v[86:89], v[162:165], v[234:237], v[86:89]
	v_mfma_f32_16x16x32_bf16 v[78:81], v[150:153], v[238:241], 0
	v_mfma_f32_16x16x32_bf16 v[78:81], v[154:157], v[242:245], v[78:81]
	v_mfma_f32_16x16x32_bf16 v[70:73], v[158:161], v[238:241], 0
	v_mfma_f32_16x16x32_bf16 v[70:73], v[162:165], v[242:245], v[70:73]
	s_setprio 0
	s_setprio 1
	v_mfma_f32_16x16x32_bf16 v[124:127], v[180:183], v[196:199], 0
	v_mfma_f32_16x16x32_bf16 v[124:127], v[184:187], v[200:203], v[124:127]
	v_mfma_f32_16x16x32_bf16 v[116:119], v[188:191], v[196:199], 0
	v_mfma_f32_16x16x32_bf16 v[116:119], v[192:195], v[200:203], v[116:119]
	v_mfma_f32_16x16x32_bf16 v[108:111], v[180:183], v[222:225], 0
	v_mfma_f32_16x16x32_bf16 v[108:111], v[184:187], v[226:229], v[108:111]
	v_mfma_f32_16x16x32_bf16 v[100:103], v[188:191], v[222:225], 0
	v_mfma_f32_16x16x32_bf16 v[100:103], v[192:195], v[226:229], v[100:103]
	v_mfma_f32_16x16x32_bf16 v[90:93], v[180:183], v[230:233], 0
	v_mfma_f32_16x16x32_bf16 v[90:93], v[184:187], v[234:237], v[90:93]
	v_mfma_f32_16x16x32_bf16 v[82:85], v[188:191], v[230:233], 0
	v_mfma_f32_16x16x32_bf16 v[82:85], v[192:195], v[234:237], v[82:85]
	v_mfma_f32_16x16x32_bf16 v[74:77], v[180:183], v[238:241], 0
	v_mfma_f32_16x16x32_bf16 v[74:77], v[184:187], v[242:245], v[74:77]
	s_setprio 2
	s_barrier
	v_mfma_f32_16x16x32_bf16 v[66:69], v[188:191], v[238:241], 0
	v_mfma_f32_16x16x32_bf16 v[66:69], v[192:195], v[242:245], v[66:69]
	s_setprio 0
	s_mov_b32 m0, s78
	v_lshl_add_u64 v[166:167], s[48:49], 0, v[136:137]
	ds_read_b128 v[196:199], v149 offset:16384
	ds_read_b128 v[200:203], v149 offset:17408
	ds_read_b128 v[222:225], v149 offset:18432
	ds_read_b128 v[226:229], v149 offset:19456
	ds_read_b128 v[230:233], v149 offset:20480
	ds_read_b128 v[234:237], v149 offset:21504
	ds_read_b128 v[238:241], v149 offset:22528
	ds_read_b128 v[242:245], v149 offset:23552
	global_load_lds_dwordx4 v[166:167], off
	v_lshl_add_u64 v[168:169], s[48:49], 0, v[132:133]
	s_mov_b32 m0, s81
	v_lshl_add_u64 v[172:173], s[50:51], 0, v[136:137]
	global_load_lds_dwordx4 v[168:169], off
	s_mov_b32 m0, s82
	global_load_lds_dwordx4 v[172:173], off
	v_lshl_add_u64 v[172:173], s[50:51], 0, v[132:133]
	s_mov_b32 m0, s83
	s_nop 0
	global_load_lds_dwordx4 v[172:173], off
	s_waitcnt vmcnt(6)
	s_waitcnt lgkmcnt(0)
	s_setprio 1
	s_barrier
	v_mfma_f32_16x16x32_bf16 v[62:65], v[150:153], v[196:199], 0
	v_mfma_f32_16x16x32_bf16 v[62:65], v[154:157], v[200:203], v[62:65]
	v_mfma_f32_16x16x32_bf16 v[54:57], v[158:161], v[196:199], 0
	v_mfma_f32_16x16x32_bf16 v[54:57], v[162:165], v[200:203], v[54:57]
	v_mfma_f32_16x16x32_bf16 v[46:49], v[150:153], v[222:225], 0
	v_mfma_f32_16x16x32_bf16 v[46:49], v[154:157], v[226:229], v[46:49]
	v_mfma_f32_16x16x32_bf16 v[38:41], v[158:161], v[222:225], 0
	v_mfma_f32_16x16x32_bf16 v[38:41], v[162:165], v[226:229], v[38:41]
	v_mfma_f32_16x16x32_bf16 v[30:33], v[150:153], v[230:233], 0
	v_mfma_f32_16x16x32_bf16 v[30:33], v[154:157], v[234:237], v[30:33]
	v_mfma_f32_16x16x32_bf16 v[22:25], v[158:161], v[230:233], 0
	v_mfma_f32_16x16x32_bf16 v[22:25], v[162:165], v[234:237], v[22:25]
	v_mfma_f32_16x16x32_bf16 v[14:17], v[150:153], v[238:241], 0
	v_mfma_f32_16x16x32_bf16 v[14:17], v[154:157], v[242:245], v[14:17]
	v_mfma_f32_16x16x32_bf16 v[6:9], v[158:161], v[238:241], 0
	v_mfma_f32_16x16x32_bf16 v[6:9], v[162:165], v[242:245], v[6:9]
	s_setprio 0
	s_setprio 1
	v_mfma_f32_16x16x32_bf16 v[58:61], v[180:183], v[196:199], 0
	v_mfma_f32_16x16x32_bf16 v[58:61], v[184:187], v[200:203], v[58:61]
	v_mfma_f32_16x16x32_bf16 v[50:53], v[188:191], v[196:199], 0
	v_mfma_f32_16x16x32_bf16 v[50:53], v[192:195], v[200:203], v[50:53]
	v_mfma_f32_16x16x32_bf16 v[42:45], v[180:183], v[222:225], 0
	v_mfma_f32_16x16x32_bf16 v[42:45], v[184:187], v[226:229], v[42:45]
	v_mfma_f32_16x16x32_bf16 v[34:37], v[188:191], v[222:225], 0
	v_mfma_f32_16x16x32_bf16 v[34:37], v[192:195], v[226:229], v[34:37]
	v_mfma_f32_16x16x32_bf16 v[26:29], v[180:183], v[230:233], 0
	v_mfma_f32_16x16x32_bf16 v[26:29], v[184:187], v[234:237], v[26:29]
	v_mfma_f32_16x16x32_bf16 v[18:21], v[188:191], v[230:233], 0
	v_mfma_f32_16x16x32_bf16 v[18:21], v[192:195], v[234:237], v[18:21]
	v_mfma_f32_16x16x32_bf16 v[10:13], v[180:183], v[238:241], 0
	v_mfma_f32_16x16x32_bf16 v[10:13], v[184:187], v[242:245], v[10:13]
	s_setprio 2
	s_barrier
; #define PG8_STAGE(bufoff, gbase, voff) do { _Pragma("unroll") for (int _i = 0; _i < 2; ++_i) \
;         __builtin_amdgcn_global_load_lds((const unsigned*)((const char*)(gbase) + (voff)[_i]), (PG8_LAS unsigned*)(lds + (bufoff) + ldsw + _i * 8192), 16, 0, AUX_A); } while (0)
; #define PG8_STAGEB(bufoff, gbase, voff) do { _Pragma("unroll") for (int _i = 0; _i < 2; ++_i) \
;         __builtin_amdgcn_global_load_lds((const unsigned*)((const char*)(gbase) + (voff)[_i]), (PG8_LAS unsigned*)(lds + (bufoff) + ldsw + _i * 8192), 16, 0, AUX_B); } while (0)
; #define PG8_LDA(dst, b, h) do { _Pragma("unroll") for (int m = 0; m < 4; ++m) _Pragma("unroll") for (int k = 0; k < 2; ++k) dst[m][k] = *(const PG8_LAS bf16x8*)(lds + PG8_SA(b, h) + aoff + m * 2048 + k * 1024); } while (0)
; #define PG8_LDB(dst, b, h) do { _Pragma("unroll") for (int n = 0; n < 2; ++n) _Pragma("unroll") for (int k = 0; k < 2; ++k) dst[n][k] = *(const PG8_LAS bf16x8*)(lds + PG8_SB(b, h) + boff + n * 2048 + k * 1024); } while (0)
; #define PG8_MMA(ai, bj, At, Bt) do { __builtin_amdgcn_s_setprio(1); _Pragma("unroll") for (int m = 0; m < 4; ++m) _Pragma("unroll") for (int n = 0; n < 2; ++n) _Pragma("unroll") for (int k = 0; k < 2; ++k) \
;         acc[ai][bj][m][n] = __builtin_amdgcn_mfma_f32_16x16x32_bf16(Bt[n][k], At[m][k], acc[ai][bj][m][n], 0, 0, 0); __builtin_amdgcn_s_setprio(0); } while (0)
; #define PG8_WAIT_V(n) asm volatile("s_waitcnt vmcnt(" #n ")" ::: "memory")
; #define PG8_WAIT_L(n) asm volatile("s_waitcnt lgkmcnt(" #n ")" ::: "memory")
; #define PG8_BAR __builtin_amdgcn_s_barrier()
; #define PG8_SCHED __builtin_amdgcn_sched_barrier(0)
; template <class Epi, class Sched, bool ALIGN_EPI = false, bool SP2 = false>
; __device__ __forceinline__ void gemm_phase(PG8_LAS unsigned char* lds, const Gemm g, const Sched& S, const Epi& E) {
;     ...
;             PG8_LDA(At, 0, 1); PG8_STAGEB(PG8_SB(0, 0), b2, voffB); PG8_STAGEB(PG8_SB(0, 1), b2 + hstep, voffB); PG8_STAGE(PG8_SA(0, 0), a2, voffA);
;             PG8_WAIT_V(8); PG8_WAIT_L(0); PG8_BAR; PG8_MMA(1, 0, At, B0); PG8_MMA(1, 1, At, B1); PG8_BAR; PG8_SCHED;
;             PG8_LDB(B0, 1, 0); PG8_LDB(B1, 1, 1); PG8_SCHED; PG8_LDA(At, 1, 0); PG8_STAGE(PG8_SA(0, 1), a2 + hstep, voffA);
;             PG8_WAIT_V(8); PG8_WAIT_L(0); PG8_BAR; PG8_MMA(0, 0, At, B0); PG8_MMA(0, 1, At, B1); PG8_BAR; PG8_SCHED;
	v_mfma_f32_16x16x32_bf16 v[2:5], v[188:191], v[238:241], 0
	v_mfma_f32_16x16x32_bf16 v[2:5], v[192:195], v[242:245], v[2:5]
	s_setprio 0
	v_add_u32_e32 v162, s84, v99
	v_add_u32_e32 v192, s88, v99
	ds_read_b128 v[150:153], v162
	ds_read_b128 v[154:157], v162 offset:1024
	ds_read_b128 v[158:161], v162 offset:2048
	ds_read_b128 v[162:165], v162 offset:3072
	ds_read_b128 v[180:183], v192
	ds_read_b128 v[184:187], v192 offset:1024
	ds_read_b128 v[188:191], v192 offset:2048
	ds_read_b128 v[192:195], v192 offset:3072
	s_mov_b32 m0, s59
	v_lshl_add_u64 v[246:247], s[42:43], 0, v[138:139]
	ds_read_b128 v[196:199], v149 offset:32768
	ds_read_b128 v[200:203], v149 offset:33792
	ds_read_b128 v[222:225], v149 offset:34816
	ds_read_b128 v[226:229], v149 offset:35840
	ds_read_b128 v[230:233], v149 offset:36864
	ds_read_b128 v[234:237], v149 offset:37888
	ds_read_b128 v[238:241], v149 offset:38912
	ds_read_b128 v[242:245], v149 offset:39936
	v_lshl_add_u64 v[172:173], s[44:45], 0, v[138:139]
	s_mov_b32 m0, s57
	v_lshl_add_u64 v[212:213], s[44:45], 0, v[134:135]
	global_load_lds_dwordx4 v[172:173], off
	s_mov_b32 m0, s58
	s_nop 0
	global_load_lds_dwordx4 v[212:213], off
	s_mov_b32 m0, s59
	s_nop 0
	global_load_lds_dwordx4 v[246:247], off
	v_lshl_add_u64 v[246:247], s[42:43], 0, v[134:135]
	s_mov_b32 m0, s60
	s_nop 0
	global_load_lds_dwordx4 v[246:247], off
	s_waitcnt vmcnt(8)
	s_waitcnt lgkmcnt(0)
	s_setprio 1
	s_barrier
	v_mfma_f32_16x16x32_bf16 v[128:131], v[150:153], v[196:199], v[128:131]
	v_mfma_f32_16x16x32_bf16 v[128:131], v[154:157], v[200:203], v[128:131]
	v_mfma_f32_16x16x32_bf16 v[120:123], v[158:161], v[196:199], v[120:123]
	v_mfma_f32_16x16x32_bf16 v[120:123], v[162:165], v[200:203], v[120:123]
	v_mfma_f32_16x16x32_bf16 v[112:115], v[150:153], v[222:225], v[112:115]
	v_mfma_f32_16x16x32_bf16 v[112:115], v[154:157], v[226:229], v[112:115]
	v_mfma_f32_16x16x32_bf16 v[104:107], v[158:161], v[222:225], v[104:107]
	v_mfma_f32_16x16x32_bf16 v[104:107], v[162:165], v[226:229], v[104:107]
	v_mfma_f32_16x16x32_bf16 v[94:97], v[150:153], v[230:233], v[94:97]
	v_mfma_f32_16x16x32_bf16 v[94:97], v[154:157], v[234:237], v[94:97]
	v_mfma_f32_16x16x32_bf16 v[86:89], v[158:161], v[230:233], v[86:89]
	v_mfma_f32_16x16x32_bf16 v[86:89], v[162:165], v[234:237], v[86:89]
	v_mfma_f32_16x16x32_bf16 v[78:81], v[150:153], v[238:241], v[78:81]
	v_mfma_f32_16x16x32_bf16 v[78:81], v[154:157], v[242:245], v[78:81]
	v_mfma_f32_16x16x32_bf16 v[70:73], v[158:161], v[238:241], v[70:73]
	v_mfma_f32_16x16x32_bf16 v[70:73], v[162:165], v[242:245], v[70:73]
	s_setprio 0
	s_setprio 1
	v_mfma_f32_16x16x32_bf16 v[124:127], v[180:183], v[196:199], v[124:127]
	v_mfma_f32_16x16x32_bf16 v[124:127], v[184:187], v[200:203], v[124:127]
	v_mfma_f32_16x16x32_bf16 v[116:119], v[188:191], v[196:199], v[116:119]
	v_mfma_f32_16x16x32_bf16 v[116:119], v[192:195], v[200:203], v[116:119]
	v_mfma_f32_16x16x32_bf16 v[108:111], v[180:183], v[222:225], v[108:111]
	v_mfma_f32_16x16x32_bf16 v[108:111], v[184:187], v[226:229], v[108:111]
	v_mfma_f32_16x16x32_bf16 v[100:103], v[188:191], v[222:225], v[100:103]
	v_mfma_f32_16x16x32_bf16 v[100:103], v[192:195], v[226:229], v[100:103]
	v_mfma_f32_16x16x32_bf16 v[90:93], v[180:183], v[230:233], v[90:93]
	v_mfma_f32_16x16x32_bf16 v[90:93], v[184:187], v[234:237], v[90:93]
	v_mfma_f32_16x16x32_bf16 v[82:85], v[188:191], v[230:233], v[82:85]
	v_mfma_f32_16x16x32_bf16 v[82:85], v[192:195], v[234:237], v[82:85]
	v_mfma_f32_16x16x32_bf16 v[74:77], v[180:183], v[238:241], v[74:77]
	v_mfma_f32_16x16x32_bf16 v[74:77], v[184:187], v[242:245], v[74:77]
	s_setprio 2
	s_barrier
; #define PG8_STAGE(bufoff, gbase, voff) do { _Pragma("unroll") for (int _i = 0; _i < 2; ++_i) \
;         __builtin_amdgcn_global_load_lds((const unsigned*)((const char*)(gbase) + (voff)[_i]), (PG8_LAS unsigned*)(lds + (bufoff) + ldsw + _i * 8192), 16, 0, AUX_A); } while (0)
; #define PG8_STAGEB(bufoff, gbase, voff) do { _Pragma("unroll") for (int _i = 0; _i < 2; ++_i) \
;         __builtin_amdgcn_global_load_lds((const unsigned*)((const char*)(gbase) + (voff)[_i]), (PG8_LAS unsigned*)(lds + (bufoff) + ldsw + _i * 8192), 16, 0, AUX_B); } while (0)
; #define PG8_LDA(dst, b, h) do { _Pragma("unroll") for (int m = 0; m < 4; ++m) _Pragma("unroll") for (int k = 0; k < 2; ++k) dst[m][k] = *(const PG8_LAS bf16x8*)(lds + PG8_SA(b, h) + aoff + m * 2048 + k * 1024); } while (0)
; #define PG8_MMA(ai, bj, At, Bt) do { __builtin_amdgcn_s_setprio(1); _Pragma("unroll") for (int m = 0; m < 4; ++m) _Pragma("unroll") for (int n = 0; n < 2; ++n) _Pragma("unroll") for (int k = 0; k < 2; ++k) \
;         acc[ai][bj][m][n] = __builtin_amdgcn_mfma_f32_16x16x32_bf16(Bt[n][k], At[m][k], acc[ai][bj][m][n], 0, 0, 0); __builtin_amdgcn_s_setprio(0); } while (0)
; #define PG8_WAIT_V(n) asm volatile("s_waitcnt vmcnt(" #n ")" ::: "memory")
; #define PG8_WAIT_L(n) asm volatile("s_waitcnt lgkmcnt(" #n ")" ::: "memory")
; #define PG8_BAR __builtin_amdgcn_s_barrier()
; #define PG8_SCHED __builtin_amdgcn_sched_barrier(0)
; template <class Epi, class Sched, bool ALIGN_EPI = false, bool SP2 = false>
; __device__ __forceinline__ void gemm_phase(PG8_LAS unsigned char* lds, const Gemm g, const Sched& S, const Epi& E) {
;     ...
;         for (int t = 0; t < nt; t += 2) {
;     ...
;             PG8_LDA(At, 1, 1); PG8_STAGEB(PG8_SB(1, 0), b3, voffB); PG8_STAGEB(PG8_SB(1, 1), b3 + hstep, voffB); PG8_STAGE(PG8_SA(1, 0), a3, voffA);
;             PG8_WAIT_V(8); PG8_WAIT_L(0); PG8_BAR; PG8_MMA(1, 0, At, B0); PG8_MMA(1, 1, At, B1); PG8_BAR; PG8_SCHED;
	v_mfma_f32_16x16x32_bf16 v[66:69], v[188:191], v[238:241], v[66:69]
	v_mfma_f32_16x16x32_bf16 v[66:69], v[192:195], v[242:245], v[66:69]
	s_setprio 0
	s_mov_b32 m0, s1
	v_lshl_add_u64 v[166:167], v[166:167], 0, s[76:77]
	ds_read_b128 v[196:199], v149 offset:49152
	ds_read_b128 v[200:203], v149 offset:50176
	ds_read_b128 v[222:225], v149 offset:51200
	ds_read_b128 v[226:229], v149 offset:52224
	ds_read_b128 v[230:233], v149 offset:53248
	ds_read_b128 v[234:237], v149 offset:54272
	ds_read_b128 v[238:241], v149 offset:55296
	ds_read_b128 v[242:245], v149 offset:56320
	global_load_lds_dwordx4 v[166:167], off
	v_lshl_add_u64 v[166:167], v[168:169], 0, s[76:77]
	s_mov_b32 m0, s0
	s_nop 0
	global_load_lds_dwordx4 v[166:167], off
	v_lshl_add_u64 v[166:167], s[36:37], 0, v[136:137]
	s_mov_b32 m0, s46
	s_nop 0
	global_load_lds_dwordx4 v[166:167], off
	v_lshl_add_u64 v[166:167], s[36:37], 0, v[132:133]
	s_mov_b32 m0, s31
	s_nop 0
	global_load_lds_dwordx4 v[166:167], off
	s_waitcnt vmcnt(6)
	s_waitcnt lgkmcnt(0)
	s_setprio 1
	s_barrier
	v_mfma_f32_16x16x32_bf16 v[62:65], v[150:153], v[196:199], v[62:65]
	v_mfma_f32_16x16x32_bf16 v[62:65], v[154:157], v[200:203], v[62:65]
	v_mfma_f32_16x16x32_bf16 v[54:57], v[158:161], v[196:199], v[54:57]
	v_mfma_f32_16x16x32_bf16 v[54:57], v[162:165], v[200:203], v[54:57]
	v_mfma_f32_16x16x32_bf16 v[46:49], v[150:153], v[222:225], v[46:49]
	v_mfma_f32_16x16x32_bf16 v[46:49], v[154:157], v[226:229], v[46:49]
	v_mfma_f32_16x16x32_bf16 v[38:41], v[158:161], v[222:225], v[38:41]
	v_mfma_f32_16x16x32_bf16 v[38:41], v[162:165], v[226:229], v[38:41]
	v_mfma_f32_16x16x32_bf16 v[30:33], v[150:153], v[230:233], v[30:33]
	v_mfma_f32_16x16x32_bf16 v[30:33], v[154:157], v[234:237], v[30:33]
	v_mfma_f32_16x16x32_bf16 v[22:25], v[158:161], v[230:233], v[22:25]
	v_mfma_f32_16x16x32_bf16 v[22:25], v[162:165], v[234:237], v[22:25]
	v_mfma_f32_16x16x32_bf16 v[14:17], v[150:153], v[238:241], v[14:17]
	v_mfma_f32_16x16x32_bf16 v[14:17], v[154:157], v[242:245], v[14:17]
	v_mfma_f32_16x16x32_bf16 v[6:9], v[158:161], v[238:241], v[6:9]
	v_mfma_f32_16x16x32_bf16 v[6:9], v[162:165], v[242:245], v[6:9]
	s_setprio 0
	s_setprio 1
	v_mfma_f32_16x16x32_bf16 v[58:61], v[180:183], v[196:199], v[58:61]
	v_mfma_f32_16x16x32_bf16 v[58:61], v[184:187], v[200:203], v[58:61]
	v_mfma_f32_16x16x32_bf16 v[50:53], v[188:191], v[196:199], v[50:53]
	v_mfma_f32_16x16x32_bf16 v[50:53], v[192:195], v[200:203], v[50:53]
	v_mfma_f32_16x16x32_bf16 v[42:45], v[180:183], v[222:225], v[42:45]
	v_mfma_f32_16x16x32_bf16 v[42:45], v[184:187], v[226:229], v[42:45]
	v_mfma_f32_16x16x32_bf16 v[34:37], v[188:191], v[222:225], v[34:37]
	v_mfma_f32_16x16x32_bf16 v[34:37], v[192:195], v[226:229], v[34:37]
	v_mfma_f32_16x16x32_bf16 v[26:29], v[180:183], v[230:233], v[26:29]
	v_mfma_f32_16x16x32_bf16 v[26:29], v[184:187], v[234:237], v[26:29]
	v_mfma_f32_16x16x32_bf16 v[18:21], v[188:191], v[230:233], v[18:21]
	v_mfma_f32_16x16x32_bf16 v[18:21], v[192:195], v[234:237], v[18:21]
	v_mfma_f32_16x16x32_bf16 v[10:13], v[180:183], v[238:241], v[10:13]
	v_mfma_f32_16x16x32_bf16 v[10:13], v[184:187], v[242:245], v[10:13]
	s_setprio 2
	s_barrier
	v_mfma_f32_16x16x32_bf16 v[2:5], v[188:191], v[238:241], v[2:5]
	v_mfma_f32_16x16x32_bf16 v[2:5], v[192:195], v[242:245], v[2:5]
	s_setprio 0
	v_lshl_add_u64 v[144:145], v[144:145], 0, s[86:87]
	v_lshl_add_u64 v[146:147], v[146:147], 0, s[86:87]
	s_cmp_gt_u32 s30, 31
	s_mov_b32 s29, s30
	s_cbranch_scc1 .Lpx_1458

; #define PG8_STAGE(bufoff, gbase, voff) do { _Pragma("unroll") for (int _i = 0; _i < 2; ++_i) \
;         __builtin_amdgcn_global_load_lds((const unsigned*)((const char*)(gbase) + (voff)[_i]), (PG8_LAS unsigned*)(lds + (bufoff) + ldsw + _i * 8192), 16, 0, AUX_A); } while (0)
; #define PG8_STAGEB(bufoff, gbase, voff) do { _Pragma("unroll") for (int _i = 0; _i < 2; ++_i) \
;         __builtin_amdgcn_global_load_lds((const unsigned*)((const char*)(gbase) + (voff)[_i]), (PG8_LAS unsigned*)(lds + (bufoff) + ldsw + _i * 8192), 16, 0, AUX_B); } while (0)
; #define PG8_WAIT_V(n) asm volatile("s_waitcnt vmcnt(" #n ")" ::: "memory")
; template <class Epi, class Sched, bool ALIGN_EPI = false, bool SP2 = false>
; __device__ __forceinline__ void gemm_phase(PG8_LAS unsigned char* lds, const Gemm g, const Sched& S, const Epi& E) {
;     ...
;         for (int t = 0; t < nt; t += 2) {
;             const bool last = (t == nt - 2);
;             const char* a1 = PG8_KP(cA, t + 1, rot, nt);
;             const char* a2 = last ? nAr : PG8_KP(cA, t + 2, rot, nt); const char* b2 = last ? nBr : PG8_KP(cB, t + 2, rot, nt);
;             const char* a3 = a2 + kstep; const char* b3 = b2 + kstep;
;             if (last && has_next) S.a_ready(nxt);
;             if constexpr (SP2) {
;             PG8_LDB(B0, 0, 0); PG8_LDB(B1, 0, 1); PG8_SCHED; PG8_LDA(At, 0, 0); PG8_STAGE(PG8_SA(1, 1), a1 + hstep, voffA);
;             PG8_WAIT_V(8); PG8_WAIT_L(0); PG8_BAR; PG8_MMA(0, 0, At, B0); PG8_MMA(0, 1, At, B1); PG8_BAR; PG8_SCHED;
;             PG8_LDA(At, 0, 1); PG8_STAGEB(PG8_SB(0, 0), b2, voffB); PG8_STAGEB(PG8_SB(0, 1), b2 + hstep, voffB); PG8_STAGE(PG8_SA(0, 0), a2, voffA);
;             PG8_WAIT_V(8); PG8_WAIT_L(0); PG8_BAR; PG8_MMA(1, 0, At, B0); PG8_MMA(1, 1, At, B1); PG8_BAR; PG8_SCHED;
;             PG8_LDB(B0, 1, 0); PG8_LDB(B1, 1, 1); PG8_SCHED; PG8_LDA(At, 1, 0); PG8_STAGE(PG8_SA(0, 1), a2 + hstep, voffA);
;             PG8_WAIT_V(8); PG8_WAIT_L(0); PG8_BAR; PG8_MMA(0, 0, At, B0); PG8_MMA(0, 1, At, B1); PG8_BAR; PG8_SCHED;
;             PG8_LDA(At, 1, 1); PG8_STAGEB(PG8_SB(1, 0), b3, voffB); PG8_STAGEB(PG8_SB(1, 1), b3 + hstep, voffB); PG8_STAGE(PG8_SA(1, 0), a3, voffA);
;             PG8_WAIT_V(8); PG8_WAIT_L(0); PG8_BAR; PG8_MMA(1, 0, At, B0); PG8_MMA(1, 1, At, B1); PG8_BAR; PG8_SCHED;
;     ...
;         if constexpr (ALIGN_EPI) { if (wr == 1) PG8_BAR; }
.Lpk_1654:
	s_or_b32 s0, s15, 1
	s_cmp_ge_i32 s0, s82
	s_cselect_b32 s2, s82, 0
	s_add_i32 s15, s15, 2
	s_cmp_ge_i32 s15, s82
	s_cselect_b32 s0, s82, 0
	s_sub_i32 s0, s83, s0
	s_ashr_i32 s1, s0, 31
	s_lshl_b64 s[0:1], s[0:1], 7
	s_add_u32 s29, s38, s0
	s_addc_u32 s42, s39, s1
	s_add_u32 s0, s34, s0
	s_addc_u32 s1, s35, s1
	s_cmp_eq_u32 s82, s83
	s_cselect_b32 s45, s41, s42
	s_cselect_b32 s44, s40, s29
	s_cselect_b32 s43, s19, s1
	s_cselect_b32 s42, s18, s0
	s_add_i32 s29, 0, 0x10000
	s_add_i32 s46, 0, 0x14000
	v_mad_i64_i32 v[168:169], s[0:1], s2, v220, v[134:135]
	s_add_i32 m0, s50, 0xc000
	global_load_lds_dwordx4 v[168:169], off
	v_mad_i64_i32 v[168:169], s[0:1], s2, v220, v[132:133]
	s_add_i32 m0, s50, 0xe000
	s_nop 0
	global_load_lds_dwordx4 v[168:169], off
	s_cmp_lg_u64 s[12:13], 0
	s_cbranch_scc1 .Lrp_1654
	s_barrier
.Lrp_1654:
	s_waitcnt vmcnt(8)
	s_waitcnt lgkmcnt(0)
	s_setprio 1
	s_barrier
	v_mfma_f32_16x16x32_bf16 v[128:131], v[136:139], v[194:197], 0
	v_mfma_f32_16x16x32_bf16 v[128:131], v[140:143], v[198:201], v[128:131]
	v_mfma_f32_16x16x32_bf16 v[124:127], v[144:147], v[194:197], 0
	v_mfma_f32_16x16x32_bf16 v[124:127], v[148:151], v[198:201], v[124:127]
	v_mfma_f32_16x16x32_bf16 v[120:123], v[136:139], v[222:225], 0
	v_mfma_f32_16x16x32_bf16 v[120:123], v[140:143], v[226:229], v[120:123]
	v_mfma_f32_16x16x32_bf16 v[112:115], v[144:147], v[222:225], 0
	v_mfma_f32_16x16x32_bf16 v[112:115], v[148:151], v[226:229], v[112:115]
	v_mfma_f32_16x16x32_bf16 v[104:107], v[136:139], v[230:233], 0
	v_mfma_f32_16x16x32_bf16 v[104:107], v[140:143], v[234:237], v[104:107]
	v_mfma_f32_16x16x32_bf16 v[94:97], v[144:147], v[230:233], 0
	v_mfma_f32_16x16x32_bf16 v[94:97], v[148:151], v[234:237], v[94:97]
	v_mfma_f32_16x16x32_bf16 v[86:89], v[136:139], v[238:241], 0
	v_mfma_f32_16x16x32_bf16 v[86:89], v[140:143], v[242:245], v[86:89]
	v_mfma_f32_16x16x32_bf16 v[78:81], v[144:147], v[238:241], 0
	v_mfma_f32_16x16x32_bf16 v[78:81], v[148:151], v[242:245], v[78:81]
	s_setprio 0
	s_setprio 1
	v_mfma_f32_16x16x32_bf16 v[116:119], v[152:155], v[194:197], 0
	v_mfma_f32_16x16x32_bf16 v[116:119], v[180:183], v[198:201], v[116:119]
	v_mfma_f32_16x16x32_bf16 v[108:111], v[184:187], v[194:197], 0
	v_mfma_f32_16x16x32_bf16 v[108:111], v[190:193], v[198:201], v[108:111]
	v_mfma_f32_16x16x32_bf16 v[100:103], v[152:155], v[222:225], 0
	v_mfma_f32_16x16x32_bf16 v[100:103], v[180:183], v[226:229], v[100:103]
	v_mfma_f32_16x16x32_bf16 v[90:93], v[184:187], v[222:225], 0
	v_mfma_f32_16x16x32_bf16 v[90:93], v[190:193], v[226:229], v[90:93]
	v_mfma_f32_16x16x32_bf16 v[82:85], v[152:155], v[230:233], 0
	v_mfma_f32_16x16x32_bf16 v[82:85], v[180:183], v[234:237], v[82:85]
	v_mfma_f32_16x16x32_bf16 v[74:77], v[184:187], v[230:233], 0
	v_mfma_f32_16x16x32_bf16 v[74:77], v[190:193], v[234:237], v[74:77]
	v_mfma_f32_16x16x32_bf16 v[70:73], v[152:155], v[238:241], 0
	v_mfma_f32_16x16x32_bf16 v[70:73], v[180:183], v[242:245], v[70:73]
	s_setprio 2
	s_barrier
	v_mfma_f32_16x16x32_bf16 v[66:69], v[184:187], v[238:241], 0
	v_mfma_f32_16x16x32_bf16 v[66:69], v[190:193], v[242:245], v[66:69]
	s_setprio 0
	s_add_i32 s0, s29, s49
	v_lshl_add_u64 v[168:169], s[42:43], 0, v[160:161]
	s_mov_b32 m0, s0
	ds_read_b128 v[194:197], v189 offset:16384
	ds_read_b128 v[198:201], v189 offset:17408
	ds_read_b128 v[222:225], v189 offset:18432
	ds_read_b128 v[226:229], v189 offset:19456
	ds_read_b128 v[230:233], v189 offset:20480
	ds_read_b128 v[234:237], v189 offset:21504
	ds_read_b128 v[238:241], v189 offset:22528
	ds_read_b128 v[242:245], v189 offset:23552
	global_load_lds_dwordx4 v[168:169], off
	s_add_i32 m0, s0, 0x2000
	s_add_u32 s0, s42, 0x160000
	v_lshl_add_u64 v[172:173], s[42:43], 0, v[156:157]
	s_addc_u32 s1, s43, 0
	s_add_i32 s2, s46, s49
	global_load_lds_dwordx4 v[172:173], off
	v_lshl_add_u64 v[202:203], s[0:1], 0, v[160:161]
	s_mov_b32 m0, s2
	v_lshl_add_u64 v[212:213], s[44:45], 0, v[158:159]
	global_load_lds_dwordx4 v[202:203], off
	v_lshl_add_u64 v[202:203], s[0:1], 0, v[156:157]
	s_add_i32 m0, s2, 0x2000
	s_nop 0
	global_load_lds_dwordx4 v[202:203], off
	v_lshl_add_u64 v[202:203], s[44:45], 0, v[162:163]
	s_mov_b32 m0, s50
	s_nop 0
	global_load_lds_dwordx4 v[202:203], off
	s_mov_b32 m0, s51
	s_nop 0
	global_load_lds_dwordx4 v[212:213], off
	s_waitcnt vmcnt(8)
	s_waitcnt lgkmcnt(0)
	s_setprio 1
	s_barrier
	v_mfma_f32_16x16x32_bf16 v[62:65], v[136:139], v[194:197], 0
	v_mfma_f32_16x16x32_bf16 v[62:65], v[140:143], v[198:201], v[62:65]
	v_mfma_f32_16x16x32_bf16 v[58:61], v[144:147], v[194:197], 0
	v_mfma_f32_16x16x32_bf16 v[58:61], v[148:151], v[198:201], v[58:61]
	v_mfma_f32_16x16x32_bf16 v[54:57], v[136:139], v[222:225], 0
	v_mfma_f32_16x16x32_bf16 v[54:57], v[140:143], v[226:229], v[54:57]
	v_mfma_f32_16x16x32_bf16 v[46:49], v[144:147], v[222:225], 0
	v_mfma_f32_16x16x32_bf16 v[46:49], v[148:151], v[226:229], v[46:49]
	v_mfma_f32_16x16x32_bf16 v[38:41], v[136:139], v[230:233], 0
	v_mfma_f32_16x16x32_bf16 v[38:41], v[140:143], v[234:237], v[38:41]
	v_mfma_f32_16x16x32_bf16 v[30:33], v[144:147], v[230:233], 0
	v_mfma_f32_16x16x32_bf16 v[30:33], v[148:151], v[234:237], v[30:33]
	v_mfma_f32_16x16x32_bf16 v[22:25], v[136:139], v[238:241], 0
	v_mfma_f32_16x16x32_bf16 v[22:25], v[140:143], v[242:245], v[22:25]
	v_mfma_f32_16x16x32_bf16 v[14:17], v[144:147], v[238:241], 0
	v_mfma_f32_16x16x32_bf16 v[14:17], v[148:151], v[242:245], v[14:17]
	s_setprio 0
	s_setprio 1
	v_mfma_f32_16x16x32_bf16 v[50:53], v[152:155], v[194:197], 0
	v_mfma_f32_16x16x32_bf16 v[50:53], v[180:183], v[198:201], v[50:53]
	v_mfma_f32_16x16x32_bf16 v[42:45], v[184:187], v[194:197], 0
	v_mfma_f32_16x16x32_bf16 v[42:45], v[190:193], v[198:201], v[42:45]
	v_mfma_f32_16x16x32_bf16 v[34:37], v[152:155], v[222:225], 0
	v_mfma_f32_16x16x32_bf16 v[34:37], v[180:183], v[226:229], v[34:37]
	v_mfma_f32_16x16x32_bf16 v[26:29], v[184:187], v[222:225], 0
	v_mfma_f32_16x16x32_bf16 v[26:29], v[190:193], v[226:229], v[26:29]
	v_mfma_f32_16x16x32_bf16 v[18:21], v[152:155], v[230:233], 0
	v_mfma_f32_16x16x32_bf16 v[18:21], v[180:183], v[234:237], v[18:21]
	v_mfma_f32_16x16x32_bf16 v[10:13], v[184:187], v[230:233], 0
	v_mfma_f32_16x16x32_bf16 v[10:13], v[190:193], v[234:237], v[10:13]
	v_mfma_f32_16x16x32_bf16 v[6:9], v[152:155], v[238:241], 0
	v_mfma_f32_16x16x32_bf16 v[6:9], v[180:183], v[242:245], v[6:9]
	s_setprio 2
	s_barrier
; #define PG8_STAGE(bufoff, gbase, voff) do { _Pragma("unroll") for (int _i = 0; _i < 2; ++_i) \
;         __builtin_amdgcn_global_load_lds((const unsigned*)((const char*)(gbase) + (voff)[_i]), (PG8_LAS unsigned*)(lds + (bufoff) + ldsw + _i * 8192), 16, 0, AUX_A); } while (0)
; #define PG8_LDA(dst, b, h) do { _Pragma("unroll") for (int m = 0; m < 4; ++m) _Pragma("unroll") for (int k = 0; k < 2; ++k) dst[m][k] = *(const PG8_LAS bf16x8*)(lds + PG8_SA(b, h) + aoff + m * 2048 + k * 1024); } while (0)
; #define PG8_LDB(dst, b, h) do { _Pragma("unroll") for (int n = 0; n < 2; ++n) _Pragma("unroll") for (int k = 0; k < 2; ++k) dst[n][k] = *(const PG8_LAS bf16x8*)(lds + PG8_SB(b, h) + boff + n * 2048 + k * 1024); } while (0)
; #define PG8_MMA(ai, bj, At, Bt) do { __builtin_amdgcn_s_setprio(1); _Pragma("unroll") for (int m = 0; m < 4; ++m) _Pragma("unroll") for (int n = 0; n < 2; ++n) _Pragma("unroll") for (int k = 0; k < 2; ++k) \
;         acc[ai][bj][m][n] = __builtin_amdgcn_mfma_f32_16x16x32_bf16(Bt[n][k], At[m][k], acc[ai][bj][m][n], 0, 0, 0); __builtin_amdgcn_s_setprio(0); } while (0)
; #define PG8_WAIT_V(n) asm volatile("s_waitcnt vmcnt(" #n ")" ::: "memory")
; #define PG8_WAIT_L(n) asm volatile("s_waitcnt lgkmcnt(" #n ")" ::: "memory")
; #define PG8_BAR __builtin_amdgcn_s_barrier()
; #define PG8_SCHED __builtin_amdgcn_sched_barrier(0)
; template <class Epi, class Sched, bool ALIGN_EPI = false, bool SP2 = false>
; __device__ __forceinline__ void gemm_phase(PG8_LAS unsigned char* lds, const Gemm g, const Sched& S, const Epi& E) {
;     ...
;             PG8_LDB(B0, 1, 0); PG8_LDB(B1, 1, 1); PG8_SCHED; PG8_LDA(At, 1, 0); PG8_STAGE(PG8_SA(0, 1), a2 + hstep, voffA);
;             PG8_WAIT_V(8); PG8_WAIT_L(0); PG8_BAR; PG8_MMA(0, 0, At, B0); PG8_MMA(0, 1, At, B1); PG8_BAR; PG8_SCHED;
	v_mfma_f32_16x16x32_bf16 v[2:5], v[184:187], v[238:241], 0
	v_mfma_f32_16x16x32_bf16 v[2:5], v[190:193], v[242:245], v[2:5]
	s_setprio 0
	s_add_i32 s2, 0, 0x18000
	s_add_i32 s29, 0, 0x1c000
	v_add_u32_e32 v148, s2, v99
	v_add_u32_e32 v190, s29, v99
	ds_read_b128 v[136:139], v148
	ds_read_b128 v[140:143], v148 offset:1024
	ds_read_b128 v[144:147], v148 offset:2048
	ds_read_b128 v[148:151], v148 offset:3072
	ds_read_b128 v[152:155], v190
	ds_read_b128 v[180:183], v190 offset:1024
	ds_read_b128 v[184:187], v190 offset:2048
	ds_read_b128 v[190:193], v190 offset:3072
	s_add_u32 s0, s44, 0x160000
	s_addc_u32 s1, s45, 0
	s_mov_b32 m0, s52
	v_lshl_add_u64 v[246:247], s[0:1], 0, v[162:163]
	ds_read_b128 v[194:197], v189 offset:32768
	ds_read_b128 v[198:201], v189 offset:33792
	ds_read_b128 v[222:225], v189 offset:34816
	ds_read_b128 v[226:229], v189 offset:35840
	ds_read_b128 v[230:233], v189 offset:36864
	ds_read_b128 v[234:237], v189 offset:37888
	ds_read_b128 v[238:241], v189 offset:38912
	ds_read_b128 v[242:245], v189 offset:39936
	global_load_lds_dwordx4 v[246:247], off
	v_lshl_add_u64 v[246:247], s[0:1], 0, v[158:159]
	s_mov_b32 m0, s53
	s_nop 0
	global_load_lds_dwordx4 v[246:247], off
	s_waitcnt vmcnt(8)
	s_waitcnt lgkmcnt(0)
	s_setprio 1
	s_barrier
	v_mfma_f32_16x16x32_bf16 v[128:131], v[136:139], v[194:197], v[128:131]
	v_mfma_f32_16x16x32_bf16 v[128:131], v[140:143], v[198:201], v[128:131]
	v_mfma_f32_16x16x32_bf16 v[124:127], v[144:147], v[194:197], v[124:127]
	v_mfma_f32_16x16x32_bf16 v[124:127], v[148:151], v[198:201], v[124:127]
	v_mfma_f32_16x16x32_bf16 v[120:123], v[136:139], v[222:225], v[120:123]
	v_mfma_f32_16x16x32_bf16 v[120:123], v[140:143], v[226:229], v[120:123]
	v_mfma_f32_16x16x32_bf16 v[112:115], v[144:147], v[222:225], v[112:115]
	v_mfma_f32_16x16x32_bf16 v[112:115], v[148:151], v[226:229], v[112:115]
	v_mfma_f32_16x16x32_bf16 v[104:107], v[136:139], v[230:233], v[104:107]
	v_mfma_f32_16x16x32_bf16 v[104:107], v[140:143], v[234:237], v[104:107]
	v_mfma_f32_16x16x32_bf16 v[94:97], v[144:147], v[230:233], v[94:97]
	v_mfma_f32_16x16x32_bf16 v[94:97], v[148:151], v[234:237], v[94:97]
	v_mfma_f32_16x16x32_bf16 v[86:89], v[136:139], v[238:241], v[86:89]
	v_mfma_f32_16x16x32_bf16 v[86:89], v[140:143], v[242:245], v[86:89]
	v_mfma_f32_16x16x32_bf16 v[78:81], v[144:147], v[238:241], v[78:81]
	v_mfma_f32_16x16x32_bf16 v[78:81], v[148:151], v[242:245], v[78:81]
	s_setprio 0
	s_setprio 1
	v_mfma_f32_16x16x32_bf16 v[116:119], v[152:155], v[194:197], v[116:119]
	v_mfma_f32_16x16x32_bf16 v[116:119], v[180:183], v[198:201], v[116:119]
	v_mfma_f32_16x16x32_bf16 v[108:111], v[184:187], v[194:197], v[108:111]
	v_mfma_f32_16x16x32_bf16 v[108:111], v[190:193], v[198:201], v[108:111]
	v_mfma_f32_16x16x32_bf16 v[100:103], v[152:155], v[222:225], v[100:103]
	v_mfma_f32_16x16x32_bf16 v[100:103], v[180:183], v[226:229], v[100:103]
	v_mfma_f32_16x16x32_bf16 v[90:93], v[184:187], v[222:225], v[90:93]
	v_mfma_f32_16x16x32_bf16 v[90:93], v[190:193], v[226:229], v[90:93]
	v_mfma_f32_16x16x32_bf16 v[82:85], v[152:155], v[230:233], v[82:85]
	v_mfma_f32_16x16x32_bf16 v[82:85], v[180:183], v[234:237], v[82:85]
	v_mfma_f32_16x16x32_bf16 v[74:77], v[184:187], v[230:233], v[74:77]
	v_mfma_f32_16x16x32_bf16 v[74:77], v[190:193], v[234:237], v[74:77]
	v_mfma_f32_16x16x32_bf16 v[70:73], v[152:155], v[238:241], v[70:73]
	v_mfma_f32_16x16x32_bf16 v[70:73], v[180:183], v[242:245], v[70:73]
	s_setprio 2
	s_barrier
; #define PG8_STAGE(bufoff, gbase, voff) do { _Pragma("unroll") for (int _i = 0; _i < 2; ++_i) \
;         __builtin_amdgcn_global_load_lds((const unsigned*)((const char*)(gbase) + (voff)[_i]), (PG8_LAS unsigned*)(lds + (bufoff) + ldsw + _i * 8192), 16, 0, AUX_A); } while (0)
; #define PG8_STAGEB(bufoff, gbase, voff) do { _Pragma("unroll") for (int _i = 0; _i < 2; ++_i) \
;         __builtin_amdgcn_global_load_lds((const unsigned*)((const char*)(gbase) + (voff)[_i]), (PG8_LAS unsigned*)(lds + (bufoff) + ldsw + _i * 8192), 16, 0, AUX_B); } while (0)
; #define PG8_LDA(dst, b, h) do { _Pragma("unroll") for (int m = 0; m < 4; ++m) _Pragma("unroll") for (int k = 0; k < 2; ++k) dst[m][k] = *(const PG8_LAS bf16x8*)(lds + PG8_SA(b, h) + aoff + m * 2048 + k * 1024); } while (0)
; #define PG8_MMA(ai, bj, At, Bt) do { __builtin_amdgcn_s_setprio(1); _Pragma("unroll") for (int m = 0; m < 4; ++m) _Pragma("unroll") for (int n = 0; n < 2; ++n) _Pragma("unroll") for (int k = 0; k < 2; ++k) \
;         acc[ai][bj][m][n] = __builtin_amdgcn_mfma_f32_16x16x32_bf16(Bt[n][k], At[m][k], acc[ai][bj][m][n], 0, 0, 0); __builtin_amdgcn_s_setprio(0); } while (0)
; #define PG8_WAIT_V(n) asm volatile("s_waitcnt vmcnt(" #n ")" ::: "memory")
; #define PG8_WAIT_L(n) asm volatile("s_waitcnt lgkmcnt(" #n ")" ::: "memory")
; #define PG8_BAR __builtin_amdgcn_s_barrier()
; #define PG8_SCHED __builtin_amdgcn_sched_barrier(0)
; template <class Epi, class Sched, bool ALIGN_EPI = false, bool SP2 = false>
; __device__ __forceinline__ void gemm_phase(PG8_LAS unsigned char* lds, const Gemm g, const Sched& S, const Epi& E) {
;     ...
;         for (int t = 0; t < nt; t += 2) {
;     ...
;             PG8_LDA(At, 1, 1); PG8_STAGEB(PG8_SB(1, 0), b3, voffB); PG8_STAGEB(PG8_SB(1, 1), b3 + hstep, voffB); PG8_STAGE(PG8_SA(1, 0), a3, voffA);
;             PG8_WAIT_V(8); PG8_WAIT_L(0); PG8_BAR; PG8_MMA(1, 0, At, B0); PG8_MMA(1, 1, At, B1); PG8_BAR; PG8_SCHED;
	v_mfma_f32_16x16x32_bf16 v[66:69], v[184:187], v[238:241], v[66:69]
	v_mfma_f32_16x16x32_bf16 v[66:69], v[190:193], v[242:245], v[66:69]
	s_setprio 0
	s_add_i32 s0, s2, s49
	v_lshl_add_u64 v[168:169], v[168:169], 0, s[76:77]
	s_mov_b32 m0, s0
	ds_read_b128 v[194:197], v189 offset:49152
	ds_read_b128 v[198:201], v189 offset:50176
	ds_read_b128 v[222:225], v189 offset:51200
	ds_read_b128 v[226:229], v189 offset:52224
	ds_read_b128 v[230:233], v189 offset:53248
	ds_read_b128 v[234:237], v189 offset:54272
	ds_read_b128 v[238:241], v189 offset:55296
	ds_read_b128 v[242:245], v189 offset:56320
	global_load_lds_dwordx4 v[168:169], off
	s_add_i32 m0, s0, 0x2000
	s_add_u32 s0, s42, 0x160080
	v_lshl_add_u64 v[168:169], v[172:173], 0, s[76:77]
	s_addc_u32 s1, s43, 0
	s_add_i32 s2, s29, s49
	global_load_lds_dwordx4 v[168:169], off
	v_lshl_add_u64 v[168:169], s[0:1], 0, v[160:161]
	s_mov_b32 m0, s2
	s_nop 0
	global_load_lds_dwordx4 v[168:169], off
	v_lshl_add_u64 v[168:169], s[0:1], 0, v[156:157]
	s_add_i32 m0, s2, 0x2000
	s_nop 0
	global_load_lds_dwordx4 v[168:169], off
	v_lshl_add_u64 v[168:169], v[202:203], 0, s[76:77]
	s_mov_b32 m0, s60
	s_nop 0
	global_load_lds_dwordx4 v[168:169], off
	v_lshl_add_u64 v[168:169], v[212:213], 0, s[76:77]
	s_mov_b32 m0, s61
	s_nop 0
	global_load_lds_dwordx4 v[168:169], off
	s_waitcnt vmcnt(8)
	s_waitcnt lgkmcnt(0)
	s_setprio 1
	s_barrier
	v_mfma_f32_16x16x32_bf16 v[62:65], v[136:139], v[194:197], v[62:65]
	v_mfma_f32_16x16x32_bf16 v[62:65], v[140:143], v[198:201], v[62:65]
	v_mfma_f32_16x16x32_bf16 v[58:61], v[144:147], v[194:197], v[58:61]
	v_mfma_f32_16x16x32_bf16 v[58:61], v[148:151], v[198:201], v[58:61]
	v_mfma_f32_16x16x32_bf16 v[54:57], v[136:139], v[222:225], v[54:57]
	v_mfma_f32_16x16x32_bf16 v[54:57], v[140:143], v[226:229], v[54:57]
	v_mfma_f32_16x16x32_bf16 v[46:49], v[144:147], v[222:225], v[46:49]
	v_mfma_f32_16x16x32_bf16 v[46:49], v[148:151], v[226:229], v[46:49]
	v_mfma_f32_16x16x32_bf16 v[38:41], v[136:139], v[230:233], v[38:41]
	v_mfma_f32_16x16x32_bf16 v[38:41], v[140:143], v[234:237], v[38:41]
	v_mfma_f32_16x16x32_bf16 v[30:33], v[144:147], v[230:233], v[30:33]
	v_mfma_f32_16x16x32_bf16 v[30:33], v[148:151], v[234:237], v[30:33]
	v_mfma_f32_16x16x32_bf16 v[22:25], v[136:139], v[238:241], v[22:25]
	v_mfma_f32_16x16x32_bf16 v[22:25], v[140:143], v[242:245], v[22:25]
	v_mfma_f32_16x16x32_bf16 v[14:17], v[144:147], v[238:241], v[14:17]
	v_mfma_f32_16x16x32_bf16 v[14:17], v[148:151], v[242:245], v[14:17]
	s_setprio 0
	s_setprio 1
	v_mfma_f32_16x16x32_bf16 v[50:53], v[152:155], v[194:197], v[50:53]
	v_mfma_f32_16x16x32_bf16 v[50:53], v[180:183], v[198:201], v[50:53]
	v_mfma_f32_16x16x32_bf16 v[42:45], v[184:187], v[194:197], v[42:45]
	v_mfma_f32_16x16x32_bf16 v[42:45], v[190:193], v[198:201], v[42:45]
	v_mfma_f32_16x16x32_bf16 v[34:37], v[152:155], v[222:225], v[34:37]
	v_mfma_f32_16x16x32_bf16 v[34:37], v[180:183], v[226:229], v[34:37]
	v_mfma_f32_16x16x32_bf16 v[26:29], v[184:187], v[222:225], v[26:29]
	v_mfma_f32_16x16x32_bf16 v[26:29], v[190:193], v[226:229], v[26:29]
	v_mfma_f32_16x16x32_bf16 v[18:21], v[152:155], v[230:233], v[18:21]
	v_mfma_f32_16x16x32_bf16 v[18:21], v[180:183], v[234:237], v[18:21]
	v_mfma_f32_16x16x32_bf16 v[10:13], v[184:187], v[230:233], v[10:13]
	v_mfma_f32_16x16x32_bf16 v[10:13], v[190:193], v[234:237], v[10:13]
	v_mfma_f32_16x16x32_bf16 v[6:9], v[152:155], v[238:241], v[6:9]
	v_mfma_f32_16x16x32_bf16 v[6:9], v[180:183], v[242:245], v[6:9]
	s_setprio 2
	s_barrier
	v_mfma_f32_16x16x32_bf16 v[2:5], v[184:187], v[238:241], v[2:5]
	v_mfma_f32_16x16x32_bf16 v[2:5], v[190:193], v[242:245], v[2:5]
	s_setprio 0
	s_add_i32 s0, s83, 2
	v_lshl_add_u64 v[132:133], v[132:133], 0, s[86:87]
	v_lshl_add_u64 v[134:135], v[134:135], 0, s[86:87]
	s_cmp_ge_i32 s83, s82
	s_mov_b32 s83, s0
	s_cbranch_scc1 .Lpx_1654
